# in-proj epilogue: one straight-line path per activation kind (none/silu/gelu/sigmoid) selected once per tile; pass-1 prefetch deferral; sample-GEMM tail batching
# speedup vs baseline: 1.0549x; 1.0108x over previous
.LBB0_73:
	s_mul_hi_i32 s0, s12, 0x92492493
	s_add_i32 s0, s0, s12
	s_lshr_b32 s1, s0, 31
	s_ashr_i32 s0, s0, 2
	s_add_i32 s4, s0, s1
	s_mul_i32 s0, s4, 7
	v_mov_b32_e32 v0, v176
	s_sub_i32 s3, s12, s0
	s_ashr_i32 s13, s4, 2
	s_and_b32 s14, s4, 3
	v_and_b32_e32 v3, 0x7f, v0
	s_lshl_b32 s0, s3, 8
	s_lshl_b32 s5, s13, 11
	v_ashrrev_i32_e32 v60, 7, v0
	v_lshlrev_b32_e32 v13, 2, v3
	s_add_i32 s0, s5, s0
	v_lshlrev_b32_e32 v12, 2, v60
	v_lshl_or_b32 v4, s14, 9, v13
	v_mov_b32_e32 v5, v2
	v_add_u32_e32 v1, s0, v12
	v_lshl_add_u64 v[56:57], s[82:83], 0, v[4:5]
	v_mad_i64_i32 v[4:5], s[0:1], v1, s96, v[56:57]
	v_or_b32_e32 v14, 1, v1
	v_or_b32_e32 v15, 2, v1
	v_or_b32_e32 v16, 3, v1
	v_add_u32_e32 v17, 16, v1
	v_mad_i64_i32 v[6:7], s[0:1], v14, s96, v[56:57]
	v_mad_i64_i32 v[8:9], s[0:1], v15, s96, v[56:57]
	v_mad_i64_i32 v[10:11], s[0:1], v16, s96, v[56:57]
	global_load_dword v50, v[4:5], off
	global_load_dword v51, v[6:7], off
	global_load_dword v52, v[8:9], off
	global_load_dword v53, v[10:11], off
	v_mad_i64_i32 v[4:5], s[0:1], v17, s96, v[56:57]
	v_add_u32_e32 v18, 17, v1
	v_add_u32_e32 v19, 18, v1
	v_add_u32_e32 v20, 19, v1
	v_mad_i64_i32 v[6:7], s[0:1], v18, s96, v[56:57]
	v_mad_i64_i32 v[8:9], s[0:1], v19, s96, v[56:57]
	global_load_dword v46, v[4:5], off
	global_load_dword v47, v[6:7], off
	global_load_dword v48, v[8:9], off
	v_mad_i64_i32 v[4:5], s[0:1], v20, s96, v[56:57]
	global_load_dword v49, v[4:5], off
	v_readfirstlane_b32 s0, v0
	s_ashr_i32 s2, s0, 6
	s_lshl_b32 s0, s14, 8
	s_add_u32 s0, s80, s0
	s_addc_u32 s1, s81, 0
	v_lshlrev_b32_e32 v4, 1, v3
	v_mov_b32_e32 v5, v2
	v_lshl_add_u64 v[58:59], s[0:1], 0, v[4:5]
	v_mad_i64_i32 v[10:11], s[0:1], v16, s30, v[58:59]
	v_mad_i64_i32 v[4:5], s[0:1], v1, s30, v[58:59]
	v_mad_i64_i32 v[6:7], s[0:1], v14, s30, v[58:59]
	v_mad_i64_i32 v[8:9], s[0:1], v15, s30, v[58:59]
	global_load_ushort v78, v[10:11], off
	global_load_ushort v77, v[8:9], off
	global_load_ushort v45, v[6:7], off
	global_load_ushort v44, v[4:5], off
	v_mad_i64_i32 v[10:11], s[0:1], v20, s30, v[58:59]
	v_mad_i64_i32 v[4:5], s[0:1], v17, s30, v[58:59]
	v_mad_i64_i32 v[6:7], s[0:1], v18, s30, v[58:59]
	v_mad_i64_i32 v[8:9], s[0:1], v19, s30, v[58:59]
	global_load_ushort v67, v[10:11], off
	global_load_ushort v65, v[8:9], off
	global_load_ushort v66, v[6:7], off
	global_load_ushort v64, v[4:5], off
	v_add_u32_e32 v62, 0, v13
	s_movk_i32 s0, 0x80
	v_mad_u32_u24 v70, v3, 44, v62
	v_mul_i32_i24_e32 v71, 0xffffffd4, v3
	v_cmp_gt_u32_e64 s[38:39], s0, v0
	s_mulk_i32 s4, 0x700
	v_and_b32_e32 v1, 63, v0
	v_and_b32_e32 v69, 48, v0
	v_lshl_add_u32 v63, v0, 2, 0
	v_cmp_lt_u32_e64 s[40:41], s51, v0
	v_lshl_add_u32 v61, v60, 3, v70
	v_cmp_gt_u32_e32 vcc, 32, v1
	s_mov_b32 s15, 0
	v_mov_b32_e32 v8, 0
	v_mov_b32_e32 v16, 0
	v_mov_b32_e32 v20, 0
	v_mov_b32_e32 v24, 0
	v_mov_b32_e32 v28, 0
	v_mov_b32_e32 v32, 0
	s_waitcnt vmcnt(0)
	v_sub_f32_e32 v4, 1.0, v50
	v_max_f32_e32 v83, 0xda24260, v4
	v_sub_f32_e32 v4, 1.0, v51
	v_max_f32_e32 v82, 0xda24260, v4
	v_sub_f32_e32 v5, 1.0, v52
	v_sub_f32_e32 v6, 1.0, v53
	v_max_f32_e32 v81, 0xda24260, v5
	v_max_f32_e32 v79, 0xda24260, v6
	v_sub_f32_e32 v4, 1.0, v46
	v_max_f32_e32 v76, 0xda24260, v4
	v_sub_f32_e32 v4, 1.0, v47
	v_max_f32_e32 v74, 0xda24260, v4
	v_sub_f32_e32 v4, 1.0, v48
	v_max_f32_e32 v73, 0xda24260, v4
	v_sub_f32_e32 v4, 1.0, v49
	v_max_f32_e32 v72, 0xda24260, v4
	v_and_b32_e32 v4, 15, v0
	v_lshl_or_b32 v3, s2, 4, v4
	v_mad_u64_u32 v[54:55], s[0:1], v3, 48, v[2:3]
	s_lshl_b32 s0, s12, 8
	s_add_i32 s5, s5, s0
	v_add_u32_e32 v3, s5, v12
	v_subrev_u32_e32 v75, s4, v3
	v_mov_b32_e32 v3, 0
	v_add_u32_e32 v55, 0, v69
	v_mul_u32_u24_e32 v68, 48, v4
	v_mov_b32_e32 v4, 0
	v_mov_b32_e32 v5, v3
	v_mov_b32_e32 v6, v3
	v_mov_b32_e32 v7, v3
	v_mov_b32_e32 v9, v3
	v_mov_b32_e32 v10, v3
	v_mov_b32_e32 v11, v3
	v_mov_b32_e32 v12, 0
	v_mov_b32_e32 v13, v3
	v_mov_b32_e32 v14, v3
	v_mov_b32_e32 v15, v3
	v_mov_b32_e32 v17, v3
	v_mov_b32_e32 v18, v3
	v_mov_b32_e32 v19, v3
	v_mov_b32_e32 v21, v3
	v_mov_b32_e32 v22, v3
	v_mov_b32_e32 v23, v3
	v_mov_b32_e32 v25, v3
	v_mov_b32_e32 v26, v3
	v_mov_b32_e32 v27, v3
	v_mov_b32_e32 v29, v3
	v_mov_b32_e32 v30, v3
	v_mov_b32_e32 v31, v3
	v_mov_b32_e32 v33, v3
	v_mov_b32_e32 v34, v3
	v_mov_b32_e32 v35, v3
	v_lshrrev_b32_e32 v160, 1, v69
	v_add_u32_e32 v161, v68, v160
	v_add_u32_e32 v160, v54, v160
	v_mov_b32_e32 v162, v64
	v_mov_b32_e32 v163, v66
	v_mov_b32_e32 v164, v65
	v_mov_b32_e32 v165, v67
	s_branch .LBB0_75
.LBB0_74:
	s_waitcnt vmcnt(8)
	s_waitcnt lgkmcnt(0)
	v_pk_mul_f32 v[6:7], v[6:7], v[220:221]
	v_pk_mul_f32 v[4:5], v[4:5], v[218:219]
	s_nop 0
	v_sub_f32_e32 v44, 1.0, v50
	v_mfma_f32_16x16x16_bf16 v[4:7], v[236:237], v[238:239], v[4:7]
	v_max_f32_e32 v83, 0xda24260, v44
	v_and_b32_e32 v44, 0xffff, v77
	v_sub_f32_e32 v77, 1.0, v52
	s_waitcnt lgkmcnt(0)
	s_barrier
	v_sub_f32_e32 v45, 1.0, v51
	v_max_f32_e32 v81, 0xda24260, v77
	v_and_b32_e32 v77, 0xffff, v78
	v_sub_f32_e32 v78, 1.0, v53
	s_add_i32 s15, s15, 32
	v_max_f32_e32 v82, 0xda24260, v45
	v_and_b32_e32 v45, 0xffff, v79
	v_max_f32_e32 v79, 0xda24260, v78
	v_and_b32_e32 v78, 0xffff, v80
	s_cmpk_eq_i32 s15, 0xe0
	s_cbranch_scc1 .LBB0_135

.LBB0_85:
	s_or_b64 exec, exec, s[0:1]
	v_add_u32_e32 v81, s15, v75
	v_add_u32_e32 v38, 32, v81
	v_mad_i64_i32 v[36:37], s[0:1], v38, s96, v[56:57]
	global_load_dword v50, v[36:37], off
	v_mad_i64_i32 v[36:37], s[0:1], v38, s30, v[58:59]
	v_add_u32_e32 v38, 33, v81
	global_load_ushort v77, v[36:37], off
	v_mad_i64_i32 v[36:37], s[0:1], v38, s96, v[56:57]
	global_load_dword v51, v[36:37], off
	v_mad_i64_i32 v[36:37], s[0:1], v38, s30, v[58:59]
	v_add_u32_e32 v38, 34, v81
	global_load_ushort v79, v[36:37], off
	v_mad_i64_i32 v[36:37], s[0:1], v38, s96, v[56:57]
	global_load_dword v52, v[36:37], off
	v_mad_i64_i32 v[36:37], s[0:1], v38, s30, v[58:59]
	v_add_u32_e32 v38, 35, v81
	global_load_ushort v78, v[36:37], off
	v_mad_i64_i32 v[36:37], s[0:1], v38, s96, v[56:57]
	global_load_dword v53, v[36:37], off
	v_mad_i64_i32 v[36:37], s[0:1], v38, s30, v[58:59]
	global_load_ushort v80, v[36:37], off
	s_waitcnt lgkmcnt(0)
	s_barrier
	ds_read_b64 v[238:239], v160 offset:14848
	ds_read_b64 v[222:223], v161 offset:8704
	ds_read_b128 v[190:193], v55 offset:20992
	ds_read_b64 v[224:225], v161 offset:9472
	ds_read_b128 v[194:197], v55 offset:21056
	ds_read_b64 v[226:227], v161 offset:10240
	ds_read_b128 v[198:201], v55 offset:21120
	ds_read_b64 v[228:229], v161 offset:11008
	ds_read_b128 v[202:205], v55 offset:21184
	ds_read_b64 v[230:231], v161 offset:11776
	ds_read_b128 v[206:209], v55 offset:21248
	ds_read_b64 v[232:233], v161 offset:12544
	ds_read_b128 v[210:213], v55 offset:21312
	s_waitcnt lgkmcnt(10)
	v_pk_mul_f32 v[34:35], v[34:35], v[192:193]
	v_pk_mul_f32 v[32:33], v[32:33], v[190:191]
	s_nop 1
	v_mfma_f32_16x16x16_bf16 v[32:35], v[222:223], v[238:239], v[32:35]
	ds_read_b64 v[234:235], v161 offset:13312
	ds_read_b128 v[214:217], v55 offset:21376
	s_waitcnt lgkmcnt(10)
	v_pk_mul_f32 v[30:31], v[30:31], v[196:197]
	v_pk_mul_f32 v[28:29], v[28:29], v[194:195]
	s_nop 1
	v_mfma_f32_16x16x16_bf16 v[28:31], v[224:225], v[238:239], v[28:31]
	ds_read_b64 v[236:237], v161 offset:14080
	ds_read_b128 v[218:221], v55 offset:21440
	s_waitcnt lgkmcnt(10)
	v_pk_mul_f32 v[26:27], v[26:27], v[200:201]
	v_pk_mul_f32 v[24:25], v[24:25], v[198:199]
	s_nop 1
	v_mfma_f32_16x16x16_bf16 v[24:27], v[226:227], v[238:239], v[24:27]
	s_waitcnt lgkmcnt(8)
	v_pk_mul_f32 v[22:23], v[22:23], v[204:205]
	v_pk_mul_f32 v[20:21], v[20:21], v[202:203]
	s_nop 1
	v_mfma_f32_16x16x16_bf16 v[20:23], v[228:229], v[238:239], v[20:23]
	s_waitcnt lgkmcnt(6)
	v_pk_mul_f32 v[18:19], v[18:19], v[208:209]
	v_pk_mul_f32 v[16:17], v[16:17], v[206:207]
	s_nop 1
	v_mfma_f32_16x16x16_bf16 v[16:19], v[230:231], v[238:239], v[16:19]
	s_waitcnt lgkmcnt(4)
	v_pk_mul_f32 v[14:15], v[14:15], v[212:213]
	v_pk_mul_f32 v[12:13], v[12:13], v[210:211]
	s_nop 1
	v_mfma_f32_16x16x16_bf16 v[12:15], v[232:233], v[238:239], v[12:15]
	s_waitcnt lgkmcnt(2)
	v_pk_mul_f32 v[10:11], v[10:11], v[216:217]
	v_pk_mul_f32 v[8:9], v[8:9], v[214:215]
	s_nop 1
	v_mfma_f32_16x16x16_bf16 v[8:11], v[234:235], v[238:239], v[8:11]
	s_waitcnt vmcnt(8)
	v_sub_f32_e32 v36, 1.0, v46
	v_max_f32_e32 v76, 0xda24260, v36
	v_sub_f32_e32 v36, 1.0, v47
	v_max_f32_e32 v74, 0xda24260, v36
	v_sub_f32_e32 v36, 1.0, v48
	v_max_f32_e32 v73, 0xda24260, v36
	v_sub_f32_e32 v36, 1.0, v49
	v_max_f32_e32 v72, 0xda24260, v36
	v_mov_b32_e32 v64, v162
	v_mov_b32_e32 v66, v163
	v_mov_b32_e32 v65, v164
	v_mov_b32_e32 v67, v165
	v_cmp_gt_f32_e64 s[0:1], s34, v76
	s_waitcnt lgkmcnt(0)
	s_barrier
	v_pk_mul_f32 v[6:7], v[6:7], v[220:221]
	v_pk_mul_f32 v[4:5], v[4:5], v[218:219]
	s_nop 1
	v_mfma_f32_16x16x16_bf16 v[4:7], v[236:237], v[238:239], v[4:7]
	v_cndmask_b32_e64 v36, 0, 32, s[0:1]
	v_ldexp_f32 v36, v76, v36
	v_log_f32_e32 v36, v36
	s_nop 0
	v_mul_f32_e32 v37, 0x3f317217, v36
	v_fma_f32 v37, v36, s97, -v37
	v_fmac_f32_e32 v37, 0x3377d1cf, v36
	v_fmac_f32_e32 v37, 0x3f317217, v36
	v_cmp_lt_f32_e64 s[42:43], |v36|, s35
	s_nop 1
	v_cndmask_b32_e64 v36, v36, v37, s[42:43]
	v_cndmask_b32_e64 v37, 0, v188, s[0:1]
	v_sub_f32_e32 v36, v36, v37
	v_cmp_gt_f32_e64 s[0:1], s34, v74
	v_add_f32_e32 v42, 0, v36
	s_nop 0
	v_cndmask_b32_e64 v36, 0, 32, s[0:1]
	v_ldexp_f32 v36, v74, v36
	v_log_f32_e32 v36, v36
	s_nop 0
	v_mul_f32_e32 v37, 0x3f317217, v36
	v_fma_f32 v37, v36, s97, -v37
	v_fmac_f32_e32 v37, 0x3377d1cf, v36
	v_fmac_f32_e32 v37, 0x3f317217, v36
	v_cmp_lt_f32_e64 s[42:43], |v36|, s35
	s_nop 1
	v_cndmask_b32_e64 v36, v36, v37, s[42:43]
	v_cndmask_b32_e64 v37, 0, v188, s[0:1]
	v_sub_f32_e32 v36, v36, v37
	v_cmp_gt_f32_e64 s[0:1], s34, v73
	v_add_f32_e32 v43, v36, v42
	s_nop 0
	v_cndmask_b32_e64 v36, 0, 32, s[0:1]
	v_ldexp_f32 v36, v73, v36
	v_log_f32_e32 v36, v36
	s_nop 0
	v_mul_f32_e32 v37, 0x3f317217, v36
	v_fma_f32 v37, v36, s97, -v37
	v_fmac_f32_e32 v37, 0x3377d1cf, v36
	v_fmac_f32_e32 v37, 0x3f317217, v36
	v_cmp_lt_f32_e64 s[42:43], |v36|, s35
	s_nop 1
	v_cndmask_b32_e64 v36, v36, v37, s[42:43]
	v_cndmask_b32_e64 v37, 0, v188, s[0:1]
	v_sub_f32_e32 v36, v36, v37
	v_cmp_gt_f32_e64 s[0:1], s34, v72
	v_add_f32_e32 v73, v36, v43
	s_nop 0
	v_cndmask_b32_e64 v36, 0, 32, s[0:1]
	v_ldexp_f32 v36, v72, v36
	v_log_f32_e32 v36, v36
	s_nop 0
	v_mul_f32_e32 v37, 0x3f317217, v36
	v_fma_f32 v37, v36, s97, -v37
	v_fmac_f32_e32 v37, 0x3377d1cf, v36
	v_fmac_f32_e32 v37, 0x3f317217, v36
	v_cmp_lt_f32_e64 s[42:43], |v36|, s35
	s_nop 1
	v_cndmask_b32_e64 v36, v36, v37, s[42:43]
	v_cndmask_b32_e64 v37, 0, v188, s[0:1]
	v_sub_f32_e32 v36, v36, v37
	v_add_f32_e32 v37, v36, v73
	ds_write_b32 v63, v37 offset:21504
	s_waitcnt lgkmcnt(0)
	s_barrier
	ds_read2st64_b32 v[38:39], v62 offset0:84 offset1:86
	ds_read2st64_b32 v[40:41], v62 offset0:88 offset1:90
	s_and_saveexec_b64 s[4:5], s[40:41]
	s_cbranch_execz .LBB0_111
	v_cmp_lt_i32_e64 s[0:1], 1, v60
	s_mov_b64 s[6:7], 0
	s_and_saveexec_b64 s[8:9], s[0:1]
	s_xor_b64 s[8:9], exec, s[8:9]
	s_cbranch_execz .LBB0_133
	v_cmp_eq_u32_e64 s[0:1], 2, v60
	s_mov_b64 s[6:7], -1
	s_and_saveexec_b64 s[10:11], s[0:1]
	s_cbranch_execz .LBB0_107
	s_waitcnt lgkmcnt(1)
	v_add_f32_e32 v45, v38, v39
	s_xor_b64 s[6:7], exec, -1

.LBB0_113:
	s_or_b64 exec, exec, s[0:1]
	v_add_u32_e32 v38, 48, v81
	v_mad_i64_i32 v[36:37], s[0:1], v38, s96, v[56:57]
	global_load_dword v46, v[36:37], off
	v_mad_i64_i32 v[36:37], s[0:1], v38, s30, v[58:59]
	v_add_u32_e32 v38, 49, v81
	global_load_ushort v162, v[36:37], off
	v_mad_i64_i32 v[36:37], s[0:1], v38, s96, v[56:57]
	global_load_dword v47, v[36:37], off
	v_mad_i64_i32 v[36:37], s[0:1], v38, s30, v[58:59]
	v_add_u32_e32 v38, 50, v81
	global_load_ushort v163, v[36:37], off
	v_mad_i64_i32 v[36:37], s[0:1], v38, s96, v[56:57]
	global_load_dword v48, v[36:37], off
	v_mad_i64_i32 v[36:37], s[0:1], v38, s30, v[58:59]
	v_add_u32_e32 v38, 51, v81
	global_load_ushort v164, v[36:37], off
	v_mad_i64_i32 v[36:37], s[0:1], v38, s96, v[56:57]
	global_load_dword v49, v[36:37], off
	v_mad_i64_i32 v[36:37], s[0:1], v38, s30, v[58:59]
	global_load_ushort v165, v[36:37], off
	s_waitcnt lgkmcnt(0)
	s_barrier
	ds_read_b64 v[238:239], v160 offset:14848
	ds_read_b64 v[222:223], v161 offset:8704
	ds_read_b128 v[190:193], v55 offset:20992
	ds_read_b64 v[224:225], v161 offset:9472
	ds_read_b128 v[194:197], v55 offset:21056
	ds_read_b64 v[226:227], v161 offset:10240
	ds_read_b128 v[198:201], v55 offset:21120
	ds_read_b64 v[228:229], v161 offset:11008
	ds_read_b128 v[202:205], v55 offset:21184
	ds_read_b64 v[230:231], v161 offset:11776
	ds_read_b128 v[206:209], v55 offset:21248
	ds_read_b64 v[232:233], v161 offset:12544
	ds_read_b128 v[210:213], v55 offset:21312
	s_waitcnt lgkmcnt(10)
	v_pk_mul_f32 v[34:35], v[34:35], v[192:193]
	v_pk_mul_f32 v[32:33], v[32:33], v[190:191]
	s_nop 1
	v_mfma_f32_16x16x16_bf16 v[32:35], v[222:223], v[238:239], v[32:35]
	ds_read_b64 v[234:235], v161 offset:13312
	ds_read_b128 v[214:217], v55 offset:21376
	s_waitcnt lgkmcnt(10)
	v_pk_mul_f32 v[30:31], v[30:31], v[196:197]
	v_pk_mul_f32 v[28:29], v[28:29], v[194:195]
	s_nop 1
	v_mfma_f32_16x16x16_bf16 v[28:31], v[224:225], v[238:239], v[28:31]
	ds_read_b64 v[236:237], v161 offset:14080
	ds_read_b128 v[218:221], v55 offset:21440
	s_waitcnt lgkmcnt(10)
	v_pk_mul_f32 v[26:27], v[26:27], v[200:201]
	v_pk_mul_f32 v[24:25], v[24:25], v[198:199]
	s_nop 1
	v_mfma_f32_16x16x16_bf16 v[24:27], v[226:227], v[238:239], v[24:27]
	s_waitcnt lgkmcnt(8)
	v_pk_mul_f32 v[22:23], v[22:23], v[204:205]
	v_pk_mul_f32 v[20:21], v[20:21], v[202:203]
	s_nop 1
	v_mfma_f32_16x16x16_bf16 v[20:23], v[228:229], v[238:239], v[20:23]
	s_waitcnt lgkmcnt(6)
	v_pk_mul_f32 v[18:19], v[18:19], v[208:209]
	v_pk_mul_f32 v[16:17], v[16:17], v[206:207]
	s_nop 1
	v_mfma_f32_16x16x16_bf16 v[16:19], v[230:231], v[238:239], v[16:19]
	s_waitcnt lgkmcnt(4)
	v_pk_mul_f32 v[14:15], v[14:15], v[212:213]
	v_pk_mul_f32 v[12:13], v[12:13], v[210:211]
	s_nop 1
	v_mfma_f32_16x16x16_bf16 v[12:15], v[232:233], v[238:239], v[12:15]
	s_waitcnt lgkmcnt(2)
	v_pk_mul_f32 v[10:11], v[10:11], v[216:217]
	v_pk_mul_f32 v[8:9], v[8:9], v[214:215]
	s_nop 1
	v_mfma_f32_16x16x16_bf16 v[8:11], v[234:235], v[238:239], v[8:11]
	s_branch .LBB0_74

.LBB0_145:
	s_or_b64 exec, exec, s[0:1]
	s_waitcnt lgkmcnt(0)
	s_barrier
	ds_read_b64 v[238:239], v160 offset:14848
	ds_read_b64 v[222:223], v161 offset:8704
	ds_read_b128 v[190:193], v55 offset:20992
	ds_read_b64 v[224:225], v161 offset:9472
	ds_read_b128 v[194:197], v55 offset:21056
	ds_read_b64 v[226:227], v161 offset:10240
	ds_read_b128 v[198:201], v55 offset:21120
	ds_read_b64 v[228:229], v161 offset:11008
	ds_read_b128 v[202:205], v55 offset:21184
	ds_read_b64 v[230:231], v161 offset:11776
	ds_read_b128 v[206:209], v55 offset:21248
	ds_read_b64 v[232:233], v161 offset:12544
	ds_read_b128 v[210:213], v55 offset:21312
	s_waitcnt lgkmcnt(10)
	v_pk_mul_f32 v[34:35], v[34:35], v[192:193]
	v_pk_mul_f32 v[32:33], v[32:33], v[190:191]
	s_nop 1
	v_mfma_f32_16x16x16_bf16 v[32:35], v[222:223], v[238:239], v[32:35]
	ds_read_b64 v[234:235], v161 offset:13312
	ds_read_b128 v[214:217], v55 offset:21376
	s_waitcnt lgkmcnt(10)
	v_pk_mul_f32 v[30:31], v[30:31], v[196:197]
	v_pk_mul_f32 v[28:29], v[28:29], v[194:195]
	s_nop 1
	v_mfma_f32_16x16x16_bf16 v[28:31], v[224:225], v[238:239], v[28:31]
	ds_read_b64 v[236:237], v161 offset:14080
	ds_read_b128 v[218:221], v55 offset:21440
	s_waitcnt lgkmcnt(10)
	v_pk_mul_f32 v[26:27], v[26:27], v[200:201]
	v_pk_mul_f32 v[24:25], v[24:25], v[198:199]
	s_nop 1
	v_mfma_f32_16x16x16_bf16 v[24:27], v[226:227], v[238:239], v[24:27]
	s_waitcnt lgkmcnt(8)
	v_pk_mul_f32 v[22:23], v[22:23], v[204:205]
	v_pk_mul_f32 v[20:21], v[20:21], v[202:203]
	s_nop 1
	v_mfma_f32_16x16x16_bf16 v[20:23], v[228:229], v[238:239], v[20:23]
	s_waitcnt lgkmcnt(6)
	v_pk_mul_f32 v[18:19], v[18:19], v[208:209]
	v_pk_mul_f32 v[16:17], v[16:17], v[206:207]
	s_nop 1
	v_mfma_f32_16x16x16_bf16 v[16:19], v[230:231], v[238:239], v[16:19]
	s_waitcnt lgkmcnt(4)
	v_pk_mul_f32 v[14:15], v[14:15], v[212:213]
	v_pk_mul_f32 v[12:13], v[12:13], v[210:211]
	s_nop 1
	v_mfma_f32_16x16x16_bf16 v[12:15], v[232:233], v[238:239], v[12:15]
	s_waitcnt lgkmcnt(2)
	v_pk_mul_f32 v[10:11], v[10:11], v[216:217]
	v_pk_mul_f32 v[8:9], v[8:9], v[214:215]
	s_nop 1
	v_mfma_f32_16x16x16_bf16 v[8:11], v[234:235], v[238:239], v[8:11]
	s_waitcnt vmcnt(0)
	v_sub_f32_e32 v36, 1.0, v46
	v_max_f32_e32 v76, 0xda24260, v36
	v_sub_f32_e32 v36, 1.0, v47
	v_max_f32_e32 v74, 0xda24260, v36
	v_sub_f32_e32 v36, 1.0, v48
	v_max_f32_e32 v73, 0xda24260, v36
	v_sub_f32_e32 v36, 1.0, v49
	v_max_f32_e32 v72, 0xda24260, v36
	v_mov_b32_e32 v64, v162
	v_mov_b32_e32 v66, v163
	v_mov_b32_e32 v65, v164
	v_mov_b32_e32 v67, v165
	v_cmp_gt_f32_e64 s[0:1], s34, v76
	s_waitcnt lgkmcnt(0)
	s_barrier
	v_pk_mul_f32 v[6:7], v[6:7], v[220:221]
	v_pk_mul_f32 v[4:5], v[4:5], v[218:219]
	s_nop 1
	v_mfma_f32_16x16x16_bf16 v[4:7], v[236:237], v[238:239], v[4:7]
	v_cndmask_b32_e64 v36, 0, 32, s[0:1]
	v_ldexp_f32 v36, v76, v36
	v_log_f32_e32 v36, v36
	s_nop 0
	v_mul_f32_e32 v37, 0x3f317217, v36
	v_fma_f32 v37, v36, s97, -v37
	v_fmac_f32_e32 v37, 0x3377d1cf, v36
	v_fmac_f32_e32 v37, 0x3f317217, v36
	v_cmp_lt_f32_e64 s[42:43], |v36|, s35
	s_nop 1
	v_cndmask_b32_e64 v36, v36, v37, s[42:43]
	v_cndmask_b32_e64 v37, 0, v188, s[0:1]
	v_sub_f32_e32 v36, v36, v37
	v_cmp_gt_f32_e64 s[0:1], s34, v74
	v_add_f32_e32 v42, 0, v36
	s_nop 0
	v_cndmask_b32_e64 v36, 0, 32, s[0:1]
	v_ldexp_f32 v36, v74, v36
	v_log_f32_e32 v36, v36
	s_nop 0
	v_mul_f32_e32 v37, 0x3f317217, v36
	v_fma_f32 v37, v36, s97, -v37
	v_fmac_f32_e32 v37, 0x3377d1cf, v36
	v_fmac_f32_e32 v37, 0x3f317217, v36
	v_cmp_lt_f32_e64 s[42:43], |v36|, s35
	s_nop 1
	v_cndmask_b32_e64 v36, v36, v37, s[42:43]
	v_cndmask_b32_e64 v37, 0, v188, s[0:1]
	v_sub_f32_e32 v36, v36, v37
	v_cmp_gt_f32_e64 s[0:1], s34, v73
	v_add_f32_e32 v43, v42, v36
	s_nop 0
	v_cndmask_b32_e64 v36, 0, 32, s[0:1]
	v_ldexp_f32 v36, v73, v36
	v_log_f32_e32 v36, v36
	s_nop 0
	v_mul_f32_e32 v37, 0x3f317217, v36
	v_fma_f32 v37, v36, s97, -v37
	v_fmac_f32_e32 v37, 0x3377d1cf, v36
	v_fmac_f32_e32 v37, 0x3f317217, v36
	v_cmp_lt_f32_e64 s[42:43], |v36|, s35
	s_nop 1
	v_cndmask_b32_e64 v36, v36, v37, s[42:43]
	v_cndmask_b32_e64 v37, 0, v188, s[0:1]
	v_sub_f32_e32 v36, v36, v37
	v_cmp_gt_f32_e64 s[0:1], s34, v72
	v_add_f32_e32 v53, v43, v36
	s_nop 0
	v_cndmask_b32_e64 v36, 0, 32, s[0:1]
	v_ldexp_f32 v36, v72, v36
	v_log_f32_e32 v36, v36
	s_nop 0
	v_mul_f32_e32 v37, 0x3f317217, v36
	v_fma_f32 v37, v36, s97, -v37
	v_fmac_f32_e32 v37, 0x3377d1cf, v36
	v_fmac_f32_e32 v37, 0x3f317217, v36
	v_cmp_lt_f32_e64 s[42:43], |v36|, s35
	s_nop 1
	v_cndmask_b32_e64 v36, v36, v37, s[42:43]
	v_cndmask_b32_e64 v37, 0, v188, s[0:1]
	v_sub_f32_e32 v36, v36, v37
	v_add_f32_e32 v37, v53, v36
	ds_write_b32 v63, v37 offset:21504
	s_waitcnt lgkmcnt(0)
	s_barrier
	ds_read2st64_b32 v[38:39], v62 offset0:84 offset1:86
	ds_read2st64_b32 v[40:41], v62 offset0:88 offset1:90
	s_and_saveexec_b64 s[4:5], s[40:41]
	s_cbranch_execz .LBB0_171
	v_cmp_lt_i32_e64 s[0:1], 1, v60
	s_mov_b64 s[6:7], 0
	s_and_saveexec_b64 s[8:9], s[0:1]
	s_xor_b64 s[8:9], exec, s[8:9]
	s_cbranch_execz .LBB0_195
	v_cmp_eq_u32_e64 s[0:1], 2, v60
	s_mov_b64 s[6:7], -1
	s_and_saveexec_b64 s[10:11], s[0:1]
	s_cbranch_execz .LBB0_167
	s_waitcnt lgkmcnt(1)
	v_add_f32_e32 v45, v38, v39
	s_xor_b64 s[6:7], exec, -1

.LBB0_440:
	v_lshl_add_u32 v195, s2, 8, v3
	s_cmp_gt_i32 s50, 1
	s_mov_b64 s[2:3], -1
	s_mov_b32 s23, 0xffff
	s_cbranch_scc0 .LBB0_591
	s_lshl_b32 s9, s50, 8
	s_cmp_gt_u32 s50, 3
	s_cbranch_scc0 .LBB0_587
	s_cmp_gt_u32 s50, 10
	s_cbranch_scc1 .Lepi_sig
	s_cmp_gt_u32 s50, 8
	s_cbranch_scc1 .Lepi_gelu
	s_cmp_eq_u32 s50, 8
	s_cbranch_scc1 .Lepi_none
	s_cmp_gt_u32 s50, 5
	s_cbranch_scc1 .Lepi_silu
	s_branch .Lepi_none
.Lepi_none:
	v_mul_lo_u32 v152, v195, s30
	v_add_u32_e32 v153, s9, v191
	v_lshl_add_u32 v152, v153, 1, v152
	v_cvt_pk_bf16_f32 v128, v128, v129
	v_cvt_pk_bf16_f32 v129, v130, v131
	v_cvt_pk_bf16_f32 v130, v124, v125
	v_cvt_pk_bf16_f32 v131, v126, v127
	global_store_dwordx4 v152, v[128:131], s[44:45]
	v_cvt_pk_bf16_f32 v120, v120, v121
	v_cvt_pk_bf16_f32 v121, v122, v123
	v_cvt_pk_bf16_f32 v122, v116, v117
	v_cvt_pk_bf16_f32 v123, v118, v119
	global_store_dwordx4 v152, v[120:123], s[44:45] offset:256
	v_add_u32_e32 v152, 0x26000, v152
	v_cvt_pk_bf16_f32 v112, v112, v113
	v_cvt_pk_bf16_f32 v113, v114, v115
	v_cvt_pk_bf16_f32 v114, v108, v109
	v_cvt_pk_bf16_f32 v115, v110, v111
	global_store_dwordx4 v152, v[112:115], s[44:45]
	v_cvt_pk_bf16_f32 v104, v104, v105
	v_cvt_pk_bf16_f32 v105, v106, v107
	v_cvt_pk_bf16_f32 v106, v100, v101
	v_cvt_pk_bf16_f32 v107, v102, v103
	global_store_dwordx4 v152, v[104:107], s[44:45] offset:256
	v_add_u32_e32 v152, 0x26000, v152
	v_cvt_pk_bf16_f32 v96, v96, v97
	v_cvt_pk_bf16_f32 v97, v98, v99
	v_cvt_pk_bf16_f32 v98, v92, v93
	v_cvt_pk_bf16_f32 v99, v94, v95
	global_store_dwordx4 v152, v[96:99], s[44:45]
	v_cvt_pk_bf16_f32 v88, v88, v89
	v_cvt_pk_bf16_f32 v89, v90, v91
	v_cvt_pk_bf16_f32 v90, v84, v85
	v_cvt_pk_bf16_f32 v91, v86, v87
	global_store_dwordx4 v152, v[88:91], s[44:45] offset:256
	v_add_u32_e32 v152, 0x26000, v152
	v_cvt_pk_bf16_f32 v80, v80, v81
	v_cvt_pk_bf16_f32 v81, v82, v83
	v_cvt_pk_bf16_f32 v82, v76, v77
	v_cvt_pk_bf16_f32 v83, v78, v79
	global_store_dwordx4 v152, v[80:83], s[44:45]
	v_cvt_pk_bf16_f32 v72, v72, v73
	v_cvt_pk_bf16_f32 v73, v74, v75
	v_cvt_pk_bf16_f32 v74, v68, v69
	v_cvt_pk_bf16_f32 v75, v70, v71
	global_store_dwordx4 v152, v[72:75], s[44:45] offset:256
	v_add_u32_e32 v152, 0xbe000, v152
	v_cvt_pk_bf16_f32 v64, v64, v65
	v_cvt_pk_bf16_f32 v65, v66, v67
	v_cvt_pk_bf16_f32 v66, v60, v61
	v_cvt_pk_bf16_f32 v67, v62, v63
	global_store_dwordx4 v152, v[64:67], s[44:45]
	v_cvt_pk_bf16_f32 v56, v56, v57
	v_cvt_pk_bf16_f32 v57, v58, v59
	v_cvt_pk_bf16_f32 v58, v52, v53
	v_cvt_pk_bf16_f32 v59, v54, v55
	global_store_dwordx4 v152, v[56:59], s[44:45] offset:256
	v_add_u32_e32 v152, 0x26000, v152
	v_cvt_pk_bf16_f32 v48, v48, v49
	v_cvt_pk_bf16_f32 v49, v50, v51
	v_cvt_pk_bf16_f32 v50, v44, v45
	v_cvt_pk_bf16_f32 v51, v46, v47
	global_store_dwordx4 v152, v[48:51], s[44:45]
	v_cvt_pk_bf16_f32 v40, v40, v41
	v_cvt_pk_bf16_f32 v41, v42, v43
	v_cvt_pk_bf16_f32 v42, v36, v37
	v_cvt_pk_bf16_f32 v43, v38, v39
	global_store_dwordx4 v152, v[40:43], s[44:45] offset:256
	v_add_u32_e32 v152, 0x26000, v152
	v_cvt_pk_bf16_f32 v32, v32, v33
	v_cvt_pk_bf16_f32 v33, v34, v35
	v_cvt_pk_bf16_f32 v34, v28, v29
	v_cvt_pk_bf16_f32 v35, v30, v31
	global_store_dwordx4 v152, v[32:35], s[44:45]
	v_cvt_pk_bf16_f32 v24, v24, v25
	v_cvt_pk_bf16_f32 v25, v26, v27
	v_cvt_pk_bf16_f32 v26, v20, v21
	v_cvt_pk_bf16_f32 v27, v22, v23
	global_store_dwordx4 v152, v[24:27], s[44:45] offset:256
	v_add_u32_e32 v152, 0x26000, v152
	v_cvt_pk_bf16_f32 v16, v16, v17
	v_cvt_pk_bf16_f32 v17, v18, v19
	v_cvt_pk_bf16_f32 v18, v12, v13
	v_cvt_pk_bf16_f32 v19, v14, v15
	global_store_dwordx4 v152, v[16:19], s[44:45]
	v_cvt_pk_bf16_f32 v8, v8, v9
	v_cvt_pk_bf16_f32 v9, v10, v11
	v_cvt_pk_bf16_f32 v10, v4, v5
	v_cvt_pk_bf16_f32 v11, v6, v7
	global_store_dwordx4 v152, v[8:11], s[44:45] offset:256
	s_branch .LBB0_590
.Lepi_silu:
	v_mul_lo_u32 v152, v195, s30
	v_add_u32_e32 v153, s9, v191
	v_lshl_add_u32 v152, v153, 1, v152
	v_mul_f32_e32 v164, 0xbfb8aa3b, v128
	v_mul_f32_e32 v165, 0xbfb8aa3b, v129
	v_mul_f32_e32 v166, 0xbfb8aa3b, v130
	v_mul_f32_e32 v167, 0xbfb8aa3b, v131
	v_mul_f32_e32 v168, 0xbfb8aa3b, v124
	v_mul_f32_e32 v169, 0xbfb8aa3b, v125
	v_mul_f32_e32 v170, 0xbfb8aa3b, v126
	v_mul_f32_e32 v171, 0xbfb8aa3b, v127
	v_exp_f32_e32 v164, v164
	v_exp_f32_e32 v165, v165
	v_exp_f32_e32 v166, v166
	v_exp_f32_e32 v167, v167
	v_exp_f32_e32 v168, v168
	v_exp_f32_e32 v169, v169
	v_exp_f32_e32 v170, v170
	v_exp_f32_e32 v171, v171
	v_add_f32_e32 v164, 1.0, v164
	v_add_f32_e32 v165, 1.0, v165
	v_add_f32_e32 v166, 1.0, v166
	v_add_f32_e32 v167, 1.0, v167
	v_add_f32_e32 v168, 1.0, v168
	v_add_f32_e32 v169, 1.0, v169
	v_add_f32_e32 v170, 1.0, v170
	v_add_f32_e32 v171, 1.0, v171
	v_rcp_f32_e32 v164, v164
	v_rcp_f32_e32 v165, v165
	v_rcp_f32_e32 v166, v166
	v_rcp_f32_e32 v167, v167
	v_rcp_f32_e32 v168, v168
	v_rcp_f32_e32 v169, v169
	v_rcp_f32_e32 v170, v170
	v_rcp_f32_e32 v171, v171
	v_mul_f32_e32 v128, v128, v164
	v_mul_f32_e32 v129, v129, v165
	v_mul_f32_e32 v130, v130, v166
	v_mul_f32_e32 v131, v131, v167
	v_mul_f32_e32 v124, v124, v168
	v_mul_f32_e32 v125, v125, v169
	v_mul_f32_e32 v126, v126, v170
	v_mul_f32_e32 v127, v127, v171
	v_cvt_pk_bf16_f32 v128, v128, v129
	v_cvt_pk_bf16_f32 v129, v130, v131
	v_cvt_pk_bf16_f32 v130, v124, v125
	v_cvt_pk_bf16_f32 v131, v126, v127
	global_store_dwordx4 v152, v[128:131], s[44:45]
	v_mul_f32_e32 v164, 0xbfb8aa3b, v120
	v_mul_f32_e32 v165, 0xbfb8aa3b, v121
	v_mul_f32_e32 v166, 0xbfb8aa3b, v122
	v_mul_f32_e32 v167, 0xbfb8aa3b, v123
	v_mul_f32_e32 v168, 0xbfb8aa3b, v116
	v_mul_f32_e32 v169, 0xbfb8aa3b, v117
	v_mul_f32_e32 v170, 0xbfb8aa3b, v118
	v_mul_f32_e32 v171, 0xbfb8aa3b, v119
	v_exp_f32_e32 v164, v164
	v_exp_f32_e32 v165, v165
	v_exp_f32_e32 v166, v166
	v_exp_f32_e32 v167, v167
	v_exp_f32_e32 v168, v168
	v_exp_f32_e32 v169, v169
	v_exp_f32_e32 v170, v170
	v_exp_f32_e32 v171, v171
	v_add_f32_e32 v164, 1.0, v164
	v_add_f32_e32 v165, 1.0, v165
	v_add_f32_e32 v166, 1.0, v166
	v_add_f32_e32 v167, 1.0, v167
	v_add_f32_e32 v168, 1.0, v168
	v_add_f32_e32 v169, 1.0, v169
	v_add_f32_e32 v170, 1.0, v170
	v_add_f32_e32 v171, 1.0, v171
	v_rcp_f32_e32 v164, v164
	v_rcp_f32_e32 v165, v165
	v_rcp_f32_e32 v166, v166
	v_rcp_f32_e32 v167, v167
	v_rcp_f32_e32 v168, v168
	v_rcp_f32_e32 v169, v169
	v_rcp_f32_e32 v170, v170
	v_rcp_f32_e32 v171, v171
	v_mul_f32_e32 v120, v120, v164
	v_mul_f32_e32 v121, v121, v165
	v_mul_f32_e32 v122, v122, v166
	v_mul_f32_e32 v123, v123, v167
	v_mul_f32_e32 v116, v116, v168
	v_mul_f32_e32 v117, v117, v169
	v_mul_f32_e32 v118, v118, v170
	v_mul_f32_e32 v119, v119, v171
	v_cvt_pk_bf16_f32 v120, v120, v121
	v_cvt_pk_bf16_f32 v121, v122, v123
	v_cvt_pk_bf16_f32 v122, v116, v117
	v_cvt_pk_bf16_f32 v123, v118, v119
	global_store_dwordx4 v152, v[120:123], s[44:45] offset:256
	v_add_u32_e32 v152, 0x26000, v152
	v_mul_f32_e32 v164, 0xbfb8aa3b, v112
	v_mul_f32_e32 v165, 0xbfb8aa3b, v113
	v_mul_f32_e32 v166, 0xbfb8aa3b, v114
	v_mul_f32_e32 v167, 0xbfb8aa3b, v115
	v_mul_f32_e32 v168, 0xbfb8aa3b, v108
	v_mul_f32_e32 v169, 0xbfb8aa3b, v109
	v_mul_f32_e32 v170, 0xbfb8aa3b, v110
	v_mul_f32_e32 v171, 0xbfb8aa3b, v111
	v_exp_f32_e32 v164, v164
	v_exp_f32_e32 v165, v165
	v_exp_f32_e32 v166, v166
	v_exp_f32_e32 v167, v167
	v_exp_f32_e32 v168, v168
	v_exp_f32_e32 v169, v169
	v_exp_f32_e32 v170, v170
	v_exp_f32_e32 v171, v171
	v_add_f32_e32 v164, 1.0, v164
	v_add_f32_e32 v165, 1.0, v165
	v_add_f32_e32 v166, 1.0, v166
	v_add_f32_e32 v167, 1.0, v167
	v_add_f32_e32 v168, 1.0, v168
	v_add_f32_e32 v169, 1.0, v169
	v_add_f32_e32 v170, 1.0, v170
	v_add_f32_e32 v171, 1.0, v171
	v_rcp_f32_e32 v164, v164
	v_rcp_f32_e32 v165, v165
	v_rcp_f32_e32 v166, v166
	v_rcp_f32_e32 v167, v167
	v_rcp_f32_e32 v168, v168
	v_rcp_f32_e32 v169, v169
	v_rcp_f32_e32 v170, v170
	v_rcp_f32_e32 v171, v171
	v_mul_f32_e32 v112, v112, v164
	v_mul_f32_e32 v113, v113, v165
	v_mul_f32_e32 v114, v114, v166
	v_mul_f32_e32 v115, v115, v167
	v_mul_f32_e32 v108, v108, v168
	v_mul_f32_e32 v109, v109, v169
	v_mul_f32_e32 v110, v110, v170
	v_mul_f32_e32 v111, v111, v171
	v_cvt_pk_bf16_f32 v112, v112, v113
	v_cvt_pk_bf16_f32 v113, v114, v115
	v_cvt_pk_bf16_f32 v114, v108, v109
	v_cvt_pk_bf16_f32 v115, v110, v111
	global_store_dwordx4 v152, v[112:115], s[44:45]
	v_mul_f32_e32 v164, 0xbfb8aa3b, v104
	v_mul_f32_e32 v165, 0xbfb8aa3b, v105
	v_mul_f32_e32 v166, 0xbfb8aa3b, v106
	v_mul_f32_e32 v167, 0xbfb8aa3b, v107
	v_mul_f32_e32 v168, 0xbfb8aa3b, v100
	v_mul_f32_e32 v169, 0xbfb8aa3b, v101
	v_mul_f32_e32 v170, 0xbfb8aa3b, v102
	v_mul_f32_e32 v171, 0xbfb8aa3b, v103
	v_exp_f32_e32 v164, v164
	v_exp_f32_e32 v165, v165
	v_exp_f32_e32 v166, v166
	v_exp_f32_e32 v167, v167
	v_exp_f32_e32 v168, v168
	v_exp_f32_e32 v169, v169
	v_exp_f32_e32 v170, v170
	v_exp_f32_e32 v171, v171
	v_add_f32_e32 v164, 1.0, v164
	v_add_f32_e32 v165, 1.0, v165
	v_add_f32_e32 v166, 1.0, v166
	v_add_f32_e32 v167, 1.0, v167
	v_add_f32_e32 v168, 1.0, v168
	v_add_f32_e32 v169, 1.0, v169
	v_add_f32_e32 v170, 1.0, v170
	v_add_f32_e32 v171, 1.0, v171
	v_rcp_f32_e32 v164, v164
	v_rcp_f32_e32 v165, v165
	v_rcp_f32_e32 v166, v166
	v_rcp_f32_e32 v167, v167
	v_rcp_f32_e32 v168, v168
	v_rcp_f32_e32 v169, v169
	v_rcp_f32_e32 v170, v170
	v_rcp_f32_e32 v171, v171
	v_mul_f32_e32 v104, v104, v164
	v_mul_f32_e32 v105, v105, v165
	v_mul_f32_e32 v106, v106, v166
	v_mul_f32_e32 v107, v107, v167
	v_mul_f32_e32 v100, v100, v168
	v_mul_f32_e32 v101, v101, v169
	v_mul_f32_e32 v102, v102, v170
	v_mul_f32_e32 v103, v103, v171
	v_cvt_pk_bf16_f32 v104, v104, v105
	v_cvt_pk_bf16_f32 v105, v106, v107
	v_cvt_pk_bf16_f32 v106, v100, v101
	v_cvt_pk_bf16_f32 v107, v102, v103
	global_store_dwordx4 v152, v[104:107], s[44:45] offset:256
	v_add_u32_e32 v152, 0x26000, v152
	v_mul_f32_e32 v164, 0xbfb8aa3b, v96
	v_mul_f32_e32 v165, 0xbfb8aa3b, v97
	v_mul_f32_e32 v166, 0xbfb8aa3b, v98
	v_mul_f32_e32 v167, 0xbfb8aa3b, v99
	v_mul_f32_e32 v168, 0xbfb8aa3b, v92
	v_mul_f32_e32 v169, 0xbfb8aa3b, v93
	v_mul_f32_e32 v170, 0xbfb8aa3b, v94
	v_mul_f32_e32 v171, 0xbfb8aa3b, v95
	v_exp_f32_e32 v164, v164
	v_exp_f32_e32 v165, v165
	v_exp_f32_e32 v166, v166
	v_exp_f32_e32 v167, v167
	v_exp_f32_e32 v168, v168
	v_exp_f32_e32 v169, v169
	v_exp_f32_e32 v170, v170
	v_exp_f32_e32 v171, v171
	v_add_f32_e32 v164, 1.0, v164
	v_add_f32_e32 v165, 1.0, v165
	v_add_f32_e32 v166, 1.0, v166
	v_add_f32_e32 v167, 1.0, v167
	v_add_f32_e32 v168, 1.0, v168
	v_add_f32_e32 v169, 1.0, v169
	v_add_f32_e32 v170, 1.0, v170
	v_add_f32_e32 v171, 1.0, v171
	v_rcp_f32_e32 v164, v164
	v_rcp_f32_e32 v165, v165
	v_rcp_f32_e32 v166, v166
	v_rcp_f32_e32 v167, v167
	v_rcp_f32_e32 v168, v168
	v_rcp_f32_e32 v169, v169
	v_rcp_f32_e32 v170, v170
	v_rcp_f32_e32 v171, v171
	v_mul_f32_e32 v96, v96, v164
	v_mul_f32_e32 v97, v97, v165
	v_mul_f32_e32 v98, v98, v166
	v_mul_f32_e32 v99, v99, v167
	v_mul_f32_e32 v92, v92, v168
	v_mul_f32_e32 v93, v93, v169
	v_mul_f32_e32 v94, v94, v170
	v_mul_f32_e32 v95, v95, v171
	v_cvt_pk_bf16_f32 v96, v96, v97
	v_cvt_pk_bf16_f32 v97, v98, v99
	v_cvt_pk_bf16_f32 v98, v92, v93
	v_cvt_pk_bf16_f32 v99, v94, v95
	global_store_dwordx4 v152, v[96:99], s[44:45]
	v_mul_f32_e32 v164, 0xbfb8aa3b, v88
	v_mul_f32_e32 v165, 0xbfb8aa3b, v89
	v_mul_f32_e32 v166, 0xbfb8aa3b, v90
	v_mul_f32_e32 v167, 0xbfb8aa3b, v91
	v_mul_f32_e32 v168, 0xbfb8aa3b, v84
	v_mul_f32_e32 v169, 0xbfb8aa3b, v85
	v_mul_f32_e32 v170, 0xbfb8aa3b, v86
	v_mul_f32_e32 v171, 0xbfb8aa3b, v87
	v_exp_f32_e32 v164, v164
	v_exp_f32_e32 v165, v165
	v_exp_f32_e32 v166, v166
	v_exp_f32_e32 v167, v167
	v_exp_f32_e32 v168, v168
	v_exp_f32_e32 v169, v169
	v_exp_f32_e32 v170, v170
	v_exp_f32_e32 v171, v171
	v_add_f32_e32 v164, 1.0, v164
	v_add_f32_e32 v165, 1.0, v165
	v_add_f32_e32 v166, 1.0, v166
	v_add_f32_e32 v167, 1.0, v167
	v_add_f32_e32 v168, 1.0, v168
	v_add_f32_e32 v169, 1.0, v169
	v_add_f32_e32 v170, 1.0, v170
	v_add_f32_e32 v171, 1.0, v171
	v_rcp_f32_e32 v164, v164
	v_rcp_f32_e32 v165, v165
	v_rcp_f32_e32 v166, v166
	v_rcp_f32_e32 v167, v167
	v_rcp_f32_e32 v168, v168
	v_rcp_f32_e32 v169, v169
	v_rcp_f32_e32 v170, v170
	v_rcp_f32_e32 v171, v171
	v_mul_f32_e32 v88, v88, v164
	v_mul_f32_e32 v89, v89, v165
	v_mul_f32_e32 v90, v90, v166
	v_mul_f32_e32 v91, v91, v167
	v_mul_f32_e32 v84, v84, v168
	v_mul_f32_e32 v85, v85, v169
	v_mul_f32_e32 v86, v86, v170
	v_mul_f32_e32 v87, v87, v171
	v_cvt_pk_bf16_f32 v88, v88, v89
	v_cvt_pk_bf16_f32 v89, v90, v91
	v_cvt_pk_bf16_f32 v90, v84, v85
	v_cvt_pk_bf16_f32 v91, v86, v87
	global_store_dwordx4 v152, v[88:91], s[44:45] offset:256
	v_add_u32_e32 v152, 0x26000, v152
	v_mul_f32_e32 v164, 0xbfb8aa3b, v80
	v_mul_f32_e32 v165, 0xbfb8aa3b, v81
	v_mul_f32_e32 v166, 0xbfb8aa3b, v82
	v_mul_f32_e32 v167, 0xbfb8aa3b, v83
	v_mul_f32_e32 v168, 0xbfb8aa3b, v76
	v_mul_f32_e32 v169, 0xbfb8aa3b, v77
	v_mul_f32_e32 v170, 0xbfb8aa3b, v78
	v_mul_f32_e32 v171, 0xbfb8aa3b, v79
	v_exp_f32_e32 v164, v164
	v_exp_f32_e32 v165, v165
	v_exp_f32_e32 v166, v166
	v_exp_f32_e32 v167, v167
	v_exp_f32_e32 v168, v168
	v_exp_f32_e32 v169, v169
	v_exp_f32_e32 v170, v170
	v_exp_f32_e32 v171, v171
	v_add_f32_e32 v164, 1.0, v164
	v_add_f32_e32 v165, 1.0, v165
	v_add_f32_e32 v166, 1.0, v166
	v_add_f32_e32 v167, 1.0, v167
	v_add_f32_e32 v168, 1.0, v168
	v_add_f32_e32 v169, 1.0, v169
	v_add_f32_e32 v170, 1.0, v170
	v_add_f32_e32 v171, 1.0, v171
	v_rcp_f32_e32 v164, v164
	v_rcp_f32_e32 v165, v165
	v_rcp_f32_e32 v166, v166
	v_rcp_f32_e32 v167, v167
	v_rcp_f32_e32 v168, v168
	v_rcp_f32_e32 v169, v169
	v_rcp_f32_e32 v170, v170
	v_rcp_f32_e32 v171, v171
	v_mul_f32_e32 v80, v80, v164
	v_mul_f32_e32 v81, v81, v165
	v_mul_f32_e32 v82, v82, v166
	v_mul_f32_e32 v83, v83, v167
	v_mul_f32_e32 v76, v76, v168
	v_mul_f32_e32 v77, v77, v169
	v_mul_f32_e32 v78, v78, v170
	v_mul_f32_e32 v79, v79, v171
	v_cvt_pk_bf16_f32 v80, v80, v81
	v_cvt_pk_bf16_f32 v81, v82, v83
	v_cvt_pk_bf16_f32 v82, v76, v77
	v_cvt_pk_bf16_f32 v83, v78, v79
	global_store_dwordx4 v152, v[80:83], s[44:45]
	v_mul_f32_e32 v164, 0xbfb8aa3b, v72
	v_mul_f32_e32 v165, 0xbfb8aa3b, v73
	v_mul_f32_e32 v166, 0xbfb8aa3b, v74
	v_mul_f32_e32 v167, 0xbfb8aa3b, v75
	v_mul_f32_e32 v168, 0xbfb8aa3b, v68
	v_mul_f32_e32 v169, 0xbfb8aa3b, v69
	v_mul_f32_e32 v170, 0xbfb8aa3b, v70
	v_mul_f32_e32 v171, 0xbfb8aa3b, v71
	v_exp_f32_e32 v164, v164
	v_exp_f32_e32 v165, v165
	v_exp_f32_e32 v166, v166
	v_exp_f32_e32 v167, v167
	v_exp_f32_e32 v168, v168
	v_exp_f32_e32 v169, v169
	v_exp_f32_e32 v170, v170
	v_exp_f32_e32 v171, v171
	v_add_f32_e32 v164, 1.0, v164
	v_add_f32_e32 v165, 1.0, v165
	v_add_f32_e32 v166, 1.0, v166
	v_add_f32_e32 v167, 1.0, v167
	v_add_f32_e32 v168, 1.0, v168
	v_add_f32_e32 v169, 1.0, v169
	v_add_f32_e32 v170, 1.0, v170
	v_add_f32_e32 v171, 1.0, v171
	v_rcp_f32_e32 v164, v164
	v_rcp_f32_e32 v165, v165
	v_rcp_f32_e32 v166, v166
	v_rcp_f32_e32 v167, v167
	v_rcp_f32_e32 v168, v168
	v_rcp_f32_e32 v169, v169
	v_rcp_f32_e32 v170, v170
	v_rcp_f32_e32 v171, v171
	v_mul_f32_e32 v72, v72, v164
	v_mul_f32_e32 v73, v73, v165
	v_mul_f32_e32 v74, v74, v166
	v_mul_f32_e32 v75, v75, v167
	v_mul_f32_e32 v68, v68, v168
	v_mul_f32_e32 v69, v69, v169
	v_mul_f32_e32 v70, v70, v170
	v_mul_f32_e32 v71, v71, v171
	v_cvt_pk_bf16_f32 v72, v72, v73
	v_cvt_pk_bf16_f32 v73, v74, v75
	v_cvt_pk_bf16_f32 v74, v68, v69
	v_cvt_pk_bf16_f32 v75, v70, v71
	global_store_dwordx4 v152, v[72:75], s[44:45] offset:256
	v_add_u32_e32 v152, 0xbe000, v152
	v_mul_f32_e32 v164, 0xbfb8aa3b, v64
	v_mul_f32_e32 v165, 0xbfb8aa3b, v65
	v_mul_f32_e32 v166, 0xbfb8aa3b, v66
	v_mul_f32_e32 v167, 0xbfb8aa3b, v67
	v_mul_f32_e32 v168, 0xbfb8aa3b, v60
	v_mul_f32_e32 v169, 0xbfb8aa3b, v61
	v_mul_f32_e32 v170, 0xbfb8aa3b, v62
	v_mul_f32_e32 v171, 0xbfb8aa3b, v63
	v_exp_f32_e32 v164, v164
	v_exp_f32_e32 v165, v165
	v_exp_f32_e32 v166, v166
	v_exp_f32_e32 v167, v167
	v_exp_f32_e32 v168, v168
	v_exp_f32_e32 v169, v169
	v_exp_f32_e32 v170, v170
	v_exp_f32_e32 v171, v171
	v_add_f32_e32 v164, 1.0, v164
	v_add_f32_e32 v165, 1.0, v165
	v_add_f32_e32 v166, 1.0, v166
	v_add_f32_e32 v167, 1.0, v167
	v_add_f32_e32 v168, 1.0, v168
	v_add_f32_e32 v169, 1.0, v169
	v_add_f32_e32 v170, 1.0, v170
	v_add_f32_e32 v171, 1.0, v171
	v_rcp_f32_e32 v164, v164
	v_rcp_f32_e32 v165, v165
	v_rcp_f32_e32 v166, v166
	v_rcp_f32_e32 v167, v167
	v_rcp_f32_e32 v168, v168
	v_rcp_f32_e32 v169, v169
	v_rcp_f32_e32 v170, v170
	v_rcp_f32_e32 v171, v171
	v_mul_f32_e32 v64, v64, v164
	v_mul_f32_e32 v65, v65, v165
	v_mul_f32_e32 v66, v66, v166
	v_mul_f32_e32 v67, v67, v167
	v_mul_f32_e32 v60, v60, v168
	v_mul_f32_e32 v61, v61, v169
	v_mul_f32_e32 v62, v62, v170
	v_mul_f32_e32 v63, v63, v171
	v_cvt_pk_bf16_f32 v64, v64, v65
	v_cvt_pk_bf16_f32 v65, v66, v67
	v_cvt_pk_bf16_f32 v66, v60, v61
	v_cvt_pk_bf16_f32 v67, v62, v63
	global_store_dwordx4 v152, v[64:67], s[44:45]
	v_mul_f32_e32 v164, 0xbfb8aa3b, v56
	v_mul_f32_e32 v165, 0xbfb8aa3b, v57
	v_mul_f32_e32 v166, 0xbfb8aa3b, v58
	v_mul_f32_e32 v167, 0xbfb8aa3b, v59
	v_mul_f32_e32 v168, 0xbfb8aa3b, v52
	v_mul_f32_e32 v169, 0xbfb8aa3b, v53
	v_mul_f32_e32 v170, 0xbfb8aa3b, v54
	v_mul_f32_e32 v171, 0xbfb8aa3b, v55
	v_exp_f32_e32 v164, v164
	v_exp_f32_e32 v165, v165
	v_exp_f32_e32 v166, v166
	v_exp_f32_e32 v167, v167
	v_exp_f32_e32 v168, v168
	v_exp_f32_e32 v169, v169
	v_exp_f32_e32 v170, v170
	v_exp_f32_e32 v171, v171
	v_add_f32_e32 v164, 1.0, v164
	v_add_f32_e32 v165, 1.0, v165
	v_add_f32_e32 v166, 1.0, v166
	v_add_f32_e32 v167, 1.0, v167
	v_add_f32_e32 v168, 1.0, v168
	v_add_f32_e32 v169, 1.0, v169
	v_add_f32_e32 v170, 1.0, v170
	v_add_f32_e32 v171, 1.0, v171
	v_rcp_f32_e32 v164, v164
	v_rcp_f32_e32 v165, v165
	v_rcp_f32_e32 v166, v166
	v_rcp_f32_e32 v167, v167
	v_rcp_f32_e32 v168, v168
	v_rcp_f32_e32 v169, v169
	v_rcp_f32_e32 v170, v170
	v_rcp_f32_e32 v171, v171
	v_mul_f32_e32 v56, v56, v164
	v_mul_f32_e32 v57, v57, v165
	v_mul_f32_e32 v58, v58, v166
	v_mul_f32_e32 v59, v59, v167
	v_mul_f32_e32 v52, v52, v168
	v_mul_f32_e32 v53, v53, v169
	v_mul_f32_e32 v54, v54, v170
	v_mul_f32_e32 v55, v55, v171
	v_cvt_pk_bf16_f32 v56, v56, v57
	v_cvt_pk_bf16_f32 v57, v58, v59
	v_cvt_pk_bf16_f32 v58, v52, v53
	v_cvt_pk_bf16_f32 v59, v54, v55
	global_store_dwordx4 v152, v[56:59], s[44:45] offset:256
	v_add_u32_e32 v152, 0x26000, v152
	v_mul_f32_e32 v164, 0xbfb8aa3b, v48
	v_mul_f32_e32 v165, 0xbfb8aa3b, v49
	v_mul_f32_e32 v166, 0xbfb8aa3b, v50
	v_mul_f32_e32 v167, 0xbfb8aa3b, v51
	v_mul_f32_e32 v168, 0xbfb8aa3b, v44
	v_mul_f32_e32 v169, 0xbfb8aa3b, v45
	v_mul_f32_e32 v170, 0xbfb8aa3b, v46
	v_mul_f32_e32 v171, 0xbfb8aa3b, v47
	v_exp_f32_e32 v164, v164
	v_exp_f32_e32 v165, v165
	v_exp_f32_e32 v166, v166
	v_exp_f32_e32 v167, v167
	v_exp_f32_e32 v168, v168
	v_exp_f32_e32 v169, v169
	v_exp_f32_e32 v170, v170
	v_exp_f32_e32 v171, v171
	v_add_f32_e32 v164, 1.0, v164
	v_add_f32_e32 v165, 1.0, v165
	v_add_f32_e32 v166, 1.0, v166
	v_add_f32_e32 v167, 1.0, v167
	v_add_f32_e32 v168, 1.0, v168
	v_add_f32_e32 v169, 1.0, v169
	v_add_f32_e32 v170, 1.0, v170
	v_add_f32_e32 v171, 1.0, v171
	v_rcp_f32_e32 v164, v164
	v_rcp_f32_e32 v165, v165
	v_rcp_f32_e32 v166, v166
	v_rcp_f32_e32 v167, v167
	v_rcp_f32_e32 v168, v168
	v_rcp_f32_e32 v169, v169
	v_rcp_f32_e32 v170, v170
	v_rcp_f32_e32 v171, v171
	v_mul_f32_e32 v48, v48, v164
	v_mul_f32_e32 v49, v49, v165
	v_mul_f32_e32 v50, v50, v166
	v_mul_f32_e32 v51, v51, v167
	v_mul_f32_e32 v44, v44, v168
	v_mul_f32_e32 v45, v45, v169
	v_mul_f32_e32 v46, v46, v170
	v_mul_f32_e32 v47, v47, v171
	v_cvt_pk_bf16_f32 v48, v48, v49
	v_cvt_pk_bf16_f32 v49, v50, v51
	v_cvt_pk_bf16_f32 v50, v44, v45
	v_cvt_pk_bf16_f32 v51, v46, v47
	global_store_dwordx4 v152, v[48:51], s[44:45]
	v_mul_f32_e32 v164, 0xbfb8aa3b, v40
	v_mul_f32_e32 v165, 0xbfb8aa3b, v41
	v_mul_f32_e32 v166, 0xbfb8aa3b, v42
	v_mul_f32_e32 v167, 0xbfb8aa3b, v43
	v_mul_f32_e32 v168, 0xbfb8aa3b, v36
	v_mul_f32_e32 v169, 0xbfb8aa3b, v37
	v_mul_f32_e32 v170, 0xbfb8aa3b, v38
	v_mul_f32_e32 v171, 0xbfb8aa3b, v39
	v_exp_f32_e32 v164, v164
	v_exp_f32_e32 v165, v165
	v_exp_f32_e32 v166, v166
	v_exp_f32_e32 v167, v167
	v_exp_f32_e32 v168, v168
	v_exp_f32_e32 v169, v169
	v_exp_f32_e32 v170, v170
	v_exp_f32_e32 v171, v171
	v_add_f32_e32 v164, 1.0, v164
	v_add_f32_e32 v165, 1.0, v165
	v_add_f32_e32 v166, 1.0, v166
	v_add_f32_e32 v167, 1.0, v167
	v_add_f32_e32 v168, 1.0, v168
	v_add_f32_e32 v169, 1.0, v169
	v_add_f32_e32 v170, 1.0, v170
	v_add_f32_e32 v171, 1.0, v171
	v_rcp_f32_e32 v164, v164
	v_rcp_f32_e32 v165, v165
	v_rcp_f32_e32 v166, v166
	v_rcp_f32_e32 v167, v167
	v_rcp_f32_e32 v168, v168
	v_rcp_f32_e32 v169, v169
	v_rcp_f32_e32 v170, v170
	v_rcp_f32_e32 v171, v171
	v_mul_f32_e32 v40, v40, v164
	v_mul_f32_e32 v41, v41, v165
	v_mul_f32_e32 v42, v42, v166
	v_mul_f32_e32 v43, v43, v167
	v_mul_f32_e32 v36, v36, v168
	v_mul_f32_e32 v37, v37, v169
	v_mul_f32_e32 v38, v38, v170
	v_mul_f32_e32 v39, v39, v171
	v_cvt_pk_bf16_f32 v40, v40, v41
	v_cvt_pk_bf16_f32 v41, v42, v43
	v_cvt_pk_bf16_f32 v42, v36, v37
	v_cvt_pk_bf16_f32 v43, v38, v39
	global_store_dwordx4 v152, v[40:43], s[44:45] offset:256
	v_add_u32_e32 v152, 0x26000, v152
	v_mul_f32_e32 v164, 0xbfb8aa3b, v32
	v_mul_f32_e32 v165, 0xbfb8aa3b, v33
	v_mul_f32_e32 v166, 0xbfb8aa3b, v34
	v_mul_f32_e32 v167, 0xbfb8aa3b, v35
	v_mul_f32_e32 v168, 0xbfb8aa3b, v28
	v_mul_f32_e32 v169, 0xbfb8aa3b, v29
	v_mul_f32_e32 v170, 0xbfb8aa3b, v30
	v_mul_f32_e32 v171, 0xbfb8aa3b, v31
	v_exp_f32_e32 v164, v164
	v_exp_f32_e32 v165, v165
	v_exp_f32_e32 v166, v166
	v_exp_f32_e32 v167, v167
	v_exp_f32_e32 v168, v168
	v_exp_f32_e32 v169, v169
	v_exp_f32_e32 v170, v170
	v_exp_f32_e32 v171, v171
	v_add_f32_e32 v164, 1.0, v164
	v_add_f32_e32 v165, 1.0, v165
	v_add_f32_e32 v166, 1.0, v166
	v_add_f32_e32 v167, 1.0, v167
	v_add_f32_e32 v168, 1.0, v168
	v_add_f32_e32 v169, 1.0, v169
	v_add_f32_e32 v170, 1.0, v170
	v_add_f32_e32 v171, 1.0, v171
	v_rcp_f32_e32 v164, v164
	v_rcp_f32_e32 v165, v165
	v_rcp_f32_e32 v166, v166
	v_rcp_f32_e32 v167, v167
	v_rcp_f32_e32 v168, v168
	v_rcp_f32_e32 v169, v169
	v_rcp_f32_e32 v170, v170
	v_rcp_f32_e32 v171, v171
	v_mul_f32_e32 v32, v32, v164
	v_mul_f32_e32 v33, v33, v165
	v_mul_f32_e32 v34, v34, v166
	v_mul_f32_e32 v35, v35, v167
	v_mul_f32_e32 v28, v28, v168
	v_mul_f32_e32 v29, v29, v169
	v_mul_f32_e32 v30, v30, v170
	v_mul_f32_e32 v31, v31, v171
	v_cvt_pk_bf16_f32 v32, v32, v33
	v_cvt_pk_bf16_f32 v33, v34, v35
	v_cvt_pk_bf16_f32 v34, v28, v29
	v_cvt_pk_bf16_f32 v35, v30, v31
	global_store_dwordx4 v152, v[32:35], s[44:45]
	v_mul_f32_e32 v164, 0xbfb8aa3b, v24
	v_mul_f32_e32 v165, 0xbfb8aa3b, v25
	v_mul_f32_e32 v166, 0xbfb8aa3b, v26
	v_mul_f32_e32 v167, 0xbfb8aa3b, v27
	v_mul_f32_e32 v168, 0xbfb8aa3b, v20
	v_mul_f32_e32 v169, 0xbfb8aa3b, v21
	v_mul_f32_e32 v170, 0xbfb8aa3b, v22
	v_mul_f32_e32 v171, 0xbfb8aa3b, v23
	v_exp_f32_e32 v164, v164
	v_exp_f32_e32 v165, v165
	v_exp_f32_e32 v166, v166
	v_exp_f32_e32 v167, v167
	v_exp_f32_e32 v168, v168
	v_exp_f32_e32 v169, v169
	v_exp_f32_e32 v170, v170
	v_exp_f32_e32 v171, v171
	v_add_f32_e32 v164, 1.0, v164
	v_add_f32_e32 v165, 1.0, v165
	v_add_f32_e32 v166, 1.0, v166
	v_add_f32_e32 v167, 1.0, v167
	v_add_f32_e32 v168, 1.0, v168
	v_add_f32_e32 v169, 1.0, v169
	v_add_f32_e32 v170, 1.0, v170
	v_add_f32_e32 v171, 1.0, v171
	v_rcp_f32_e32 v164, v164
	v_rcp_f32_e32 v165, v165
	v_rcp_f32_e32 v166, v166
	v_rcp_f32_e32 v167, v167
	v_rcp_f32_e32 v168, v168
	v_rcp_f32_e32 v169, v169
	v_rcp_f32_e32 v170, v170
	v_rcp_f32_e32 v171, v171
	v_mul_f32_e32 v24, v24, v164
	v_mul_f32_e32 v25, v25, v165
	v_mul_f32_e32 v26, v26, v166
	v_mul_f32_e32 v27, v27, v167
	v_mul_f32_e32 v20, v20, v168
	v_mul_f32_e32 v21, v21, v169
	v_mul_f32_e32 v22, v22, v170
	v_mul_f32_e32 v23, v23, v171
	v_cvt_pk_bf16_f32 v24, v24, v25
	v_cvt_pk_bf16_f32 v25, v26, v27
	v_cvt_pk_bf16_f32 v26, v20, v21
	v_cvt_pk_bf16_f32 v27, v22, v23
	global_store_dwordx4 v152, v[24:27], s[44:45] offset:256
	v_add_u32_e32 v152, 0x26000, v152
	v_mul_f32_e32 v164, 0xbfb8aa3b, v16
	v_mul_f32_e32 v165, 0xbfb8aa3b, v17
	v_mul_f32_e32 v166, 0xbfb8aa3b, v18
	v_mul_f32_e32 v167, 0xbfb8aa3b, v19
	v_mul_f32_e32 v168, 0xbfb8aa3b, v12
	v_mul_f32_e32 v169, 0xbfb8aa3b, v13
	v_mul_f32_e32 v170, 0xbfb8aa3b, v14
	v_mul_f32_e32 v171, 0xbfb8aa3b, v15
	v_exp_f32_e32 v164, v164
	v_exp_f32_e32 v165, v165
	v_exp_f32_e32 v166, v166
	v_exp_f32_e32 v167, v167
	v_exp_f32_e32 v168, v168
	v_exp_f32_e32 v169, v169
	v_exp_f32_e32 v170, v170
	v_exp_f32_e32 v171, v171
	v_add_f32_e32 v164, 1.0, v164
	v_add_f32_e32 v165, 1.0, v165
	v_add_f32_e32 v166, 1.0, v166
	v_add_f32_e32 v167, 1.0, v167
	v_add_f32_e32 v168, 1.0, v168
	v_add_f32_e32 v169, 1.0, v169
	v_add_f32_e32 v170, 1.0, v170
	v_add_f32_e32 v171, 1.0, v171
	v_rcp_f32_e32 v164, v164
	v_rcp_f32_e32 v165, v165
	v_rcp_f32_e32 v166, v166
	v_rcp_f32_e32 v167, v167
	v_rcp_f32_e32 v168, v168
	v_rcp_f32_e32 v169, v169
	v_rcp_f32_e32 v170, v170
	v_rcp_f32_e32 v171, v171
	v_mul_f32_e32 v16, v16, v164
	v_mul_f32_e32 v17, v17, v165
	v_mul_f32_e32 v18, v18, v166
	v_mul_f32_e32 v19, v19, v167
	v_mul_f32_e32 v12, v12, v168
	v_mul_f32_e32 v13, v13, v169
	v_mul_f32_e32 v14, v14, v170
	v_mul_f32_e32 v15, v15, v171
	v_cvt_pk_bf16_f32 v16, v16, v17
	v_cvt_pk_bf16_f32 v17, v18, v19
	v_cvt_pk_bf16_f32 v18, v12, v13
	v_cvt_pk_bf16_f32 v19, v14, v15
	global_store_dwordx4 v152, v[16:19], s[44:45]
	v_mul_f32_e32 v164, 0xbfb8aa3b, v8
	v_mul_f32_e32 v165, 0xbfb8aa3b, v9
	v_mul_f32_e32 v166, 0xbfb8aa3b, v10
	v_mul_f32_e32 v167, 0xbfb8aa3b, v11
	v_mul_f32_e32 v168, 0xbfb8aa3b, v4
	v_mul_f32_e32 v169, 0xbfb8aa3b, v5
	v_mul_f32_e32 v170, 0xbfb8aa3b, v6
	v_mul_f32_e32 v171, 0xbfb8aa3b, v7
	v_exp_f32_e32 v164, v164
	v_exp_f32_e32 v165, v165
	v_exp_f32_e32 v166, v166
	v_exp_f32_e32 v167, v167
	v_exp_f32_e32 v168, v168
	v_exp_f32_e32 v169, v169
	v_exp_f32_e32 v170, v170
	v_exp_f32_e32 v171, v171
	v_add_f32_e32 v164, 1.0, v164
	v_add_f32_e32 v165, 1.0, v165
	v_add_f32_e32 v166, 1.0, v166
	v_add_f32_e32 v167, 1.0, v167
	v_add_f32_e32 v168, 1.0, v168
	v_add_f32_e32 v169, 1.0, v169
	v_add_f32_e32 v170, 1.0, v170
	v_add_f32_e32 v171, 1.0, v171
	v_rcp_f32_e32 v164, v164
	v_rcp_f32_e32 v165, v165
	v_rcp_f32_e32 v166, v166
	v_rcp_f32_e32 v167, v167
	v_rcp_f32_e32 v168, v168
	v_rcp_f32_e32 v169, v169
	v_rcp_f32_e32 v170, v170
	v_rcp_f32_e32 v171, v171
	v_mul_f32_e32 v8, v8, v164
	v_mul_f32_e32 v9, v9, v165
	v_mul_f32_e32 v10, v10, v166
	v_mul_f32_e32 v11, v11, v167
	v_mul_f32_e32 v4, v4, v168
	v_mul_f32_e32 v5, v5, v169
	v_mul_f32_e32 v6, v6, v170
	v_mul_f32_e32 v7, v7, v171
	v_cvt_pk_bf16_f32 v8, v8, v9
	v_cvt_pk_bf16_f32 v9, v10, v11
	v_cvt_pk_bf16_f32 v10, v4, v5
	v_cvt_pk_bf16_f32 v11, v6, v7
	global_store_dwordx4 v152, v[8:11], s[44:45] offset:256
	s_branch .LBB0_590
.Lepi_gelu:
	v_mul_lo_u32 v152, v195, s30
	v_add_u32_e32 v153, s9, v191
	v_lshl_add_u32 v152, v153, 1, v152
	v_mul_f32_e32 v164, 0x3d372713, v128
	v_mul_f32_e32 v165, 0x3d372713, v129
	v_mul_f32_e32 v166, 0x3d372713, v130
	v_mul_f32_e32 v167, 0x3d372713, v131
	v_mul_f32_e32 v168, 0x3d372713, v124
	v_mul_f32_e32 v169, 0x3d372713, v125
	v_mul_f32_e32 v170, 0x3d372713, v126
	v_mul_f32_e32 v171, 0x3d372713, v127
	v_mul_f32_e32 v164, v128, v164
	v_mul_f32_e32 v165, v129, v165
	v_mul_f32_e32 v166, v130, v166
	v_mul_f32_e32 v167, v131, v167
	v_mul_f32_e32 v168, v124, v168
	v_mul_f32_e32 v169, v125, v169
	v_mul_f32_e32 v170, v126, v170
	v_mul_f32_e32 v171, v127, v171
	v_fma_f32 v164, v128, v164, v128
	v_fma_f32 v165, v129, v165, v129
	v_fma_f32 v166, v130, v166, v130
	v_fma_f32 v167, v131, v167, v131
	v_fma_f32 v168, v124, v168, v124
	v_fma_f32 v169, v125, v169, v125
	v_fma_f32 v170, v126, v170, v126
	v_fma_f32 v171, v127, v171, v127
	v_mul_f32_e32 v164, 0x3fcc422a, v164
	v_mul_f32_e32 v165, 0x3fcc422a, v165
	v_mul_f32_e32 v166, 0x3fcc422a, v166
	v_mul_f32_e32 v167, 0x3fcc422a, v167
	v_mul_f32_e32 v168, 0x3fcc422a, v168
	v_mul_f32_e32 v169, 0x3fcc422a, v169
	v_mul_f32_e32 v170, 0x3fcc422a, v170
	v_mul_f32_e32 v171, 0x3fcc422a, v171
	v_mul_f32_e32 v164, 0xbfb8aa3b, v164
	v_mul_f32_e32 v165, 0xbfb8aa3b, v165
	v_mul_f32_e32 v166, 0xbfb8aa3b, v166
	v_mul_f32_e32 v167, 0xbfb8aa3b, v167
	v_mul_f32_e32 v168, 0xbfb8aa3b, v168
	v_mul_f32_e32 v169, 0xbfb8aa3b, v169
	v_mul_f32_e32 v170, 0xbfb8aa3b, v170
	v_mul_f32_e32 v171, 0xbfb8aa3b, v171
	v_exp_f32_e32 v164, v164
	v_exp_f32_e32 v165, v165
	v_exp_f32_e32 v166, v166
	v_exp_f32_e32 v167, v167
	v_exp_f32_e32 v168, v168
	v_exp_f32_e32 v169, v169
	v_exp_f32_e32 v170, v170
	v_exp_f32_e32 v171, v171
	v_add_f32_e32 v164, 1.0, v164
	v_add_f32_e32 v165, 1.0, v165
	v_add_f32_e32 v166, 1.0, v166
	v_add_f32_e32 v167, 1.0, v167
	v_add_f32_e32 v168, 1.0, v168
	v_add_f32_e32 v169, 1.0, v169
	v_add_f32_e32 v170, 1.0, v170
	v_add_f32_e32 v171, 1.0, v171
	v_rcp_f32_e32 v164, v164
	v_rcp_f32_e32 v165, v165
	v_rcp_f32_e32 v166, v166
	v_rcp_f32_e32 v167, v167
	v_rcp_f32_e32 v168, v168
	v_rcp_f32_e32 v169, v169
	v_rcp_f32_e32 v170, v170
	v_rcp_f32_e32 v171, v171
	v_mul_f32_e32 v128, v128, v164
	v_mul_f32_e32 v129, v129, v165
	v_mul_f32_e32 v130, v130, v166
	v_mul_f32_e32 v131, v131, v167
	v_mul_f32_e32 v124, v124, v168
	v_mul_f32_e32 v125, v125, v169
	v_mul_f32_e32 v126, v126, v170
	v_mul_f32_e32 v127, v127, v171
	v_cvt_pk_bf16_f32 v128, v128, v129
	v_cvt_pk_bf16_f32 v129, v130, v131
	v_cvt_pk_bf16_f32 v130, v124, v125
	v_cvt_pk_bf16_f32 v131, v126, v127
	global_store_dwordx4 v152, v[128:131], s[44:45]
	v_mul_f32_e32 v164, 0x3d372713, v120
	v_mul_f32_e32 v165, 0x3d372713, v121
	v_mul_f32_e32 v166, 0x3d372713, v122
	v_mul_f32_e32 v167, 0x3d372713, v123
	v_mul_f32_e32 v168, 0x3d372713, v116
	v_mul_f32_e32 v169, 0x3d372713, v117
	v_mul_f32_e32 v170, 0x3d372713, v118
	v_mul_f32_e32 v171, 0x3d372713, v119
	v_mul_f32_e32 v164, v120, v164
	v_mul_f32_e32 v165, v121, v165
	v_mul_f32_e32 v166, v122, v166
	v_mul_f32_e32 v167, v123, v167
	v_mul_f32_e32 v168, v116, v168
	v_mul_f32_e32 v169, v117, v169
	v_mul_f32_e32 v170, v118, v170
	v_mul_f32_e32 v171, v119, v171
	v_fma_f32 v164, v120, v164, v120
	v_fma_f32 v165, v121, v165, v121
	v_fma_f32 v166, v122, v166, v122
	v_fma_f32 v167, v123, v167, v123
	v_fma_f32 v168, v116, v168, v116
	v_fma_f32 v169, v117, v169, v117
	v_fma_f32 v170, v118, v170, v118
	v_fma_f32 v171, v119, v171, v119
	v_mul_f32_e32 v164, 0x3fcc422a, v164
	v_mul_f32_e32 v165, 0x3fcc422a, v165
	v_mul_f32_e32 v166, 0x3fcc422a, v166
	v_mul_f32_e32 v167, 0x3fcc422a, v167
	v_mul_f32_e32 v168, 0x3fcc422a, v168
	v_mul_f32_e32 v169, 0x3fcc422a, v169
	v_mul_f32_e32 v170, 0x3fcc422a, v170
	v_mul_f32_e32 v171, 0x3fcc422a, v171
	v_mul_f32_e32 v164, 0xbfb8aa3b, v164
	v_mul_f32_e32 v165, 0xbfb8aa3b, v165
	v_mul_f32_e32 v166, 0xbfb8aa3b, v166
	v_mul_f32_e32 v167, 0xbfb8aa3b, v167
	v_mul_f32_e32 v168, 0xbfb8aa3b, v168
	v_mul_f32_e32 v169, 0xbfb8aa3b, v169
	v_mul_f32_e32 v170, 0xbfb8aa3b, v170
	v_mul_f32_e32 v171, 0xbfb8aa3b, v171
	v_exp_f32_e32 v164, v164
	v_exp_f32_e32 v165, v165
	v_exp_f32_e32 v166, v166
	v_exp_f32_e32 v167, v167
	v_exp_f32_e32 v168, v168
	v_exp_f32_e32 v169, v169
	v_exp_f32_e32 v170, v170
	v_exp_f32_e32 v171, v171
	v_add_f32_e32 v164, 1.0, v164
	v_add_f32_e32 v165, 1.0, v165
	v_add_f32_e32 v166, 1.0, v166
	v_add_f32_e32 v167, 1.0, v167
	v_add_f32_e32 v168, 1.0, v168
	v_add_f32_e32 v169, 1.0, v169
	v_add_f32_e32 v170, 1.0, v170
	v_add_f32_e32 v171, 1.0, v171
	v_rcp_f32_e32 v164, v164
	v_rcp_f32_e32 v165, v165
	v_rcp_f32_e32 v166, v166
	v_rcp_f32_e32 v167, v167
	v_rcp_f32_e32 v168, v168
	v_rcp_f32_e32 v169, v169
	v_rcp_f32_e32 v170, v170
	v_rcp_f32_e32 v171, v171
	v_mul_f32_e32 v120, v120, v164
	v_mul_f32_e32 v121, v121, v165
	v_mul_f32_e32 v122, v122, v166
	v_mul_f32_e32 v123, v123, v167
	v_mul_f32_e32 v116, v116, v168
	v_mul_f32_e32 v117, v117, v169
	v_mul_f32_e32 v118, v118, v170
	v_mul_f32_e32 v119, v119, v171
	v_cvt_pk_bf16_f32 v120, v120, v121
	v_cvt_pk_bf16_f32 v121, v122, v123
	v_cvt_pk_bf16_f32 v122, v116, v117
	v_cvt_pk_bf16_f32 v123, v118, v119
	global_store_dwordx4 v152, v[120:123], s[44:45] offset:256
	v_add_u32_e32 v152, 0x26000, v152
	v_mul_f32_e32 v164, 0x3d372713, v112
	v_mul_f32_e32 v165, 0x3d372713, v113
	v_mul_f32_e32 v166, 0x3d372713, v114
	v_mul_f32_e32 v167, 0x3d372713, v115
	v_mul_f32_e32 v168, 0x3d372713, v108
	v_mul_f32_e32 v169, 0x3d372713, v109
	v_mul_f32_e32 v170, 0x3d372713, v110
	v_mul_f32_e32 v171, 0x3d372713, v111
	v_mul_f32_e32 v164, v112, v164
	v_mul_f32_e32 v165, v113, v165
	v_mul_f32_e32 v166, v114, v166
	v_mul_f32_e32 v167, v115, v167
	v_mul_f32_e32 v168, v108, v168
	v_mul_f32_e32 v169, v109, v169
	v_mul_f32_e32 v170, v110, v170
	v_mul_f32_e32 v171, v111, v171
	v_fma_f32 v164, v112, v164, v112
	v_fma_f32 v165, v113, v165, v113
	v_fma_f32 v166, v114, v166, v114
	v_fma_f32 v167, v115, v167, v115
	v_fma_f32 v168, v108, v168, v108
	v_fma_f32 v169, v109, v169, v109
	v_fma_f32 v170, v110, v170, v110
	v_fma_f32 v171, v111, v171, v111
	v_mul_f32_e32 v164, 0x3fcc422a, v164
	v_mul_f32_e32 v165, 0x3fcc422a, v165
	v_mul_f32_e32 v166, 0x3fcc422a, v166
	v_mul_f32_e32 v167, 0x3fcc422a, v167
	v_mul_f32_e32 v168, 0x3fcc422a, v168
	v_mul_f32_e32 v169, 0x3fcc422a, v169
	v_mul_f32_e32 v170, 0x3fcc422a, v170
	v_mul_f32_e32 v171, 0x3fcc422a, v171
	v_mul_f32_e32 v164, 0xbfb8aa3b, v164
	v_mul_f32_e32 v165, 0xbfb8aa3b, v165
	v_mul_f32_e32 v166, 0xbfb8aa3b, v166
	v_mul_f32_e32 v167, 0xbfb8aa3b, v167
	v_mul_f32_e32 v168, 0xbfb8aa3b, v168
	v_mul_f32_e32 v169, 0xbfb8aa3b, v169
	v_mul_f32_e32 v170, 0xbfb8aa3b, v170
	v_mul_f32_e32 v171, 0xbfb8aa3b, v171
	v_exp_f32_e32 v164, v164
	v_exp_f32_e32 v165, v165
	v_exp_f32_e32 v166, v166
	v_exp_f32_e32 v167, v167
	v_exp_f32_e32 v168, v168
	v_exp_f32_e32 v169, v169
	v_exp_f32_e32 v170, v170
	v_exp_f32_e32 v171, v171
	v_add_f32_e32 v164, 1.0, v164
	v_add_f32_e32 v165, 1.0, v165
	v_add_f32_e32 v166, 1.0, v166
	v_add_f32_e32 v167, 1.0, v167
	v_add_f32_e32 v168, 1.0, v168
	v_add_f32_e32 v169, 1.0, v169
	v_add_f32_e32 v170, 1.0, v170
	v_add_f32_e32 v171, 1.0, v171
	v_rcp_f32_e32 v164, v164
	v_rcp_f32_e32 v165, v165
	v_rcp_f32_e32 v166, v166
	v_rcp_f32_e32 v167, v167
	v_rcp_f32_e32 v168, v168
	v_rcp_f32_e32 v169, v169
	v_rcp_f32_e32 v170, v170
	v_rcp_f32_e32 v171, v171
	v_mul_f32_e32 v112, v112, v164
	v_mul_f32_e32 v113, v113, v165
	v_mul_f32_e32 v114, v114, v166
	v_mul_f32_e32 v115, v115, v167
	v_mul_f32_e32 v108, v108, v168
	v_mul_f32_e32 v109, v109, v169
	v_mul_f32_e32 v110, v110, v170
	v_mul_f32_e32 v111, v111, v171
	v_cvt_pk_bf16_f32 v112, v112, v113
	v_cvt_pk_bf16_f32 v113, v114, v115
	v_cvt_pk_bf16_f32 v114, v108, v109
	v_cvt_pk_bf16_f32 v115, v110, v111
	global_store_dwordx4 v152, v[112:115], s[44:45]
	v_mul_f32_e32 v164, 0x3d372713, v104
	v_mul_f32_e32 v165, 0x3d372713, v105
	v_mul_f32_e32 v166, 0x3d372713, v106
	v_mul_f32_e32 v167, 0x3d372713, v107
	v_mul_f32_e32 v168, 0x3d372713, v100
	v_mul_f32_e32 v169, 0x3d372713, v101
	v_mul_f32_e32 v170, 0x3d372713, v102
	v_mul_f32_e32 v171, 0x3d372713, v103
	v_mul_f32_e32 v164, v104, v164
	v_mul_f32_e32 v165, v105, v165
	v_mul_f32_e32 v166, v106, v166
	v_mul_f32_e32 v167, v107, v167
	v_mul_f32_e32 v168, v100, v168
	v_mul_f32_e32 v169, v101, v169
	v_mul_f32_e32 v170, v102, v170
	v_mul_f32_e32 v171, v103, v171
	v_fma_f32 v164, v104, v164, v104
	v_fma_f32 v165, v105, v165, v105
	v_fma_f32 v166, v106, v166, v106
	v_fma_f32 v167, v107, v167, v107
	v_fma_f32 v168, v100, v168, v100
	v_fma_f32 v169, v101, v169, v101
	v_fma_f32 v170, v102, v170, v102
	v_fma_f32 v171, v103, v171, v103
	v_mul_f32_e32 v164, 0x3fcc422a, v164
	v_mul_f32_e32 v165, 0x3fcc422a, v165
	v_mul_f32_e32 v166, 0x3fcc422a, v166
	v_mul_f32_e32 v167, 0x3fcc422a, v167
	v_mul_f32_e32 v168, 0x3fcc422a, v168
	v_mul_f32_e32 v169, 0x3fcc422a, v169
	v_mul_f32_e32 v170, 0x3fcc422a, v170
	v_mul_f32_e32 v171, 0x3fcc422a, v171
	v_mul_f32_e32 v164, 0xbfb8aa3b, v164
	v_mul_f32_e32 v165, 0xbfb8aa3b, v165
	v_mul_f32_e32 v166, 0xbfb8aa3b, v166
	v_mul_f32_e32 v167, 0xbfb8aa3b, v167
	v_mul_f32_e32 v168, 0xbfb8aa3b, v168
	v_mul_f32_e32 v169, 0xbfb8aa3b, v169
	v_mul_f32_e32 v170, 0xbfb8aa3b, v170
	v_mul_f32_e32 v171, 0xbfb8aa3b, v171
	v_exp_f32_e32 v164, v164
	v_exp_f32_e32 v165, v165
	v_exp_f32_e32 v166, v166
	v_exp_f32_e32 v167, v167
	v_exp_f32_e32 v168, v168
	v_exp_f32_e32 v169, v169
	v_exp_f32_e32 v170, v170
	v_exp_f32_e32 v171, v171
	v_add_f32_e32 v164, 1.0, v164
	v_add_f32_e32 v165, 1.0, v165
	v_add_f32_e32 v166, 1.0, v166
	v_add_f32_e32 v167, 1.0, v167
	v_add_f32_e32 v168, 1.0, v168
	v_add_f32_e32 v169, 1.0, v169
	v_add_f32_e32 v170, 1.0, v170
	v_add_f32_e32 v171, 1.0, v171
	v_rcp_f32_e32 v164, v164
	v_rcp_f32_e32 v165, v165
	v_rcp_f32_e32 v166, v166
	v_rcp_f32_e32 v167, v167
	v_rcp_f32_e32 v168, v168
	v_rcp_f32_e32 v169, v169
	v_rcp_f32_e32 v170, v170
	v_rcp_f32_e32 v171, v171
	v_mul_f32_e32 v104, v104, v164
	v_mul_f32_e32 v105, v105, v165
	v_mul_f32_e32 v106, v106, v166
	v_mul_f32_e32 v107, v107, v167
	v_mul_f32_e32 v100, v100, v168
	v_mul_f32_e32 v101, v101, v169
	v_mul_f32_e32 v102, v102, v170
	v_mul_f32_e32 v103, v103, v171
	v_cvt_pk_bf16_f32 v104, v104, v105
	v_cvt_pk_bf16_f32 v105, v106, v107
	v_cvt_pk_bf16_f32 v106, v100, v101
	v_cvt_pk_bf16_f32 v107, v102, v103
	global_store_dwordx4 v152, v[104:107], s[44:45] offset:256
	v_add_u32_e32 v152, 0x26000, v152
	v_mul_f32_e32 v164, 0x3d372713, v96
	v_mul_f32_e32 v165, 0x3d372713, v97
	v_mul_f32_e32 v166, 0x3d372713, v98
	v_mul_f32_e32 v167, 0x3d372713, v99
	v_mul_f32_e32 v168, 0x3d372713, v92
	v_mul_f32_e32 v169, 0x3d372713, v93
	v_mul_f32_e32 v170, 0x3d372713, v94
	v_mul_f32_e32 v171, 0x3d372713, v95
	v_mul_f32_e32 v164, v96, v164
	v_mul_f32_e32 v165, v97, v165
	v_mul_f32_e32 v166, v98, v166
	v_mul_f32_e32 v167, v99, v167
	v_mul_f32_e32 v168, v92, v168
	v_mul_f32_e32 v169, v93, v169
	v_mul_f32_e32 v170, v94, v170
	v_mul_f32_e32 v171, v95, v171
	v_fma_f32 v164, v96, v164, v96
	v_fma_f32 v165, v97, v165, v97
	v_fma_f32 v166, v98, v166, v98
	v_fma_f32 v167, v99, v167, v99
	v_fma_f32 v168, v92, v168, v92
	v_fma_f32 v169, v93, v169, v93
	v_fma_f32 v170, v94, v170, v94
	v_fma_f32 v171, v95, v171, v95
	v_mul_f32_e32 v164, 0x3fcc422a, v164
	v_mul_f32_e32 v165, 0x3fcc422a, v165
	v_mul_f32_e32 v166, 0x3fcc422a, v166
	v_mul_f32_e32 v167, 0x3fcc422a, v167
	v_mul_f32_e32 v168, 0x3fcc422a, v168
	v_mul_f32_e32 v169, 0x3fcc422a, v169
	v_mul_f32_e32 v170, 0x3fcc422a, v170
	v_mul_f32_e32 v171, 0x3fcc422a, v171
	v_mul_f32_e32 v164, 0xbfb8aa3b, v164
	v_mul_f32_e32 v165, 0xbfb8aa3b, v165
	v_mul_f32_e32 v166, 0xbfb8aa3b, v166
	v_mul_f32_e32 v167, 0xbfb8aa3b, v167
	v_mul_f32_e32 v168, 0xbfb8aa3b, v168
	v_mul_f32_e32 v169, 0xbfb8aa3b, v169
	v_mul_f32_e32 v170, 0xbfb8aa3b, v170
	v_mul_f32_e32 v171, 0xbfb8aa3b, v171
	v_exp_f32_e32 v164, v164
	v_exp_f32_e32 v165, v165
	v_exp_f32_e32 v166, v166
	v_exp_f32_e32 v167, v167
	v_exp_f32_e32 v168, v168
	v_exp_f32_e32 v169, v169
	v_exp_f32_e32 v170, v170
	v_exp_f32_e32 v171, v171
	v_add_f32_e32 v164, 1.0, v164
	v_add_f32_e32 v165, 1.0, v165
	v_add_f32_e32 v166, 1.0, v166
	v_add_f32_e32 v167, 1.0, v167
	v_add_f32_e32 v168, 1.0, v168
	v_add_f32_e32 v169, 1.0, v169
	v_add_f32_e32 v170, 1.0, v170
	v_add_f32_e32 v171, 1.0, v171
	v_rcp_f32_e32 v164, v164
	v_rcp_f32_e32 v165, v165
	v_rcp_f32_e32 v166, v166
	v_rcp_f32_e32 v167, v167
	v_rcp_f32_e32 v168, v168
	v_rcp_f32_e32 v169, v169
	v_rcp_f32_e32 v170, v170
	v_rcp_f32_e32 v171, v171
	v_mul_f32_e32 v96, v96, v164
	v_mul_f32_e32 v97, v97, v165
	v_mul_f32_e32 v98, v98, v166
	v_mul_f32_e32 v99, v99, v167
	v_mul_f32_e32 v92, v92, v168
	v_mul_f32_e32 v93, v93, v169
	v_mul_f32_e32 v94, v94, v170
	v_mul_f32_e32 v95, v95, v171
	v_cvt_pk_bf16_f32 v96, v96, v97
	v_cvt_pk_bf16_f32 v97, v98, v99
	v_cvt_pk_bf16_f32 v98, v92, v93
	v_cvt_pk_bf16_f32 v99, v94, v95
	global_store_dwordx4 v152, v[96:99], s[44:45]
	v_mul_f32_e32 v164, 0x3d372713, v88
	v_mul_f32_e32 v165, 0x3d372713, v89
	v_mul_f32_e32 v166, 0x3d372713, v90
	v_mul_f32_e32 v167, 0x3d372713, v91
	v_mul_f32_e32 v168, 0x3d372713, v84
	v_mul_f32_e32 v169, 0x3d372713, v85
	v_mul_f32_e32 v170, 0x3d372713, v86
	v_mul_f32_e32 v171, 0x3d372713, v87
	v_mul_f32_e32 v164, v88, v164
	v_mul_f32_e32 v165, v89, v165
	v_mul_f32_e32 v166, v90, v166
	v_mul_f32_e32 v167, v91, v167
	v_mul_f32_e32 v168, v84, v168
	v_mul_f32_e32 v169, v85, v169
	v_mul_f32_e32 v170, v86, v170
	v_mul_f32_e32 v171, v87, v171
	v_fma_f32 v164, v88, v164, v88
	v_fma_f32 v165, v89, v165, v89
	v_fma_f32 v166, v90, v166, v90
	v_fma_f32 v167, v91, v167, v91
	v_fma_f32 v168, v84, v168, v84
	v_fma_f32 v169, v85, v169, v85
	v_fma_f32 v170, v86, v170, v86
	v_fma_f32 v171, v87, v171, v87
	v_mul_f32_e32 v164, 0x3fcc422a, v164
	v_mul_f32_e32 v165, 0x3fcc422a, v165
	v_mul_f32_e32 v166, 0x3fcc422a, v166
	v_mul_f32_e32 v167, 0x3fcc422a, v167
	v_mul_f32_e32 v168, 0x3fcc422a, v168
	v_mul_f32_e32 v169, 0x3fcc422a, v169
	v_mul_f32_e32 v170, 0x3fcc422a, v170
	v_mul_f32_e32 v171, 0x3fcc422a, v171
	v_mul_f32_e32 v164, 0xbfb8aa3b, v164
	v_mul_f32_e32 v165, 0xbfb8aa3b, v165
	v_mul_f32_e32 v166, 0xbfb8aa3b, v166
	v_mul_f32_e32 v167, 0xbfb8aa3b, v167
	v_mul_f32_e32 v168, 0xbfb8aa3b, v168
	v_mul_f32_e32 v169, 0xbfb8aa3b, v169
	v_mul_f32_e32 v170, 0xbfb8aa3b, v170
	v_mul_f32_e32 v171, 0xbfb8aa3b, v171
	v_exp_f32_e32 v164, v164
	v_exp_f32_e32 v165, v165
	v_exp_f32_e32 v166, v166
	v_exp_f32_e32 v167, v167
	v_exp_f32_e32 v168, v168
	v_exp_f32_e32 v169, v169
	v_exp_f32_e32 v170, v170
	v_exp_f32_e32 v171, v171
	v_add_f32_e32 v164, 1.0, v164
	v_add_f32_e32 v165, 1.0, v165
	v_add_f32_e32 v166, 1.0, v166
	v_add_f32_e32 v167, 1.0, v167
	v_add_f32_e32 v168, 1.0, v168
	v_add_f32_e32 v169, 1.0, v169
	v_add_f32_e32 v170, 1.0, v170
	v_add_f32_e32 v171, 1.0, v171
	v_rcp_f32_e32 v164, v164
	v_rcp_f32_e32 v165, v165
	v_rcp_f32_e32 v166, v166
	v_rcp_f32_e32 v167, v167
	v_rcp_f32_e32 v168, v168
	v_rcp_f32_e32 v169, v169
	v_rcp_f32_e32 v170, v170
	v_rcp_f32_e32 v171, v171
	v_mul_f32_e32 v88, v88, v164
	v_mul_f32_e32 v89, v89, v165
	v_mul_f32_e32 v90, v90, v166
	v_mul_f32_e32 v91, v91, v167
	v_mul_f32_e32 v84, v84, v168
	v_mul_f32_e32 v85, v85, v169
	v_mul_f32_e32 v86, v86, v170
	v_mul_f32_e32 v87, v87, v171
	v_cvt_pk_bf16_f32 v88, v88, v89
	v_cvt_pk_bf16_f32 v89, v90, v91
	v_cvt_pk_bf16_f32 v90, v84, v85
	v_cvt_pk_bf16_f32 v91, v86, v87
	global_store_dwordx4 v152, v[88:91], s[44:45] offset:256
	v_add_u32_e32 v152, 0x26000, v152
	v_mul_f32_e32 v164, 0x3d372713, v80
	v_mul_f32_e32 v165, 0x3d372713, v81
	v_mul_f32_e32 v166, 0x3d372713, v82
	v_mul_f32_e32 v167, 0x3d372713, v83
	v_mul_f32_e32 v168, 0x3d372713, v76
	v_mul_f32_e32 v169, 0x3d372713, v77
	v_mul_f32_e32 v170, 0x3d372713, v78
	v_mul_f32_e32 v171, 0x3d372713, v79
	v_mul_f32_e32 v164, v80, v164
	v_mul_f32_e32 v165, v81, v165
	v_mul_f32_e32 v166, v82, v166
	v_mul_f32_e32 v167, v83, v167
	v_mul_f32_e32 v168, v76, v168
	v_mul_f32_e32 v169, v77, v169
	v_mul_f32_e32 v170, v78, v170
	v_mul_f32_e32 v171, v79, v171
	v_fma_f32 v164, v80, v164, v80
	v_fma_f32 v165, v81, v165, v81
	v_fma_f32 v166, v82, v166, v82
	v_fma_f32 v167, v83, v167, v83
	v_fma_f32 v168, v76, v168, v76
	v_fma_f32 v169, v77, v169, v77
	v_fma_f32 v170, v78, v170, v78
	v_fma_f32 v171, v79, v171, v79
	v_mul_f32_e32 v164, 0x3fcc422a, v164
	v_mul_f32_e32 v165, 0x3fcc422a, v165
	v_mul_f32_e32 v166, 0x3fcc422a, v166
	v_mul_f32_e32 v167, 0x3fcc422a, v167
	v_mul_f32_e32 v168, 0x3fcc422a, v168
	v_mul_f32_e32 v169, 0x3fcc422a, v169
	v_mul_f32_e32 v170, 0x3fcc422a, v170
	v_mul_f32_e32 v171, 0x3fcc422a, v171
	v_mul_f32_e32 v164, 0xbfb8aa3b, v164
	v_mul_f32_e32 v165, 0xbfb8aa3b, v165
	v_mul_f32_e32 v166, 0xbfb8aa3b, v166
	v_mul_f32_e32 v167, 0xbfb8aa3b, v167
	v_mul_f32_e32 v168, 0xbfb8aa3b, v168
	v_mul_f32_e32 v169, 0xbfb8aa3b, v169
	v_mul_f32_e32 v170, 0xbfb8aa3b, v170
	v_mul_f32_e32 v171, 0xbfb8aa3b, v171
	v_exp_f32_e32 v164, v164
	v_exp_f32_e32 v165, v165
	v_exp_f32_e32 v166, v166
	v_exp_f32_e32 v167, v167
	v_exp_f32_e32 v168, v168
	v_exp_f32_e32 v169, v169
	v_exp_f32_e32 v170, v170
	v_exp_f32_e32 v171, v171
	v_add_f32_e32 v164, 1.0, v164
	v_add_f32_e32 v165, 1.0, v165
	v_add_f32_e32 v166, 1.0, v166
	v_add_f32_e32 v167, 1.0, v167
	v_add_f32_e32 v168, 1.0, v168
	v_add_f32_e32 v169, 1.0, v169
	v_add_f32_e32 v170, 1.0, v170
	v_add_f32_e32 v171, 1.0, v171
	v_rcp_f32_e32 v164, v164
	v_rcp_f32_e32 v165, v165
	v_rcp_f32_e32 v166, v166
	v_rcp_f32_e32 v167, v167
	v_rcp_f32_e32 v168, v168
	v_rcp_f32_e32 v169, v169
	v_rcp_f32_e32 v170, v170
	v_rcp_f32_e32 v171, v171
	v_mul_f32_e32 v80, v80, v164
	v_mul_f32_e32 v81, v81, v165
	v_mul_f32_e32 v82, v82, v166
	v_mul_f32_e32 v83, v83, v167
	v_mul_f32_e32 v76, v76, v168
	v_mul_f32_e32 v77, v77, v169
	v_mul_f32_e32 v78, v78, v170
	v_mul_f32_e32 v79, v79, v171
	v_cvt_pk_bf16_f32 v80, v80, v81
	v_cvt_pk_bf16_f32 v81, v82, v83
	v_cvt_pk_bf16_f32 v82, v76, v77
	v_cvt_pk_bf16_f32 v83, v78, v79
	global_store_dwordx4 v152, v[80:83], s[44:45]
	v_mul_f32_e32 v164, 0x3d372713, v72
	v_mul_f32_e32 v165, 0x3d372713, v73
	v_mul_f32_e32 v166, 0x3d372713, v74
	v_mul_f32_e32 v167, 0x3d372713, v75
	v_mul_f32_e32 v168, 0x3d372713, v68
	v_mul_f32_e32 v169, 0x3d372713, v69
	v_mul_f32_e32 v170, 0x3d372713, v70
	v_mul_f32_e32 v171, 0x3d372713, v71
	v_mul_f32_e32 v164, v72, v164
	v_mul_f32_e32 v165, v73, v165
	v_mul_f32_e32 v166, v74, v166
	v_mul_f32_e32 v167, v75, v167
	v_mul_f32_e32 v168, v68, v168
	v_mul_f32_e32 v169, v69, v169
	v_mul_f32_e32 v170, v70, v170
	v_mul_f32_e32 v171, v71, v171
	v_fma_f32 v164, v72, v164, v72
	v_fma_f32 v165, v73, v165, v73
	v_fma_f32 v166, v74, v166, v74
	v_fma_f32 v167, v75, v167, v75
	v_fma_f32 v168, v68, v168, v68
	v_fma_f32 v169, v69, v169, v69
	v_fma_f32 v170, v70, v170, v70
	v_fma_f32 v171, v71, v171, v71
	v_mul_f32_e32 v164, 0x3fcc422a, v164
	v_mul_f32_e32 v165, 0x3fcc422a, v165
	v_mul_f32_e32 v166, 0x3fcc422a, v166
	v_mul_f32_e32 v167, 0x3fcc422a, v167
	v_mul_f32_e32 v168, 0x3fcc422a, v168
	v_mul_f32_e32 v169, 0x3fcc422a, v169
	v_mul_f32_e32 v170, 0x3fcc422a, v170
	v_mul_f32_e32 v171, 0x3fcc422a, v171
	v_mul_f32_e32 v164, 0xbfb8aa3b, v164
	v_mul_f32_e32 v165, 0xbfb8aa3b, v165
	v_mul_f32_e32 v166, 0xbfb8aa3b, v166
	v_mul_f32_e32 v167, 0xbfb8aa3b, v167
	v_mul_f32_e32 v168, 0xbfb8aa3b, v168
	v_mul_f32_e32 v169, 0xbfb8aa3b, v169
	v_mul_f32_e32 v170, 0xbfb8aa3b, v170
	v_mul_f32_e32 v171, 0xbfb8aa3b, v171
	v_exp_f32_e32 v164, v164
	v_exp_f32_e32 v165, v165
	v_exp_f32_e32 v166, v166
	v_exp_f32_e32 v167, v167
	v_exp_f32_e32 v168, v168
	v_exp_f32_e32 v169, v169
	v_exp_f32_e32 v170, v170
	v_exp_f32_e32 v171, v171
	v_add_f32_e32 v164, 1.0, v164
	v_add_f32_e32 v165, 1.0, v165
	v_add_f32_e32 v166, 1.0, v166
	v_add_f32_e32 v167, 1.0, v167
	v_add_f32_e32 v168, 1.0, v168
	v_add_f32_e32 v169, 1.0, v169
	v_add_f32_e32 v170, 1.0, v170
	v_add_f32_e32 v171, 1.0, v171
	v_rcp_f32_e32 v164, v164
	v_rcp_f32_e32 v165, v165
	v_rcp_f32_e32 v166, v166
	v_rcp_f32_e32 v167, v167
	v_rcp_f32_e32 v168, v168
	v_rcp_f32_e32 v169, v169
	v_rcp_f32_e32 v170, v170
	v_rcp_f32_e32 v171, v171
	v_mul_f32_e32 v72, v72, v164
	v_mul_f32_e32 v73, v73, v165
	v_mul_f32_e32 v74, v74, v166
	v_mul_f32_e32 v75, v75, v167
	v_mul_f32_e32 v68, v68, v168
	v_mul_f32_e32 v69, v69, v169
	v_mul_f32_e32 v70, v70, v170
	v_mul_f32_e32 v71, v71, v171
	v_cvt_pk_bf16_f32 v72, v72, v73
	v_cvt_pk_bf16_f32 v73, v74, v75
	v_cvt_pk_bf16_f32 v74, v68, v69
	v_cvt_pk_bf16_f32 v75, v70, v71
	global_store_dwordx4 v152, v[72:75], s[44:45] offset:256
	v_add_u32_e32 v152, 0xbe000, v152
	v_mul_f32_e32 v164, 0x3d372713, v64
	v_mul_f32_e32 v165, 0x3d372713, v65
	v_mul_f32_e32 v166, 0x3d372713, v66
	v_mul_f32_e32 v167, 0x3d372713, v67
	v_mul_f32_e32 v168, 0x3d372713, v60
	v_mul_f32_e32 v169, 0x3d372713, v61
	v_mul_f32_e32 v170, 0x3d372713, v62
	v_mul_f32_e32 v171, 0x3d372713, v63
	v_mul_f32_e32 v164, v64, v164
	v_mul_f32_e32 v165, v65, v165
	v_mul_f32_e32 v166, v66, v166
	v_mul_f32_e32 v167, v67, v167
	v_mul_f32_e32 v168, v60, v168
	v_mul_f32_e32 v169, v61, v169
	v_mul_f32_e32 v170, v62, v170
	v_mul_f32_e32 v171, v63, v171
	v_fma_f32 v164, v64, v164, v64
	v_fma_f32 v165, v65, v165, v65
	v_fma_f32 v166, v66, v166, v66
	v_fma_f32 v167, v67, v167, v67
	v_fma_f32 v168, v60, v168, v60
	v_fma_f32 v169, v61, v169, v61
	v_fma_f32 v170, v62, v170, v62
	v_fma_f32 v171, v63, v171, v63
	v_mul_f32_e32 v164, 0x3fcc422a, v164
	v_mul_f32_e32 v165, 0x3fcc422a, v165
	v_mul_f32_e32 v166, 0x3fcc422a, v166
	v_mul_f32_e32 v167, 0x3fcc422a, v167
	v_mul_f32_e32 v168, 0x3fcc422a, v168
	v_mul_f32_e32 v169, 0x3fcc422a, v169
	v_mul_f32_e32 v170, 0x3fcc422a, v170
	v_mul_f32_e32 v171, 0x3fcc422a, v171
	v_mul_f32_e32 v164, 0xbfb8aa3b, v164
	v_mul_f32_e32 v165, 0xbfb8aa3b, v165
	v_mul_f32_e32 v166, 0xbfb8aa3b, v166
	v_mul_f32_e32 v167, 0xbfb8aa3b, v167
	v_mul_f32_e32 v168, 0xbfb8aa3b, v168
	v_mul_f32_e32 v169, 0xbfb8aa3b, v169
	v_mul_f32_e32 v170, 0xbfb8aa3b, v170
	v_mul_f32_e32 v171, 0xbfb8aa3b, v171
	v_exp_f32_e32 v164, v164
	v_exp_f32_e32 v165, v165
	v_exp_f32_e32 v166, v166
	v_exp_f32_e32 v167, v167
	v_exp_f32_e32 v168, v168
	v_exp_f32_e32 v169, v169
	v_exp_f32_e32 v170, v170
	v_exp_f32_e32 v171, v171
	v_add_f32_e32 v164, 1.0, v164
	v_add_f32_e32 v165, 1.0, v165
	v_add_f32_e32 v166, 1.0, v166
	v_add_f32_e32 v167, 1.0, v167
	v_add_f32_e32 v168, 1.0, v168
	v_add_f32_e32 v169, 1.0, v169
	v_add_f32_e32 v170, 1.0, v170
	v_add_f32_e32 v171, 1.0, v171
	v_rcp_f32_e32 v164, v164
	v_rcp_f32_e32 v165, v165
	v_rcp_f32_e32 v166, v166
	v_rcp_f32_e32 v167, v167
	v_rcp_f32_e32 v168, v168
	v_rcp_f32_e32 v169, v169
	v_rcp_f32_e32 v170, v170
	v_rcp_f32_e32 v171, v171
	v_mul_f32_e32 v64, v64, v164
	v_mul_f32_e32 v65, v65, v165
	v_mul_f32_e32 v66, v66, v166
	v_mul_f32_e32 v67, v67, v167
	v_mul_f32_e32 v60, v60, v168
	v_mul_f32_e32 v61, v61, v169
	v_mul_f32_e32 v62, v62, v170
	v_mul_f32_e32 v63, v63, v171
	v_cvt_pk_bf16_f32 v64, v64, v65
	v_cvt_pk_bf16_f32 v65, v66, v67
	v_cvt_pk_bf16_f32 v66, v60, v61
	v_cvt_pk_bf16_f32 v67, v62, v63
	global_store_dwordx4 v152, v[64:67], s[44:45]
	v_mul_f32_e32 v164, 0x3d372713, v56
	v_mul_f32_e32 v165, 0x3d372713, v57
	v_mul_f32_e32 v166, 0x3d372713, v58
	v_mul_f32_e32 v167, 0x3d372713, v59
	v_mul_f32_e32 v168, 0x3d372713, v52
	v_mul_f32_e32 v169, 0x3d372713, v53
	v_mul_f32_e32 v170, 0x3d372713, v54
	v_mul_f32_e32 v171, 0x3d372713, v55
	v_mul_f32_e32 v164, v56, v164
	v_mul_f32_e32 v165, v57, v165
	v_mul_f32_e32 v166, v58, v166
	v_mul_f32_e32 v167, v59, v167
	v_mul_f32_e32 v168, v52, v168
	v_mul_f32_e32 v169, v53, v169
	v_mul_f32_e32 v170, v54, v170
	v_mul_f32_e32 v171, v55, v171
	v_fma_f32 v164, v56, v164, v56
	v_fma_f32 v165, v57, v165, v57
	v_fma_f32 v166, v58, v166, v58
	v_fma_f32 v167, v59, v167, v59
	v_fma_f32 v168, v52, v168, v52
	v_fma_f32 v169, v53, v169, v53
	v_fma_f32 v170, v54, v170, v54
	v_fma_f32 v171, v55, v171, v55
	v_mul_f32_e32 v164, 0x3fcc422a, v164
	v_mul_f32_e32 v165, 0x3fcc422a, v165
	v_mul_f32_e32 v166, 0x3fcc422a, v166
	v_mul_f32_e32 v167, 0x3fcc422a, v167
	v_mul_f32_e32 v168, 0x3fcc422a, v168
	v_mul_f32_e32 v169, 0x3fcc422a, v169
	v_mul_f32_e32 v170, 0x3fcc422a, v170
	v_mul_f32_e32 v171, 0x3fcc422a, v171
	v_mul_f32_e32 v164, 0xbfb8aa3b, v164
	v_mul_f32_e32 v165, 0xbfb8aa3b, v165
	v_mul_f32_e32 v166, 0xbfb8aa3b, v166
	v_mul_f32_e32 v167, 0xbfb8aa3b, v167
	v_mul_f32_e32 v168, 0xbfb8aa3b, v168
	v_mul_f32_e32 v169, 0xbfb8aa3b, v169
	v_mul_f32_e32 v170, 0xbfb8aa3b, v170
	v_mul_f32_e32 v171, 0xbfb8aa3b, v171
	v_exp_f32_e32 v164, v164
	v_exp_f32_e32 v165, v165
	v_exp_f32_e32 v166, v166
	v_exp_f32_e32 v167, v167
	v_exp_f32_e32 v168, v168
	v_exp_f32_e32 v169, v169
	v_exp_f32_e32 v170, v170
	v_exp_f32_e32 v171, v171
	v_add_f32_e32 v164, 1.0, v164
	v_add_f32_e32 v165, 1.0, v165
	v_add_f32_e32 v166, 1.0, v166
	v_add_f32_e32 v167, 1.0, v167
	v_add_f32_e32 v168, 1.0, v168
	v_add_f32_e32 v169, 1.0, v169
	v_add_f32_e32 v170, 1.0, v170
	v_add_f32_e32 v171, 1.0, v171
	v_rcp_f32_e32 v164, v164
	v_rcp_f32_e32 v165, v165
	v_rcp_f32_e32 v166, v166
	v_rcp_f32_e32 v167, v167
	v_rcp_f32_e32 v168, v168
	v_rcp_f32_e32 v169, v169
	v_rcp_f32_e32 v170, v170
	v_rcp_f32_e32 v171, v171
	v_mul_f32_e32 v56, v56, v164
	v_mul_f32_e32 v57, v57, v165
	v_mul_f32_e32 v58, v58, v166
	v_mul_f32_e32 v59, v59, v167
	v_mul_f32_e32 v52, v52, v168
	v_mul_f32_e32 v53, v53, v169
	v_mul_f32_e32 v54, v54, v170
	v_mul_f32_e32 v55, v55, v171
	v_cvt_pk_bf16_f32 v56, v56, v57
	v_cvt_pk_bf16_f32 v57, v58, v59
	v_cvt_pk_bf16_f32 v58, v52, v53
	v_cvt_pk_bf16_f32 v59, v54, v55
	global_store_dwordx4 v152, v[56:59], s[44:45] offset:256
	v_add_u32_e32 v152, 0x26000, v152
	v_mul_f32_e32 v164, 0x3d372713, v48
	v_mul_f32_e32 v165, 0x3d372713, v49
	v_mul_f32_e32 v166, 0x3d372713, v50
	v_mul_f32_e32 v167, 0x3d372713, v51
	v_mul_f32_e32 v168, 0x3d372713, v44
	v_mul_f32_e32 v169, 0x3d372713, v45
	v_mul_f32_e32 v170, 0x3d372713, v46
	v_mul_f32_e32 v171, 0x3d372713, v47
	v_mul_f32_e32 v164, v48, v164
	v_mul_f32_e32 v165, v49, v165
	v_mul_f32_e32 v166, v50, v166
	v_mul_f32_e32 v167, v51, v167
	v_mul_f32_e32 v168, v44, v168
	v_mul_f32_e32 v169, v45, v169
	v_mul_f32_e32 v170, v46, v170
	v_mul_f32_e32 v171, v47, v171
	v_fma_f32 v164, v48, v164, v48
	v_fma_f32 v165, v49, v165, v49
	v_fma_f32 v166, v50, v166, v50
	v_fma_f32 v167, v51, v167, v51
	v_fma_f32 v168, v44, v168, v44
	v_fma_f32 v169, v45, v169, v45
	v_fma_f32 v170, v46, v170, v46
	v_fma_f32 v171, v47, v171, v47
	v_mul_f32_e32 v164, 0x3fcc422a, v164
	v_mul_f32_e32 v165, 0x3fcc422a, v165
	v_mul_f32_e32 v166, 0x3fcc422a, v166
	v_mul_f32_e32 v167, 0x3fcc422a, v167
	v_mul_f32_e32 v168, 0x3fcc422a, v168
	v_mul_f32_e32 v169, 0x3fcc422a, v169
	v_mul_f32_e32 v170, 0x3fcc422a, v170
	v_mul_f32_e32 v171, 0x3fcc422a, v171
	v_mul_f32_e32 v164, 0xbfb8aa3b, v164
	v_mul_f32_e32 v165, 0xbfb8aa3b, v165
	v_mul_f32_e32 v166, 0xbfb8aa3b, v166
	v_mul_f32_e32 v167, 0xbfb8aa3b, v167
	v_mul_f32_e32 v168, 0xbfb8aa3b, v168
	v_mul_f32_e32 v169, 0xbfb8aa3b, v169
	v_mul_f32_e32 v170, 0xbfb8aa3b, v170
	v_mul_f32_e32 v171, 0xbfb8aa3b, v171
	v_exp_f32_e32 v164, v164
	v_exp_f32_e32 v165, v165
	v_exp_f32_e32 v166, v166
	v_exp_f32_e32 v167, v167
	v_exp_f32_e32 v168, v168
	v_exp_f32_e32 v169, v169
	v_exp_f32_e32 v170, v170
	v_exp_f32_e32 v171, v171
	v_add_f32_e32 v164, 1.0, v164
	v_add_f32_e32 v165, 1.0, v165
	v_add_f32_e32 v166, 1.0, v166
	v_add_f32_e32 v167, 1.0, v167
	v_add_f32_e32 v168, 1.0, v168
	v_add_f32_e32 v169, 1.0, v169
	v_add_f32_e32 v170, 1.0, v170
	v_add_f32_e32 v171, 1.0, v171
	v_rcp_f32_e32 v164, v164
	v_rcp_f32_e32 v165, v165
	v_rcp_f32_e32 v166, v166
	v_rcp_f32_e32 v167, v167
	v_rcp_f32_e32 v168, v168
	v_rcp_f32_e32 v169, v169
	v_rcp_f32_e32 v170, v170
	v_rcp_f32_e32 v171, v171
	v_mul_f32_e32 v48, v48, v164
	v_mul_f32_e32 v49, v49, v165
	v_mul_f32_e32 v50, v50, v166
	v_mul_f32_e32 v51, v51, v167
	v_mul_f32_e32 v44, v44, v168
	v_mul_f32_e32 v45, v45, v169
	v_mul_f32_e32 v46, v46, v170
	v_mul_f32_e32 v47, v47, v171
	v_cvt_pk_bf16_f32 v48, v48, v49
	v_cvt_pk_bf16_f32 v49, v50, v51
	v_cvt_pk_bf16_f32 v50, v44, v45
	v_cvt_pk_bf16_f32 v51, v46, v47
	global_store_dwordx4 v152, v[48:51], s[44:45]
	v_mul_f32_e32 v164, 0x3d372713, v40
	v_mul_f32_e32 v165, 0x3d372713, v41
	v_mul_f32_e32 v166, 0x3d372713, v42
	v_mul_f32_e32 v167, 0x3d372713, v43
	v_mul_f32_e32 v168, 0x3d372713, v36
	v_mul_f32_e32 v169, 0x3d372713, v37
	v_mul_f32_e32 v170, 0x3d372713, v38
	v_mul_f32_e32 v171, 0x3d372713, v39
	v_mul_f32_e32 v164, v40, v164
	v_mul_f32_e32 v165, v41, v165
	v_mul_f32_e32 v166, v42, v166
	v_mul_f32_e32 v167, v43, v167
	v_mul_f32_e32 v168, v36, v168
	v_mul_f32_e32 v169, v37, v169
	v_mul_f32_e32 v170, v38, v170
	v_mul_f32_e32 v171, v39, v171
	v_fma_f32 v164, v40, v164, v40
	v_fma_f32 v165, v41, v165, v41
	v_fma_f32 v166, v42, v166, v42
	v_fma_f32 v167, v43, v167, v43
	v_fma_f32 v168, v36, v168, v36
	v_fma_f32 v169, v37, v169, v37
	v_fma_f32 v170, v38, v170, v38
	v_fma_f32 v171, v39, v171, v39
	v_mul_f32_e32 v164, 0x3fcc422a, v164
	v_mul_f32_e32 v165, 0x3fcc422a, v165
	v_mul_f32_e32 v166, 0x3fcc422a, v166
	v_mul_f32_e32 v167, 0x3fcc422a, v167
	v_mul_f32_e32 v168, 0x3fcc422a, v168
	v_mul_f32_e32 v169, 0x3fcc422a, v169
	v_mul_f32_e32 v170, 0x3fcc422a, v170
	v_mul_f32_e32 v171, 0x3fcc422a, v171
	v_mul_f32_e32 v164, 0xbfb8aa3b, v164
	v_mul_f32_e32 v165, 0xbfb8aa3b, v165
	v_mul_f32_e32 v166, 0xbfb8aa3b, v166
	v_mul_f32_e32 v167, 0xbfb8aa3b, v167
	v_mul_f32_e32 v168, 0xbfb8aa3b, v168
	v_mul_f32_e32 v169, 0xbfb8aa3b, v169
	v_mul_f32_e32 v170, 0xbfb8aa3b, v170
	v_mul_f32_e32 v171, 0xbfb8aa3b, v171
	v_exp_f32_e32 v164, v164
	v_exp_f32_e32 v165, v165
	v_exp_f32_e32 v166, v166
	v_exp_f32_e32 v167, v167
	v_exp_f32_e32 v168, v168
	v_exp_f32_e32 v169, v169
	v_exp_f32_e32 v170, v170
	v_exp_f32_e32 v171, v171
	v_add_f32_e32 v164, 1.0, v164
	v_add_f32_e32 v165, 1.0, v165
	v_add_f32_e32 v166, 1.0, v166
	v_add_f32_e32 v167, 1.0, v167
	v_add_f32_e32 v168, 1.0, v168
	v_add_f32_e32 v169, 1.0, v169
	v_add_f32_e32 v170, 1.0, v170
	v_add_f32_e32 v171, 1.0, v171
	v_rcp_f32_e32 v164, v164
	v_rcp_f32_e32 v165, v165
	v_rcp_f32_e32 v166, v166
	v_rcp_f32_e32 v167, v167
	v_rcp_f32_e32 v168, v168
	v_rcp_f32_e32 v169, v169
	v_rcp_f32_e32 v170, v170
	v_rcp_f32_e32 v171, v171
	v_mul_f32_e32 v40, v40, v164
	v_mul_f32_e32 v41, v41, v165
	v_mul_f32_e32 v42, v42, v166
	v_mul_f32_e32 v43, v43, v167
	v_mul_f32_e32 v36, v36, v168
	v_mul_f32_e32 v37, v37, v169
	v_mul_f32_e32 v38, v38, v170
	v_mul_f32_e32 v39, v39, v171
	v_cvt_pk_bf16_f32 v40, v40, v41
	v_cvt_pk_bf16_f32 v41, v42, v43
	v_cvt_pk_bf16_f32 v42, v36, v37
	v_cvt_pk_bf16_f32 v43, v38, v39
	global_store_dwordx4 v152, v[40:43], s[44:45] offset:256
	v_add_u32_e32 v152, 0x26000, v152
	v_mul_f32_e32 v164, 0x3d372713, v32
	v_mul_f32_e32 v165, 0x3d372713, v33
	v_mul_f32_e32 v166, 0x3d372713, v34
	v_mul_f32_e32 v167, 0x3d372713, v35
	v_mul_f32_e32 v168, 0x3d372713, v28
	v_mul_f32_e32 v169, 0x3d372713, v29
	v_mul_f32_e32 v170, 0x3d372713, v30
	v_mul_f32_e32 v171, 0x3d372713, v31
	v_mul_f32_e32 v164, v32, v164
	v_mul_f32_e32 v165, v33, v165
	v_mul_f32_e32 v166, v34, v166
	v_mul_f32_e32 v167, v35, v167
	v_mul_f32_e32 v168, v28, v168
	v_mul_f32_e32 v169, v29, v169
	v_mul_f32_e32 v170, v30, v170
	v_mul_f32_e32 v171, v31, v171
	v_fma_f32 v164, v32, v164, v32
	v_fma_f32 v165, v33, v165, v33
	v_fma_f32 v166, v34, v166, v34
	v_fma_f32 v167, v35, v167, v35
	v_fma_f32 v168, v28, v168, v28
	v_fma_f32 v169, v29, v169, v29
	v_fma_f32 v170, v30, v170, v30
	v_fma_f32 v171, v31, v171, v31
	v_mul_f32_e32 v164, 0x3fcc422a, v164
	v_mul_f32_e32 v165, 0x3fcc422a, v165
	v_mul_f32_e32 v166, 0x3fcc422a, v166
	v_mul_f32_e32 v167, 0x3fcc422a, v167
	v_mul_f32_e32 v168, 0x3fcc422a, v168
	v_mul_f32_e32 v169, 0x3fcc422a, v169
	v_mul_f32_e32 v170, 0x3fcc422a, v170
	v_mul_f32_e32 v171, 0x3fcc422a, v171
	v_mul_f32_e32 v164, 0xbfb8aa3b, v164
	v_mul_f32_e32 v165, 0xbfb8aa3b, v165
	v_mul_f32_e32 v166, 0xbfb8aa3b, v166
	v_mul_f32_e32 v167, 0xbfb8aa3b, v167
	v_mul_f32_e32 v168, 0xbfb8aa3b, v168
	v_mul_f32_e32 v169, 0xbfb8aa3b, v169
	v_mul_f32_e32 v170, 0xbfb8aa3b, v170
	v_mul_f32_e32 v171, 0xbfb8aa3b, v171
	v_exp_f32_e32 v164, v164
	v_exp_f32_e32 v165, v165
	v_exp_f32_e32 v166, v166
	v_exp_f32_e32 v167, v167
	v_exp_f32_e32 v168, v168
	v_exp_f32_e32 v169, v169
	v_exp_f32_e32 v170, v170
	v_exp_f32_e32 v171, v171
	v_add_f32_e32 v164, 1.0, v164
	v_add_f32_e32 v165, 1.0, v165
	v_add_f32_e32 v166, 1.0, v166
	v_add_f32_e32 v167, 1.0, v167
	v_add_f32_e32 v168, 1.0, v168
	v_add_f32_e32 v169, 1.0, v169
	v_add_f32_e32 v170, 1.0, v170
	v_add_f32_e32 v171, 1.0, v171
	v_rcp_f32_e32 v164, v164
	v_rcp_f32_e32 v165, v165
	v_rcp_f32_e32 v166, v166
	v_rcp_f32_e32 v167, v167
	v_rcp_f32_e32 v168, v168
	v_rcp_f32_e32 v169, v169
	v_rcp_f32_e32 v170, v170
	v_rcp_f32_e32 v171, v171
	v_mul_f32_e32 v32, v32, v164
	v_mul_f32_e32 v33, v33, v165
	v_mul_f32_e32 v34, v34, v166
	v_mul_f32_e32 v35, v35, v167
	v_mul_f32_e32 v28, v28, v168
	v_mul_f32_e32 v29, v29, v169
	v_mul_f32_e32 v30, v30, v170
	v_mul_f32_e32 v31, v31, v171
	v_cvt_pk_bf16_f32 v32, v32, v33
	v_cvt_pk_bf16_f32 v33, v34, v35
	v_cvt_pk_bf16_f32 v34, v28, v29
	v_cvt_pk_bf16_f32 v35, v30, v31
	global_store_dwordx4 v152, v[32:35], s[44:45]
	v_mul_f32_e32 v164, 0x3d372713, v24
	v_mul_f32_e32 v165, 0x3d372713, v25
	v_mul_f32_e32 v166, 0x3d372713, v26
	v_mul_f32_e32 v167, 0x3d372713, v27
	v_mul_f32_e32 v168, 0x3d372713, v20
	v_mul_f32_e32 v169, 0x3d372713, v21
	v_mul_f32_e32 v170, 0x3d372713, v22
	v_mul_f32_e32 v171, 0x3d372713, v23
	v_mul_f32_e32 v164, v24, v164
	v_mul_f32_e32 v165, v25, v165
	v_mul_f32_e32 v166, v26, v166
	v_mul_f32_e32 v167, v27, v167
	v_mul_f32_e32 v168, v20, v168
	v_mul_f32_e32 v169, v21, v169
	v_mul_f32_e32 v170, v22, v170
	v_mul_f32_e32 v171, v23, v171
	v_fma_f32 v164, v24, v164, v24
	v_fma_f32 v165, v25, v165, v25
	v_fma_f32 v166, v26, v166, v26
	v_fma_f32 v167, v27, v167, v27
	v_fma_f32 v168, v20, v168, v20
	v_fma_f32 v169, v21, v169, v21
	v_fma_f32 v170, v22, v170, v22
	v_fma_f32 v171, v23, v171, v23
	v_mul_f32_e32 v164, 0x3fcc422a, v164
	v_mul_f32_e32 v165, 0x3fcc422a, v165
	v_mul_f32_e32 v166, 0x3fcc422a, v166
	v_mul_f32_e32 v167, 0x3fcc422a, v167
	v_mul_f32_e32 v168, 0x3fcc422a, v168
	v_mul_f32_e32 v169, 0x3fcc422a, v169
	v_mul_f32_e32 v170, 0x3fcc422a, v170
	v_mul_f32_e32 v171, 0x3fcc422a, v171
	v_mul_f32_e32 v164, 0xbfb8aa3b, v164
	v_mul_f32_e32 v165, 0xbfb8aa3b, v165
	v_mul_f32_e32 v166, 0xbfb8aa3b, v166
	v_mul_f32_e32 v167, 0xbfb8aa3b, v167
	v_mul_f32_e32 v168, 0xbfb8aa3b, v168
	v_mul_f32_e32 v169, 0xbfb8aa3b, v169
	v_mul_f32_e32 v170, 0xbfb8aa3b, v170
	v_mul_f32_e32 v171, 0xbfb8aa3b, v171
	v_exp_f32_e32 v164, v164
	v_exp_f32_e32 v165, v165
	v_exp_f32_e32 v166, v166
	v_exp_f32_e32 v167, v167
	v_exp_f32_e32 v168, v168
	v_exp_f32_e32 v169, v169
	v_exp_f32_e32 v170, v170
	v_exp_f32_e32 v171, v171
	v_add_f32_e32 v164, 1.0, v164
	v_add_f32_e32 v165, 1.0, v165
	v_add_f32_e32 v166, 1.0, v166
	v_add_f32_e32 v167, 1.0, v167
	v_add_f32_e32 v168, 1.0, v168
	v_add_f32_e32 v169, 1.0, v169
	v_add_f32_e32 v170, 1.0, v170
	v_add_f32_e32 v171, 1.0, v171
	v_rcp_f32_e32 v164, v164
	v_rcp_f32_e32 v165, v165
	v_rcp_f32_e32 v166, v166
	v_rcp_f32_e32 v167, v167
	v_rcp_f32_e32 v168, v168
	v_rcp_f32_e32 v169, v169
	v_rcp_f32_e32 v170, v170
	v_rcp_f32_e32 v171, v171
	v_mul_f32_e32 v24, v24, v164
	v_mul_f32_e32 v25, v25, v165
	v_mul_f32_e32 v26, v26, v166
	v_mul_f32_e32 v27, v27, v167
	v_mul_f32_e32 v20, v20, v168
	v_mul_f32_e32 v21, v21, v169
	v_mul_f32_e32 v22, v22, v170
	v_mul_f32_e32 v23, v23, v171
	v_cvt_pk_bf16_f32 v24, v24, v25
	v_cvt_pk_bf16_f32 v25, v26, v27
	v_cvt_pk_bf16_f32 v26, v20, v21
	v_cvt_pk_bf16_f32 v27, v22, v23
	global_store_dwordx4 v152, v[24:27], s[44:45] offset:256
	v_add_u32_e32 v152, 0x26000, v152
	v_mul_f32_e32 v164, 0x3d372713, v16
	v_mul_f32_e32 v165, 0x3d372713, v17
	v_mul_f32_e32 v166, 0x3d372713, v18
	v_mul_f32_e32 v167, 0x3d372713, v19
	v_mul_f32_e32 v168, 0x3d372713, v12
	v_mul_f32_e32 v169, 0x3d372713, v13
	v_mul_f32_e32 v170, 0x3d372713, v14
	v_mul_f32_e32 v171, 0x3d372713, v15
	v_mul_f32_e32 v164, v16, v164
	v_mul_f32_e32 v165, v17, v165
	v_mul_f32_e32 v166, v18, v166
	v_mul_f32_e32 v167, v19, v167
	v_mul_f32_e32 v168, v12, v168
	v_mul_f32_e32 v169, v13, v169
	v_mul_f32_e32 v170, v14, v170
	v_mul_f32_e32 v171, v15, v171
	v_fma_f32 v164, v16, v164, v16
	v_fma_f32 v165, v17, v165, v17
	v_fma_f32 v166, v18, v166, v18
	v_fma_f32 v167, v19, v167, v19
	v_fma_f32 v168, v12, v168, v12
	v_fma_f32 v169, v13, v169, v13
	v_fma_f32 v170, v14, v170, v14
	v_fma_f32 v171, v15, v171, v15
	v_mul_f32_e32 v164, 0x3fcc422a, v164
	v_mul_f32_e32 v165, 0x3fcc422a, v165
	v_mul_f32_e32 v166, 0x3fcc422a, v166
	v_mul_f32_e32 v167, 0x3fcc422a, v167
	v_mul_f32_e32 v168, 0x3fcc422a, v168
	v_mul_f32_e32 v169, 0x3fcc422a, v169
	v_mul_f32_e32 v170, 0x3fcc422a, v170
	v_mul_f32_e32 v171, 0x3fcc422a, v171
	v_mul_f32_e32 v164, 0xbfb8aa3b, v164
	v_mul_f32_e32 v165, 0xbfb8aa3b, v165
	v_mul_f32_e32 v166, 0xbfb8aa3b, v166
	v_mul_f32_e32 v167, 0xbfb8aa3b, v167
	v_mul_f32_e32 v168, 0xbfb8aa3b, v168
	v_mul_f32_e32 v169, 0xbfb8aa3b, v169
	v_mul_f32_e32 v170, 0xbfb8aa3b, v170
	v_mul_f32_e32 v171, 0xbfb8aa3b, v171
	v_exp_f32_e32 v164, v164
	v_exp_f32_e32 v165, v165
	v_exp_f32_e32 v166, v166
	v_exp_f32_e32 v167, v167
	v_exp_f32_e32 v168, v168
	v_exp_f32_e32 v169, v169
	v_exp_f32_e32 v170, v170
	v_exp_f32_e32 v171, v171
	v_add_f32_e32 v164, 1.0, v164
	v_add_f32_e32 v165, 1.0, v165
	v_add_f32_e32 v166, 1.0, v166
	v_add_f32_e32 v167, 1.0, v167
	v_add_f32_e32 v168, 1.0, v168
	v_add_f32_e32 v169, 1.0, v169
	v_add_f32_e32 v170, 1.0, v170
	v_add_f32_e32 v171, 1.0, v171
	v_rcp_f32_e32 v164, v164
	v_rcp_f32_e32 v165, v165
	v_rcp_f32_e32 v166, v166
	v_rcp_f32_e32 v167, v167
	v_rcp_f32_e32 v168, v168
	v_rcp_f32_e32 v169, v169
	v_rcp_f32_e32 v170, v170
	v_rcp_f32_e32 v171, v171
	v_mul_f32_e32 v16, v16, v164
	v_mul_f32_e32 v17, v17, v165
	v_mul_f32_e32 v18, v18, v166
	v_mul_f32_e32 v19, v19, v167
	v_mul_f32_e32 v12, v12, v168
	v_mul_f32_e32 v13, v13, v169
	v_mul_f32_e32 v14, v14, v170
	v_mul_f32_e32 v15, v15, v171
	v_cvt_pk_bf16_f32 v16, v16, v17
	v_cvt_pk_bf16_f32 v17, v18, v19
	v_cvt_pk_bf16_f32 v18, v12, v13
	v_cvt_pk_bf16_f32 v19, v14, v15
	global_store_dwordx4 v152, v[16:19], s[44:45]
	v_mul_f32_e32 v164, 0x3d372713, v8
	v_mul_f32_e32 v165, 0x3d372713, v9
	v_mul_f32_e32 v166, 0x3d372713, v10
	v_mul_f32_e32 v167, 0x3d372713, v11
	v_mul_f32_e32 v168, 0x3d372713, v4
	v_mul_f32_e32 v169, 0x3d372713, v5
	v_mul_f32_e32 v170, 0x3d372713, v6
	v_mul_f32_e32 v171, 0x3d372713, v7
	v_mul_f32_e32 v164, v8, v164
	v_mul_f32_e32 v165, v9, v165
	v_mul_f32_e32 v166, v10, v166
	v_mul_f32_e32 v167, v11, v167
	v_mul_f32_e32 v168, v4, v168
	v_mul_f32_e32 v169, v5, v169
	v_mul_f32_e32 v170, v6, v170
	v_mul_f32_e32 v171, v7, v171
	v_fma_f32 v164, v8, v164, v8
	v_fma_f32 v165, v9, v165, v9
	v_fma_f32 v166, v10, v166, v10
	v_fma_f32 v167, v11, v167, v11
	v_fma_f32 v168, v4, v168, v4
	v_fma_f32 v169, v5, v169, v5
	v_fma_f32 v170, v6, v170, v6
	v_fma_f32 v171, v7, v171, v7
	v_mul_f32_e32 v164, 0x3fcc422a, v164
	v_mul_f32_e32 v165, 0x3fcc422a, v165
	v_mul_f32_e32 v166, 0x3fcc422a, v166
	v_mul_f32_e32 v167, 0x3fcc422a, v167
	v_mul_f32_e32 v168, 0x3fcc422a, v168
	v_mul_f32_e32 v169, 0x3fcc422a, v169
	v_mul_f32_e32 v170, 0x3fcc422a, v170
	v_mul_f32_e32 v171, 0x3fcc422a, v171
	v_mul_f32_e32 v164, 0xbfb8aa3b, v164
	v_mul_f32_e32 v165, 0xbfb8aa3b, v165
	v_mul_f32_e32 v166, 0xbfb8aa3b, v166
	v_mul_f32_e32 v167, 0xbfb8aa3b, v167
	v_mul_f32_e32 v168, 0xbfb8aa3b, v168
	v_mul_f32_e32 v169, 0xbfb8aa3b, v169
	v_mul_f32_e32 v170, 0xbfb8aa3b, v170
	v_mul_f32_e32 v171, 0xbfb8aa3b, v171
	v_exp_f32_e32 v164, v164
	v_exp_f32_e32 v165, v165
	v_exp_f32_e32 v166, v166
	v_exp_f32_e32 v167, v167
	v_exp_f32_e32 v168, v168
	v_exp_f32_e32 v169, v169
	v_exp_f32_e32 v170, v170
	v_exp_f32_e32 v171, v171
	v_add_f32_e32 v164, 1.0, v164
	v_add_f32_e32 v165, 1.0, v165
	v_add_f32_e32 v166, 1.0, v166
	v_add_f32_e32 v167, 1.0, v167
	v_add_f32_e32 v168, 1.0, v168
	v_add_f32_e32 v169, 1.0, v169
	v_add_f32_e32 v170, 1.0, v170
	v_add_f32_e32 v171, 1.0, v171
	v_rcp_f32_e32 v164, v164
	v_rcp_f32_e32 v165, v165
	v_rcp_f32_e32 v166, v166
	v_rcp_f32_e32 v167, v167
	v_rcp_f32_e32 v168, v168
	v_rcp_f32_e32 v169, v169
	v_rcp_f32_e32 v170, v170
	v_rcp_f32_e32 v171, v171
	v_mul_f32_e32 v8, v8, v164
	v_mul_f32_e32 v9, v9, v165
	v_mul_f32_e32 v10, v10, v166
	v_mul_f32_e32 v11, v11, v167
	v_mul_f32_e32 v4, v4, v168
	v_mul_f32_e32 v5, v5, v169
	v_mul_f32_e32 v6, v6, v170
	v_mul_f32_e32 v7, v7, v171
	v_cvt_pk_bf16_f32 v8, v8, v9
	v_cvt_pk_bf16_f32 v9, v10, v11
	v_cvt_pk_bf16_f32 v10, v4, v5
	v_cvt_pk_bf16_f32 v11, v6, v7
	global_store_dwordx4 v152, v[8:11], s[44:45] offset:256
	s_branch .LBB0_590
.Lepi_sig:
	v_mul_lo_u32 v152, v195, s30
	v_add_u32_e32 v153, s9, v191
	v_lshl_add_u32 v152, v153, 1, v152
	v_mul_f32_e32 v128, 0xbfb8aa3b, v128
	v_mul_f32_e32 v129, 0xbfb8aa3b, v129
	v_mul_f32_e32 v130, 0xbfb8aa3b, v130
	v_mul_f32_e32 v131, 0xbfb8aa3b, v131
	v_mul_f32_e32 v124, 0xbfb8aa3b, v124
	v_mul_f32_e32 v125, 0xbfb8aa3b, v125
	v_mul_f32_e32 v126, 0xbfb8aa3b, v126
	v_mul_f32_e32 v127, 0xbfb8aa3b, v127
	v_exp_f32_e32 v128, v128
	v_exp_f32_e32 v129, v129
	v_exp_f32_e32 v130, v130
	v_exp_f32_e32 v131, v131
	v_exp_f32_e32 v124, v124
	v_exp_f32_e32 v125, v125
	v_exp_f32_e32 v126, v126
	v_exp_f32_e32 v127, v127
	v_add_f32_e32 v128, 1.0, v128
	v_add_f32_e32 v129, 1.0, v129
	v_add_f32_e32 v130, 1.0, v130
	v_add_f32_e32 v131, 1.0, v131
	v_add_f32_e32 v124, 1.0, v124
	v_add_f32_e32 v125, 1.0, v125
	v_add_f32_e32 v126, 1.0, v126
	v_add_f32_e32 v127, 1.0, v127
	v_rcp_f32_e32 v128, v128
	v_rcp_f32_e32 v129, v129
	v_rcp_f32_e32 v130, v130
	v_rcp_f32_e32 v131, v131
	v_rcp_f32_e32 v124, v124
	v_rcp_f32_e32 v125, v125
	v_rcp_f32_e32 v126, v126
	v_rcp_f32_e32 v127, v127
	v_cvt_pk_bf16_f32 v128, v128, v129
	v_cvt_pk_bf16_f32 v129, v130, v131
	v_cvt_pk_bf16_f32 v130, v124, v125
	v_cvt_pk_bf16_f32 v131, v126, v127
	global_store_dwordx4 v152, v[128:131], s[44:45]
	v_mul_f32_e32 v120, 0xbfb8aa3b, v120
	v_mul_f32_e32 v121, 0xbfb8aa3b, v121
	v_mul_f32_e32 v122, 0xbfb8aa3b, v122
	v_mul_f32_e32 v123, 0xbfb8aa3b, v123
	v_mul_f32_e32 v116, 0xbfb8aa3b, v116
	v_mul_f32_e32 v117, 0xbfb8aa3b, v117
	v_mul_f32_e32 v118, 0xbfb8aa3b, v118
	v_mul_f32_e32 v119, 0xbfb8aa3b, v119
	v_exp_f32_e32 v120, v120
	v_exp_f32_e32 v121, v121
	v_exp_f32_e32 v122, v122
	v_exp_f32_e32 v123, v123
	v_exp_f32_e32 v116, v116
	v_exp_f32_e32 v117, v117
	v_exp_f32_e32 v118, v118
	v_exp_f32_e32 v119, v119
	v_add_f32_e32 v120, 1.0, v120
	v_add_f32_e32 v121, 1.0, v121
	v_add_f32_e32 v122, 1.0, v122
	v_add_f32_e32 v123, 1.0, v123
	v_add_f32_e32 v116, 1.0, v116
	v_add_f32_e32 v117, 1.0, v117
	v_add_f32_e32 v118, 1.0, v118
	v_add_f32_e32 v119, 1.0, v119
	v_rcp_f32_e32 v120, v120
	v_rcp_f32_e32 v121, v121
	v_rcp_f32_e32 v122, v122
	v_rcp_f32_e32 v123, v123
	v_rcp_f32_e32 v116, v116
	v_rcp_f32_e32 v117, v117
	v_rcp_f32_e32 v118, v118
	v_rcp_f32_e32 v119, v119
	v_cvt_pk_bf16_f32 v120, v120, v121
	v_cvt_pk_bf16_f32 v121, v122, v123
	v_cvt_pk_bf16_f32 v122, v116, v117
	v_cvt_pk_bf16_f32 v123, v118, v119
	global_store_dwordx4 v152, v[120:123], s[44:45] offset:256
	v_add_u32_e32 v152, 0x26000, v152
	v_mul_f32_e32 v112, 0xbfb8aa3b, v112
	v_mul_f32_e32 v113, 0xbfb8aa3b, v113
	v_mul_f32_e32 v114, 0xbfb8aa3b, v114
	v_mul_f32_e32 v115, 0xbfb8aa3b, v115
	v_mul_f32_e32 v108, 0xbfb8aa3b, v108
	v_mul_f32_e32 v109, 0xbfb8aa3b, v109
	v_mul_f32_e32 v110, 0xbfb8aa3b, v110
	v_mul_f32_e32 v111, 0xbfb8aa3b, v111
	v_exp_f32_e32 v112, v112
	v_exp_f32_e32 v113, v113
	v_exp_f32_e32 v114, v114
	v_exp_f32_e32 v115, v115
	v_exp_f32_e32 v108, v108
	v_exp_f32_e32 v109, v109
	v_exp_f32_e32 v110, v110
	v_exp_f32_e32 v111, v111
	v_add_f32_e32 v112, 1.0, v112
	v_add_f32_e32 v113, 1.0, v113
	v_add_f32_e32 v114, 1.0, v114
	v_add_f32_e32 v115, 1.0, v115
	v_add_f32_e32 v108, 1.0, v108
	v_add_f32_e32 v109, 1.0, v109
	v_add_f32_e32 v110, 1.0, v110
	v_add_f32_e32 v111, 1.0, v111
	v_rcp_f32_e32 v112, v112
	v_rcp_f32_e32 v113, v113
	v_rcp_f32_e32 v114, v114
	v_rcp_f32_e32 v115, v115
	v_rcp_f32_e32 v108, v108
	v_rcp_f32_e32 v109, v109
	v_rcp_f32_e32 v110, v110
	v_rcp_f32_e32 v111, v111
	v_cvt_pk_bf16_f32 v112, v112, v113
	v_cvt_pk_bf16_f32 v113, v114, v115
	v_cvt_pk_bf16_f32 v114, v108, v109
	v_cvt_pk_bf16_f32 v115, v110, v111
	global_store_dwordx4 v152, v[112:115], s[44:45]
	v_mul_f32_e32 v104, 0xbfb8aa3b, v104
	v_mul_f32_e32 v105, 0xbfb8aa3b, v105
	v_mul_f32_e32 v106, 0xbfb8aa3b, v106
	v_mul_f32_e32 v107, 0xbfb8aa3b, v107
	v_mul_f32_e32 v100, 0xbfb8aa3b, v100
	v_mul_f32_e32 v101, 0xbfb8aa3b, v101
	v_mul_f32_e32 v102, 0xbfb8aa3b, v102
	v_mul_f32_e32 v103, 0xbfb8aa3b, v103
	v_exp_f32_e32 v104, v104
	v_exp_f32_e32 v105, v105
	v_exp_f32_e32 v106, v106
	v_exp_f32_e32 v107, v107
	v_exp_f32_e32 v100, v100
	v_exp_f32_e32 v101, v101
	v_exp_f32_e32 v102, v102
	v_exp_f32_e32 v103, v103
	v_add_f32_e32 v104, 1.0, v104
	v_add_f32_e32 v105, 1.0, v105
	v_add_f32_e32 v106, 1.0, v106
	v_add_f32_e32 v107, 1.0, v107
	v_add_f32_e32 v100, 1.0, v100
	v_add_f32_e32 v101, 1.0, v101
	v_add_f32_e32 v102, 1.0, v102
	v_add_f32_e32 v103, 1.0, v103
	v_rcp_f32_e32 v104, v104
	v_rcp_f32_e32 v105, v105
	v_rcp_f32_e32 v106, v106
	v_rcp_f32_e32 v107, v107
	v_rcp_f32_e32 v100, v100
	v_rcp_f32_e32 v101, v101
	v_rcp_f32_e32 v102, v102
	v_rcp_f32_e32 v103, v103
	v_cvt_pk_bf16_f32 v104, v104, v105
	v_cvt_pk_bf16_f32 v105, v106, v107
	v_cvt_pk_bf16_f32 v106, v100, v101
	v_cvt_pk_bf16_f32 v107, v102, v103
	global_store_dwordx4 v152, v[104:107], s[44:45] offset:256
	v_add_u32_e32 v152, 0x26000, v152
	v_mul_f32_e32 v96, 0xbfb8aa3b, v96
	v_mul_f32_e32 v97, 0xbfb8aa3b, v97
	v_mul_f32_e32 v98, 0xbfb8aa3b, v98
	v_mul_f32_e32 v99, 0xbfb8aa3b, v99
	v_mul_f32_e32 v92, 0xbfb8aa3b, v92
	v_mul_f32_e32 v93, 0xbfb8aa3b, v93
	v_mul_f32_e32 v94, 0xbfb8aa3b, v94
	v_mul_f32_e32 v95, 0xbfb8aa3b, v95
	v_exp_f32_e32 v96, v96
	v_exp_f32_e32 v97, v97
	v_exp_f32_e32 v98, v98
	v_exp_f32_e32 v99, v99
	v_exp_f32_e32 v92, v92
	v_exp_f32_e32 v93, v93
	v_exp_f32_e32 v94, v94
	v_exp_f32_e32 v95, v95
	v_add_f32_e32 v96, 1.0, v96
	v_add_f32_e32 v97, 1.0, v97
	v_add_f32_e32 v98, 1.0, v98
	v_add_f32_e32 v99, 1.0, v99
	v_add_f32_e32 v92, 1.0, v92
	v_add_f32_e32 v93, 1.0, v93
	v_add_f32_e32 v94, 1.0, v94
	v_add_f32_e32 v95, 1.0, v95
	v_rcp_f32_e32 v96, v96
	v_rcp_f32_e32 v97, v97
	v_rcp_f32_e32 v98, v98
	v_rcp_f32_e32 v99, v99
	v_rcp_f32_e32 v92, v92
	v_rcp_f32_e32 v93, v93
	v_rcp_f32_e32 v94, v94
	v_rcp_f32_e32 v95, v95
	v_cvt_pk_bf16_f32 v96, v96, v97
	v_cvt_pk_bf16_f32 v97, v98, v99
	v_cvt_pk_bf16_f32 v98, v92, v93
	v_cvt_pk_bf16_f32 v99, v94, v95
	global_store_dwordx4 v152, v[96:99], s[44:45]
	v_mul_f32_e32 v88, 0xbfb8aa3b, v88
	v_mul_f32_e32 v89, 0xbfb8aa3b, v89
	v_mul_f32_e32 v90, 0xbfb8aa3b, v90
	v_mul_f32_e32 v91, 0xbfb8aa3b, v91
	v_mul_f32_e32 v84, 0xbfb8aa3b, v84
	v_mul_f32_e32 v85, 0xbfb8aa3b, v85
	v_mul_f32_e32 v86, 0xbfb8aa3b, v86
	v_mul_f32_e32 v87, 0xbfb8aa3b, v87
	v_exp_f32_e32 v88, v88
	v_exp_f32_e32 v89, v89
	v_exp_f32_e32 v90, v90
	v_exp_f32_e32 v91, v91
	v_exp_f32_e32 v84, v84
	v_exp_f32_e32 v85, v85
	v_exp_f32_e32 v86, v86
	v_exp_f32_e32 v87, v87
	v_add_f32_e32 v88, 1.0, v88
	v_add_f32_e32 v89, 1.0, v89
	v_add_f32_e32 v90, 1.0, v90
	v_add_f32_e32 v91, 1.0, v91
	v_add_f32_e32 v84, 1.0, v84
	v_add_f32_e32 v85, 1.0, v85
	v_add_f32_e32 v86, 1.0, v86
	v_add_f32_e32 v87, 1.0, v87
	v_rcp_f32_e32 v88, v88
	v_rcp_f32_e32 v89, v89
	v_rcp_f32_e32 v90, v90
	v_rcp_f32_e32 v91, v91
	v_rcp_f32_e32 v84, v84
	v_rcp_f32_e32 v85, v85
	v_rcp_f32_e32 v86, v86
	v_rcp_f32_e32 v87, v87
	v_cvt_pk_bf16_f32 v88, v88, v89
	v_cvt_pk_bf16_f32 v89, v90, v91
	v_cvt_pk_bf16_f32 v90, v84, v85
	v_cvt_pk_bf16_f32 v91, v86, v87
	global_store_dwordx4 v152, v[88:91], s[44:45] offset:256
	v_add_u32_e32 v152, 0x26000, v152
	v_mul_f32_e32 v80, 0xbfb8aa3b, v80
	v_mul_f32_e32 v81, 0xbfb8aa3b, v81
	v_mul_f32_e32 v82, 0xbfb8aa3b, v82
	v_mul_f32_e32 v83, 0xbfb8aa3b, v83
	v_mul_f32_e32 v76, 0xbfb8aa3b, v76
	v_mul_f32_e32 v77, 0xbfb8aa3b, v77
	v_mul_f32_e32 v78, 0xbfb8aa3b, v78
	v_mul_f32_e32 v79, 0xbfb8aa3b, v79
	v_exp_f32_e32 v80, v80
	v_exp_f32_e32 v81, v81
	v_exp_f32_e32 v82, v82
	v_exp_f32_e32 v83, v83
	v_exp_f32_e32 v76, v76
	v_exp_f32_e32 v77, v77
	v_exp_f32_e32 v78, v78
	v_exp_f32_e32 v79, v79
	v_add_f32_e32 v80, 1.0, v80
	v_add_f32_e32 v81, 1.0, v81
	v_add_f32_e32 v82, 1.0, v82
	v_add_f32_e32 v83, 1.0, v83
	v_add_f32_e32 v76, 1.0, v76
	v_add_f32_e32 v77, 1.0, v77
	v_add_f32_e32 v78, 1.0, v78
	v_add_f32_e32 v79, 1.0, v79
	v_rcp_f32_e32 v80, v80
	v_rcp_f32_e32 v81, v81
	v_rcp_f32_e32 v82, v82
	v_rcp_f32_e32 v83, v83
	v_rcp_f32_e32 v76, v76
	v_rcp_f32_e32 v77, v77
	v_rcp_f32_e32 v78, v78
	v_rcp_f32_e32 v79, v79
	v_cvt_pk_bf16_f32 v80, v80, v81
	v_cvt_pk_bf16_f32 v81, v82, v83
	v_cvt_pk_bf16_f32 v82, v76, v77
	v_cvt_pk_bf16_f32 v83, v78, v79
	global_store_dwordx4 v152, v[80:83], s[44:45]
	v_mul_f32_e32 v72, 0xbfb8aa3b, v72
	v_mul_f32_e32 v73, 0xbfb8aa3b, v73
	v_mul_f32_e32 v74, 0xbfb8aa3b, v74
	v_mul_f32_e32 v75, 0xbfb8aa3b, v75
	v_mul_f32_e32 v68, 0xbfb8aa3b, v68
	v_mul_f32_e32 v69, 0xbfb8aa3b, v69
	v_mul_f32_e32 v70, 0xbfb8aa3b, v70
	v_mul_f32_e32 v71, 0xbfb8aa3b, v71
	v_exp_f32_e32 v72, v72
	v_exp_f32_e32 v73, v73
	v_exp_f32_e32 v74, v74
	v_exp_f32_e32 v75, v75
	v_exp_f32_e32 v68, v68
	v_exp_f32_e32 v69, v69
	v_exp_f32_e32 v70, v70
	v_exp_f32_e32 v71, v71
	v_add_f32_e32 v72, 1.0, v72
	v_add_f32_e32 v73, 1.0, v73
	v_add_f32_e32 v74, 1.0, v74
	v_add_f32_e32 v75, 1.0, v75
	v_add_f32_e32 v68, 1.0, v68
	v_add_f32_e32 v69, 1.0, v69
	v_add_f32_e32 v70, 1.0, v70
	v_add_f32_e32 v71, 1.0, v71
	v_rcp_f32_e32 v72, v72
	v_rcp_f32_e32 v73, v73
	v_rcp_f32_e32 v74, v74
	v_rcp_f32_e32 v75, v75
	v_rcp_f32_e32 v68, v68
	v_rcp_f32_e32 v69, v69
	v_rcp_f32_e32 v70, v70
	v_rcp_f32_e32 v71, v71
	v_cvt_pk_bf16_f32 v72, v72, v73
	v_cvt_pk_bf16_f32 v73, v74, v75
	v_cvt_pk_bf16_f32 v74, v68, v69
	v_cvt_pk_bf16_f32 v75, v70, v71
	global_store_dwordx4 v152, v[72:75], s[44:45] offset:256
	v_add_u32_e32 v152, 0xbe000, v152
	v_mul_f32_e32 v64, 0xbfb8aa3b, v64
	v_mul_f32_e32 v65, 0xbfb8aa3b, v65
	v_mul_f32_e32 v66, 0xbfb8aa3b, v66
	v_mul_f32_e32 v67, 0xbfb8aa3b, v67
	v_mul_f32_e32 v60, 0xbfb8aa3b, v60
	v_mul_f32_e32 v61, 0xbfb8aa3b, v61
	v_mul_f32_e32 v62, 0xbfb8aa3b, v62
	v_mul_f32_e32 v63, 0xbfb8aa3b, v63
	v_exp_f32_e32 v64, v64
	v_exp_f32_e32 v65, v65
	v_exp_f32_e32 v66, v66
	v_exp_f32_e32 v67, v67
	v_exp_f32_e32 v60, v60
	v_exp_f32_e32 v61, v61
	v_exp_f32_e32 v62, v62
	v_exp_f32_e32 v63, v63
	v_add_f32_e32 v64, 1.0, v64
	v_add_f32_e32 v65, 1.0, v65
	v_add_f32_e32 v66, 1.0, v66
	v_add_f32_e32 v67, 1.0, v67
	v_add_f32_e32 v60, 1.0, v60
	v_add_f32_e32 v61, 1.0, v61
	v_add_f32_e32 v62, 1.0, v62
	v_add_f32_e32 v63, 1.0, v63
	v_rcp_f32_e32 v64, v64
	v_rcp_f32_e32 v65, v65
	v_rcp_f32_e32 v66, v66
	v_rcp_f32_e32 v67, v67
	v_rcp_f32_e32 v60, v60
	v_rcp_f32_e32 v61, v61
	v_rcp_f32_e32 v62, v62
	v_rcp_f32_e32 v63, v63
	v_cvt_pk_bf16_f32 v64, v64, v65
	v_cvt_pk_bf16_f32 v65, v66, v67
	v_cvt_pk_bf16_f32 v66, v60, v61
	v_cvt_pk_bf16_f32 v67, v62, v63
	global_store_dwordx4 v152, v[64:67], s[44:45]
	v_mul_f32_e32 v56, 0xbfb8aa3b, v56
	v_mul_f32_e32 v57, 0xbfb8aa3b, v57
	v_mul_f32_e32 v58, 0xbfb8aa3b, v58
	v_mul_f32_e32 v59, 0xbfb8aa3b, v59
	v_mul_f32_e32 v52, 0xbfb8aa3b, v52
	v_mul_f32_e32 v53, 0xbfb8aa3b, v53
	v_mul_f32_e32 v54, 0xbfb8aa3b, v54
	v_mul_f32_e32 v55, 0xbfb8aa3b, v55
	v_exp_f32_e32 v56, v56
	v_exp_f32_e32 v57, v57
	v_exp_f32_e32 v58, v58
	v_exp_f32_e32 v59, v59
	v_exp_f32_e32 v52, v52
	v_exp_f32_e32 v53, v53
	v_exp_f32_e32 v54, v54
	v_exp_f32_e32 v55, v55
	v_add_f32_e32 v56, 1.0, v56
	v_add_f32_e32 v57, 1.0, v57
	v_add_f32_e32 v58, 1.0, v58
	v_add_f32_e32 v59, 1.0, v59
	v_add_f32_e32 v52, 1.0, v52
	v_add_f32_e32 v53, 1.0, v53
	v_add_f32_e32 v54, 1.0, v54
	v_add_f32_e32 v55, 1.0, v55
	v_rcp_f32_e32 v56, v56
	v_rcp_f32_e32 v57, v57
	v_rcp_f32_e32 v58, v58
	v_rcp_f32_e32 v59, v59
	v_rcp_f32_e32 v52, v52
	v_rcp_f32_e32 v53, v53
	v_rcp_f32_e32 v54, v54
	v_rcp_f32_e32 v55, v55
	v_cvt_pk_bf16_f32 v56, v56, v57
	v_cvt_pk_bf16_f32 v57, v58, v59
	v_cvt_pk_bf16_f32 v58, v52, v53
	v_cvt_pk_bf16_f32 v59, v54, v55
	global_store_dwordx4 v152, v[56:59], s[44:45] offset:256
	v_add_u32_e32 v152, 0x26000, v152
	v_mul_f32_e32 v48, 0xbfb8aa3b, v48
	v_mul_f32_e32 v49, 0xbfb8aa3b, v49
	v_mul_f32_e32 v50, 0xbfb8aa3b, v50
	v_mul_f32_e32 v51, 0xbfb8aa3b, v51
	v_mul_f32_e32 v44, 0xbfb8aa3b, v44
	v_mul_f32_e32 v45, 0xbfb8aa3b, v45
	v_mul_f32_e32 v46, 0xbfb8aa3b, v46
	v_mul_f32_e32 v47, 0xbfb8aa3b, v47
	v_exp_f32_e32 v48, v48
	v_exp_f32_e32 v49, v49
	v_exp_f32_e32 v50, v50
	v_exp_f32_e32 v51, v51
	v_exp_f32_e32 v44, v44
	v_exp_f32_e32 v45, v45
	v_exp_f32_e32 v46, v46
	v_exp_f32_e32 v47, v47
	v_add_f32_e32 v48, 1.0, v48
	v_add_f32_e32 v49, 1.0, v49
	v_add_f32_e32 v50, 1.0, v50
	v_add_f32_e32 v51, 1.0, v51
	v_add_f32_e32 v44, 1.0, v44
	v_add_f32_e32 v45, 1.0, v45
	v_add_f32_e32 v46, 1.0, v46
	v_add_f32_e32 v47, 1.0, v47
	v_rcp_f32_e32 v48, v48
	v_rcp_f32_e32 v49, v49
	v_rcp_f32_e32 v50, v50
	v_rcp_f32_e32 v51, v51
	v_rcp_f32_e32 v44, v44
	v_rcp_f32_e32 v45, v45
	v_rcp_f32_e32 v46, v46
	v_rcp_f32_e32 v47, v47
	v_cvt_pk_bf16_f32 v48, v48, v49
	v_cvt_pk_bf16_f32 v49, v50, v51
	v_cvt_pk_bf16_f32 v50, v44, v45
	v_cvt_pk_bf16_f32 v51, v46, v47
	global_store_dwordx4 v152, v[48:51], s[44:45]
	v_mul_f32_e32 v40, 0xbfb8aa3b, v40
	v_mul_f32_e32 v41, 0xbfb8aa3b, v41
	v_mul_f32_e32 v42, 0xbfb8aa3b, v42
	v_mul_f32_e32 v43, 0xbfb8aa3b, v43
	v_mul_f32_e32 v36, 0xbfb8aa3b, v36
	v_mul_f32_e32 v37, 0xbfb8aa3b, v37
	v_mul_f32_e32 v38, 0xbfb8aa3b, v38
	v_mul_f32_e32 v39, 0xbfb8aa3b, v39
	v_exp_f32_e32 v40, v40
	v_exp_f32_e32 v41, v41
	v_exp_f32_e32 v42, v42
	v_exp_f32_e32 v43, v43
	v_exp_f32_e32 v36, v36
	v_exp_f32_e32 v37, v37
	v_exp_f32_e32 v38, v38
	v_exp_f32_e32 v39, v39
	v_add_f32_e32 v40, 1.0, v40
	v_add_f32_e32 v41, 1.0, v41
	v_add_f32_e32 v42, 1.0, v42
	v_add_f32_e32 v43, 1.0, v43
	v_add_f32_e32 v36, 1.0, v36
	v_add_f32_e32 v37, 1.0, v37
	v_add_f32_e32 v38, 1.0, v38
	v_add_f32_e32 v39, 1.0, v39
	v_rcp_f32_e32 v40, v40
	v_rcp_f32_e32 v41, v41
	v_rcp_f32_e32 v42, v42
	v_rcp_f32_e32 v43, v43
	v_rcp_f32_e32 v36, v36
	v_rcp_f32_e32 v37, v37
	v_rcp_f32_e32 v38, v38
	v_rcp_f32_e32 v39, v39
	v_cvt_pk_bf16_f32 v40, v40, v41
	v_cvt_pk_bf16_f32 v41, v42, v43
	v_cvt_pk_bf16_f32 v42, v36, v37
	v_cvt_pk_bf16_f32 v43, v38, v39
	global_store_dwordx4 v152, v[40:43], s[44:45] offset:256
	v_add_u32_e32 v152, 0x26000, v152
	v_mul_f32_e32 v32, 0xbfb8aa3b, v32
	v_mul_f32_e32 v33, 0xbfb8aa3b, v33
	v_mul_f32_e32 v34, 0xbfb8aa3b, v34
	v_mul_f32_e32 v35, 0xbfb8aa3b, v35
	v_mul_f32_e32 v28, 0xbfb8aa3b, v28
	v_mul_f32_e32 v29, 0xbfb8aa3b, v29
	v_mul_f32_e32 v30, 0xbfb8aa3b, v30
	v_mul_f32_e32 v31, 0xbfb8aa3b, v31
	v_exp_f32_e32 v32, v32
	v_exp_f32_e32 v33, v33
	v_exp_f32_e32 v34, v34
	v_exp_f32_e32 v35, v35
	v_exp_f32_e32 v28, v28
	v_exp_f32_e32 v29, v29
	v_exp_f32_e32 v30, v30
	v_exp_f32_e32 v31, v31
	v_add_f32_e32 v32, 1.0, v32
	v_add_f32_e32 v33, 1.0, v33
	v_add_f32_e32 v34, 1.0, v34
	v_add_f32_e32 v35, 1.0, v35
	v_add_f32_e32 v28, 1.0, v28
	v_add_f32_e32 v29, 1.0, v29
	v_add_f32_e32 v30, 1.0, v30
	v_add_f32_e32 v31, 1.0, v31
	v_rcp_f32_e32 v32, v32
	v_rcp_f32_e32 v33, v33
	v_rcp_f32_e32 v34, v34
	v_rcp_f32_e32 v35, v35
	v_rcp_f32_e32 v28, v28
	v_rcp_f32_e32 v29, v29
	v_rcp_f32_e32 v30, v30
	v_rcp_f32_e32 v31, v31
	v_cvt_pk_bf16_f32 v32, v32, v33
	v_cvt_pk_bf16_f32 v33, v34, v35
	v_cvt_pk_bf16_f32 v34, v28, v29
	v_cvt_pk_bf16_f32 v35, v30, v31
	global_store_dwordx4 v152, v[32:35], s[44:45]
	v_mul_f32_e32 v24, 0xbfb8aa3b, v24
	v_mul_f32_e32 v25, 0xbfb8aa3b, v25
	v_mul_f32_e32 v26, 0xbfb8aa3b, v26
	v_mul_f32_e32 v27, 0xbfb8aa3b, v27
	v_mul_f32_e32 v20, 0xbfb8aa3b, v20
	v_mul_f32_e32 v21, 0xbfb8aa3b, v21
	v_mul_f32_e32 v22, 0xbfb8aa3b, v22
	v_mul_f32_e32 v23, 0xbfb8aa3b, v23
	v_exp_f32_e32 v24, v24
	v_exp_f32_e32 v25, v25
	v_exp_f32_e32 v26, v26
	v_exp_f32_e32 v27, v27
	v_exp_f32_e32 v20, v20
	v_exp_f32_e32 v21, v21
	v_exp_f32_e32 v22, v22
	v_exp_f32_e32 v23, v23
	v_add_f32_e32 v24, 1.0, v24
	v_add_f32_e32 v25, 1.0, v25
	v_add_f32_e32 v26, 1.0, v26
	v_add_f32_e32 v27, 1.0, v27
	v_add_f32_e32 v20, 1.0, v20
	v_add_f32_e32 v21, 1.0, v21
	v_add_f32_e32 v22, 1.0, v22
	v_add_f32_e32 v23, 1.0, v23
	v_rcp_f32_e32 v24, v24
	v_rcp_f32_e32 v25, v25
	v_rcp_f32_e32 v26, v26
	v_rcp_f32_e32 v27, v27
	v_rcp_f32_e32 v20, v20
	v_rcp_f32_e32 v21, v21
	v_rcp_f32_e32 v22, v22
	v_rcp_f32_e32 v23, v23
	v_cvt_pk_bf16_f32 v24, v24, v25
	v_cvt_pk_bf16_f32 v25, v26, v27
	v_cvt_pk_bf16_f32 v26, v20, v21
	v_cvt_pk_bf16_f32 v27, v22, v23
	global_store_dwordx4 v152, v[24:27], s[44:45] offset:256
	v_add_u32_e32 v152, 0x26000, v152
	v_mul_f32_e32 v16, 0xbfb8aa3b, v16
	v_mul_f32_e32 v17, 0xbfb8aa3b, v17
	v_mul_f32_e32 v18, 0xbfb8aa3b, v18
	v_mul_f32_e32 v19, 0xbfb8aa3b, v19
	v_mul_f32_e32 v12, 0xbfb8aa3b, v12
	v_mul_f32_e32 v13, 0xbfb8aa3b, v13
	v_mul_f32_e32 v14, 0xbfb8aa3b, v14
	v_mul_f32_e32 v15, 0xbfb8aa3b, v15
	v_exp_f32_e32 v16, v16
	v_exp_f32_e32 v17, v17
	v_exp_f32_e32 v18, v18
	v_exp_f32_e32 v19, v19
	v_exp_f32_e32 v12, v12
	v_exp_f32_e32 v13, v13
	v_exp_f32_e32 v14, v14
	v_exp_f32_e32 v15, v15
	v_add_f32_e32 v16, 1.0, v16
	v_add_f32_e32 v17, 1.0, v17
	v_add_f32_e32 v18, 1.0, v18
	v_add_f32_e32 v19, 1.0, v19
	v_add_f32_e32 v12, 1.0, v12
	v_add_f32_e32 v13, 1.0, v13
	v_add_f32_e32 v14, 1.0, v14
	v_add_f32_e32 v15, 1.0, v15
	v_rcp_f32_e32 v16, v16
	v_rcp_f32_e32 v17, v17
	v_rcp_f32_e32 v18, v18
	v_rcp_f32_e32 v19, v19
	v_rcp_f32_e32 v12, v12
	v_rcp_f32_e32 v13, v13
	v_rcp_f32_e32 v14, v14
	v_rcp_f32_e32 v15, v15
	v_cvt_pk_bf16_f32 v16, v16, v17
	v_cvt_pk_bf16_f32 v17, v18, v19
	v_cvt_pk_bf16_f32 v18, v12, v13
	v_cvt_pk_bf16_f32 v19, v14, v15
	global_store_dwordx4 v152, v[16:19], s[44:45]
	v_mul_f32_e32 v8, 0xbfb8aa3b, v8
	v_mul_f32_e32 v9, 0xbfb8aa3b, v9
	v_mul_f32_e32 v10, 0xbfb8aa3b, v10
	v_mul_f32_e32 v11, 0xbfb8aa3b, v11
	v_mul_f32_e32 v4, 0xbfb8aa3b, v4
	v_mul_f32_e32 v5, 0xbfb8aa3b, v5
	v_mul_f32_e32 v6, 0xbfb8aa3b, v6
	v_mul_f32_e32 v7, 0xbfb8aa3b, v7
	v_exp_f32_e32 v8, v8
	v_exp_f32_e32 v9, v9
	v_exp_f32_e32 v10, v10
	v_exp_f32_e32 v11, v11
	v_exp_f32_e32 v4, v4
	v_exp_f32_e32 v5, v5
	v_exp_f32_e32 v6, v6
	v_exp_f32_e32 v7, v7
	v_add_f32_e32 v8, 1.0, v8
	v_add_f32_e32 v9, 1.0, v9
	v_add_f32_e32 v10, 1.0, v10
	v_add_f32_e32 v11, 1.0, v11
	v_add_f32_e32 v4, 1.0, v4
	v_add_f32_e32 v5, 1.0, v5
	v_add_f32_e32 v6, 1.0, v6
	v_add_f32_e32 v7, 1.0, v7
	v_rcp_f32_e32 v8, v8
	v_rcp_f32_e32 v9, v9
	v_rcp_f32_e32 v10, v10
	v_rcp_f32_e32 v11, v11
	v_rcp_f32_e32 v4, v4
	v_rcp_f32_e32 v5, v5
	v_rcp_f32_e32 v6, v6
	v_rcp_f32_e32 v7, v7
	v_cvt_pk_bf16_f32 v8, v8, v9
	v_cvt_pk_bf16_f32 v9, v10, v11
	v_cvt_pk_bf16_f32 v10, v4, v5
	v_cvt_pk_bf16_f32 v11, v6, v7
	global_store_dwordx4 v152, v[8:11], s[44:45] offset:256
	s_branch .LBB0_590
.LBB0_587:
	s_and_b64 vcc, exec, s[2:3]
	s_cbranch_vccz .LBB0_589
	v_add_u32_e32 v152, s9, v192
	v_mov_b32_e32 v153, v2
	v_lshl_add_u64 v[132:133], v[152:153], 2, s[56:57]
	global_load_dwordx4 v[160:163], v[132:133], off
	global_load_dwordx4 v[196:199], v[132:133], off offset:16
	global_load_dwordx4 v[136:139], v[132:133], off offset:512
	s_nop 0
	global_load_dwordx4 v[132:135], v[132:133], off offset:528
	v_mul_f32_e32 v153, 0x3fb8aa3b, v128
	v_exp_f32_e32 v153, v153
	v_mov_b64_e32 v[168:169], s[42:43]
	v_mad_i64_i32 v[170:171], s[2:3], v195, s96, v[168:169]
	v_add_f32_e32 v153, 1.0, v153
	v_rcp_f32_e32 v166, v153
	v_mul_f32_e32 v153, 0x3fb8aa3b, v129
	v_exp_f32_e32 v153, v153
	s_waitcnt vmcnt(0) lgkmcnt(0)
	v_pk_add_f32 v[160:161], v[160:161], 1.0 op_sel_hi:[1,0] neg_lo:[1,0] neg_hi:[1,0]
	v_add_f32_e32 v153, 1.0, v153
	v_rcp_f32_e32 v167, v153
	v_mul_f32_e32 v153, 0x3fb8aa3b, v130
	v_exp_f32_e32 v153, v153
	v_pk_add_f32 v[164:165], v[162:163], 1.0 op_sel_hi:[1,0] neg_lo:[1,0] neg_hi:[1,0]
	v_pk_mul_f32 v[200:201], v[166:167], v[160:161]
	v_lshlrev_b32_e32 v166, 2, v152
	v_add_f32_e32 v153, 1.0, v153
	v_rcp_f32_e32 v172, v153
	v_mul_f32_e32 v153, 0x3fb8aa3b, v131
	v_exp_f32_e32 v153, v153
	v_mov_b32_e32 v167, v2
	v_mul_f32_e32 v152, 0x3fb8aa3b, v124
	v_exp_f32_e32 v152, v152
	v_add_f32_e32 v153, 1.0, v153
	v_rcp_f32_e32 v173, v153
	v_mul_f32_e32 v153, 0x3fb8aa3b, v125
	v_exp_f32_e32 v153, v153
	v_add_f32_e32 v152, 1.0, v152
	v_pk_mul_f32 v[202:203], v[172:173], v[164:165]
	v_lshl_add_u64 v[172:173], v[170:171], 0, v[166:167]
	v_mul_f32_e32 v170, 0x3fb8aa3b, v126
	v_exp_f32_e32 v170, v170
	v_add_f32_e32 v153, 1.0, v153
	v_rcp_f32_e32 v152, v152
	v_rcp_f32_e32 v153, v153
	v_add_f32_e32 v170, 1.0, v170
	v_rcp_f32_e32 v174, v170
	v_mul_f32_e32 v170, 0x3fb8aa3b, v127
	v_exp_f32_e32 v170, v170
	v_pk_add_f32 v[162:163], v[196:197], 1.0 op_sel_hi:[1,0] neg_lo:[1,0] neg_hi:[1,0]
	v_pk_add_f32 v[136:137], v[136:137], 1.0 op_sel_hi:[1,0] neg_lo:[1,0] neg_hi:[1,0]
	v_pk_mul_f32 v[196:197], v[152:153], v[162:163]
	v_mul_f32_e32 v152, 0x3fb8aa3b, v120
	v_mul_f32_e32 v153, 0x3fb8aa3b, v121
	v_add_f32_e32 v170, 1.0, v170
	v_exp_f32_e32 v152, v152
	v_exp_f32_e32 v153, v153
	v_rcp_f32_e32 v175, v170
	v_pk_add_f32 v[170:171], v[198:199], 1.0 op_sel_hi:[1,0] neg_lo:[1,0] neg_hi:[1,0]
	v_add_f32_e32 v152, 1.0, v152
	v_add_f32_e32 v153, 1.0, v153
	v_pk_mul_f32 v[198:199], v[174:175], v[170:171]
	v_rcp_f32_e32 v152, v152
	v_rcp_f32_e32 v153, v153
	v_mul_f32_e32 v174, 0x3fb8aa3b, v122
	v_mul_f32_e32 v175, 0x3fb8aa3b, v123
	v_exp_f32_e32 v174, v174
	v_exp_f32_e32 v175, v175
	global_store_dwordx4 v[172:173], v[196:199], off offset:16
	v_pk_add_f32 v[138:139], v[138:139], 1.0 op_sel_hi:[1,0] neg_lo:[1,0] neg_hi:[1,0]
	v_add_f32_e32 v174, 1.0, v174
	v_pk_mul_f32 v[196:197], v[152:153], v[136:137]
	v_mul_f32_e32 v152, 0x3fb8aa3b, v116
	v_add_f32_e32 v175, 1.0, v175
	v_exp_f32_e32 v152, v152
	v_rcp_f32_e32 v174, v174
	v_rcp_f32_e32 v175, v175
	v_mul_f32_e32 v153, 0x3fb8aa3b, v119
	v_add_f32_e32 v152, 1.0, v152
	v_exp_f32_e32 v153, v153
	v_pk_mul_f32 v[198:199], v[174:175], v[138:139]
	v_rcp_f32_e32 v174, v152
	v_mul_f32_e32 v152, 0x3fb8aa3b, v117
	v_exp_f32_e32 v152, v152
	v_add_f32_e32 v153, 1.0, v153
	v_rcp_f32_e32 v153, v153
	v_pk_add_f32 v[132:133], v[132:133], 1.0 op_sel_hi:[1,0] neg_lo:[1,0] neg_hi:[1,0]
	v_add_f32_e32 v152, 1.0, v152
	v_rcp_f32_e32 v175, v152
	v_mul_f32_e32 v152, 0x3fb8aa3b, v118
	v_exp_f32_e32 v152, v152
	v_pk_add_f32 v[134:135], v[134:135], 1.0 op_sel_hi:[1,0] neg_lo:[1,0] neg_hi:[1,0]
	global_store_dwordx4 v[172:173], v[196:199], off offset:512
	global_store_dwordx4 v[172:173], v[200:203], off
	v_add_f32_e32 v152, 1.0, v152
	v_rcp_f32_e32 v152, v152
	v_pk_mul_f32 v[196:197], v[174:175], v[132:133]
	v_mul_f32_e32 v174, 0x3fb8aa3b, v114
	v_mul_f32_e32 v175, 0x3fb8aa3b, v115
	v_pk_mul_f32 v[198:199], v[152:153], v[134:135]
	global_store_dwordx4 v[172:173], v[196:199], off offset:528
	v_mul_f32_e32 v172, 0x3fb8aa3b, v112
	v_mul_f32_e32 v173, 0x3fb8aa3b, v113
	v_exp_f32_e32 v172, v172
	v_exp_f32_e32 v173, v173
	v_exp_f32_e32 v174, v174
	v_exp_f32_e32 v175, v175
	v_add_f32_e32 v172, 1.0, v172
	v_add_f32_e32 v173, 1.0, v173
	v_add_f32_e32 v174, 1.0, v174
	v_add_f32_e32 v175, 1.0, v175
	v_rcp_f32_e32 v172, v172
	v_rcp_f32_e32 v173, v173
	v_rcp_f32_e32 v174, v174
	v_rcp_f32_e32 v175, v175
	v_or_b32_e32 v152, 16, v195
	v_mad_i64_i32 v[152:153], s[2:3], v152, s96, v[168:169]
	v_pk_mul_f32 v[196:197], v[172:173], v[160:161]
	v_pk_mul_f32 v[198:199], v[174:175], v[164:165]
	v_lshl_add_u64 v[172:173], v[152:153], 0, v[166:167]
	v_mul_f32_e32 v152, 0x3fb8aa3b, v108
	v_mul_f32_e32 v153, 0x3fb8aa3b, v109
	v_mul_f32_e32 v174, 0x3fb8aa3b, v110
	v_mul_f32_e32 v175, 0x3fb8aa3b, v111
	v_exp_f32_e32 v152, v152
	v_exp_f32_e32 v153, v153
	v_exp_f32_e32 v174, v174
	v_exp_f32_e32 v175, v175
	v_add_f32_e32 v152, 1.0, v152
	v_add_f32_e32 v153, 1.0, v153
	v_add_f32_e32 v174, 1.0, v174
	v_add_f32_e32 v175, 1.0, v175
	v_rcp_f32_e32 v152, v152
	v_rcp_f32_e32 v153, v153
	v_rcp_f32_e32 v174, v174
	v_rcp_f32_e32 v175, v175
	global_store_dwordx4 v[172:173], v[196:199], off
	s_nop 1
	v_pk_mul_f32 v[196:197], v[152:153], v[162:163]
	v_pk_mul_f32 v[198:199], v[174:175], v[170:171]
	v_mul_f32_e32 v152, 0x3fb8aa3b, v104
	v_mul_f32_e32 v153, 0x3fb8aa3b, v105
	v_mul_f32_e32 v174, 0x3fb8aa3b, v106
	v_mul_f32_e32 v175, 0x3fb8aa3b, v107
	v_exp_f32_e32 v152, v152
	v_exp_f32_e32 v153, v153
	v_exp_f32_e32 v174, v174
	v_exp_f32_e32 v175, v175
	v_add_f32_e32 v152, 1.0, v152
	v_add_f32_e32 v153, 1.0, v153
	v_add_f32_e32 v174, 1.0, v174
	v_add_f32_e32 v175, 1.0, v175
	v_rcp_f32_e32 v152, v152
	v_rcp_f32_e32 v153, v153
	v_rcp_f32_e32 v174, v174
	v_rcp_f32_e32 v175, v175
	global_store_dwordx4 v[172:173], v[196:199], off offset:16
	s_nop 1
	v_pk_mul_f32 v[196:197], v[152:153], v[136:137]
	v_pk_mul_f32 v[198:199], v[174:175], v[138:139]
	v_mul_f32_e32 v152, 0x3fb8aa3b, v100
	v_mul_f32_e32 v153, 0x3fb8aa3b, v101
	v_mul_f32_e32 v174, 0x3fb8aa3b, v102
	v_mul_f32_e32 v175, 0x3fb8aa3b, v103
	v_exp_f32_e32 v152, v152
	v_exp_f32_e32 v153, v153
	v_exp_f32_e32 v174, v174
	v_exp_f32_e32 v175, v175
	v_add_f32_e32 v152, 1.0, v152
	v_add_f32_e32 v153, 1.0, v153
	v_add_f32_e32 v174, 1.0, v174
	v_add_f32_e32 v175, 1.0, v175
	v_rcp_f32_e32 v152, v152
	v_rcp_f32_e32 v153, v153
	v_rcp_f32_e32 v174, v174
	v_rcp_f32_e32 v175, v175
	global_store_dwordx4 v[172:173], v[196:199], off offset:512
	s_nop 1
	v_pk_mul_f32 v[196:197], v[152:153], v[132:133]
	v_pk_mul_f32 v[198:199], v[174:175], v[134:135]
	global_store_dwordx4 v[172:173], v[196:199], off offset:528
	v_mul_f32_e32 v172, 0x3fb8aa3b, v96
	v_mul_f32_e32 v173, 0x3fb8aa3b, v97
	v_mul_f32_e32 v174, 0x3fb8aa3b, v98
	v_mul_f32_e32 v175, 0x3fb8aa3b, v99
	v_exp_f32_e32 v172, v172
	v_exp_f32_e32 v173, v173
	v_exp_f32_e32 v174, v174
	v_exp_f32_e32 v175, v175
	v_add_f32_e32 v172, 1.0, v172
	v_add_f32_e32 v173, 1.0, v173
	v_add_f32_e32 v174, 1.0, v174
	v_add_f32_e32 v175, 1.0, v175
	v_rcp_f32_e32 v172, v172
	v_rcp_f32_e32 v173, v173
	v_rcp_f32_e32 v174, v174
	v_rcp_f32_e32 v175, v175
	v_or_b32_e32 v152, 32, v195
	v_mad_i64_i32 v[152:153], s[2:3], v152, s96, v[168:169]
	v_pk_mul_f32 v[196:197], v[172:173], v[160:161]
	v_pk_mul_f32 v[198:199], v[174:175], v[164:165]
	v_lshl_add_u64 v[172:173], v[152:153], 0, v[166:167]
	v_mul_f32_e32 v152, 0x3fb8aa3b, v92
	v_mul_f32_e32 v153, 0x3fb8aa3b, v93
	v_mul_f32_e32 v174, 0x3fb8aa3b, v94
	v_mul_f32_e32 v175, 0x3fb8aa3b, v95
	v_exp_f32_e32 v152, v152
	v_exp_f32_e32 v153, v153
	v_exp_f32_e32 v174, v174
	v_exp_f32_e32 v175, v175
	v_add_f32_e32 v152, 1.0, v152
	v_add_f32_e32 v153, 1.0, v153
	v_add_f32_e32 v174, 1.0, v174
	v_add_f32_e32 v175, 1.0, v175
	v_rcp_f32_e32 v152, v152
	v_rcp_f32_e32 v153, v153
	v_rcp_f32_e32 v174, v174
	v_rcp_f32_e32 v175, v175
	global_store_dwordx4 v[172:173], v[196:199], off
	s_nop 1
	v_pk_mul_f32 v[196:197], v[152:153], v[162:163]
	v_pk_mul_f32 v[198:199], v[174:175], v[170:171]
	v_mul_f32_e32 v152, 0x3fb8aa3b, v88
	v_mul_f32_e32 v153, 0x3fb8aa3b, v89
	v_mul_f32_e32 v174, 0x3fb8aa3b, v90
	v_mul_f32_e32 v175, 0x3fb8aa3b, v91
	v_exp_f32_e32 v152, v152
	v_exp_f32_e32 v153, v153
	v_exp_f32_e32 v174, v174
	v_exp_f32_e32 v175, v175
	v_add_f32_e32 v152, 1.0, v152
	v_add_f32_e32 v153, 1.0, v153
	v_add_f32_e32 v174, 1.0, v174
	v_add_f32_e32 v175, 1.0, v175
	v_rcp_f32_e32 v152, v152
	v_rcp_f32_e32 v153, v153
	v_rcp_f32_e32 v174, v174
	v_rcp_f32_e32 v175, v175
	global_store_dwordx4 v[172:173], v[196:199], off offset:16
	s_nop 1
	v_pk_mul_f32 v[196:197], v[152:153], v[136:137]
	v_pk_mul_f32 v[198:199], v[174:175], v[138:139]
	v_mul_f32_e32 v152, 0x3fb8aa3b, v84
	v_mul_f32_e32 v153, 0x3fb8aa3b, v85
	v_mul_f32_e32 v174, 0x3fb8aa3b, v86
	v_mul_f32_e32 v175, 0x3fb8aa3b, v87
	v_exp_f32_e32 v152, v152
	v_exp_f32_e32 v153, v153
	v_exp_f32_e32 v174, v174
	v_exp_f32_e32 v175, v175
	v_add_f32_e32 v152, 1.0, v152
	v_add_f32_e32 v153, 1.0, v153
	v_add_f32_e32 v174, 1.0, v174
	v_add_f32_e32 v175, 1.0, v175
	v_rcp_f32_e32 v152, v152
	v_rcp_f32_e32 v153, v153
	v_rcp_f32_e32 v174, v174
	v_rcp_f32_e32 v175, v175
	global_store_dwordx4 v[172:173], v[196:199], off offset:512
	s_nop 1
	v_pk_mul_f32 v[196:197], v[152:153], v[132:133]
	v_pk_mul_f32 v[198:199], v[174:175], v[134:135]
	global_store_dwordx4 v[172:173], v[196:199], off offset:528
	v_mul_f32_e32 v172, 0x3fb8aa3b, v80
	v_mul_f32_e32 v173, 0x3fb8aa3b, v81
	v_mul_f32_e32 v174, 0x3fb8aa3b, v82
	v_mul_f32_e32 v175, 0x3fb8aa3b, v83
	v_exp_f32_e32 v172, v172
	v_exp_f32_e32 v173, v173
	v_exp_f32_e32 v174, v174
	v_exp_f32_e32 v175, v175
	v_add_f32_e32 v172, 1.0, v172
	v_add_f32_e32 v173, 1.0, v173
	v_add_f32_e32 v174, 1.0, v174
	v_add_f32_e32 v175, 1.0, v175
	v_rcp_f32_e32 v172, v172
	v_rcp_f32_e32 v173, v173
	v_rcp_f32_e32 v174, v174
	v_rcp_f32_e32 v175, v175
	v_or_b32_e32 v152, 48, v195
	v_mad_i64_i32 v[152:153], s[2:3], v152, s96, v[168:169]
	v_pk_mul_f32 v[196:197], v[172:173], v[160:161]
	v_pk_mul_f32 v[198:199], v[174:175], v[164:165]
	v_lshl_add_u64 v[172:173], v[152:153], 0, v[166:167]
	v_mul_f32_e32 v152, 0x3fb8aa3b, v76
	v_mul_f32_e32 v153, 0x3fb8aa3b, v77
	v_mul_f32_e32 v174, 0x3fb8aa3b, v78
	v_mul_f32_e32 v175, 0x3fb8aa3b, v79
	v_exp_f32_e32 v152, v152
	v_exp_f32_e32 v153, v153
	v_exp_f32_e32 v174, v174
	v_exp_f32_e32 v175, v175
	v_add_f32_e32 v152, 1.0, v152
	v_add_f32_e32 v153, 1.0, v153
	v_add_f32_e32 v174, 1.0, v174
	v_add_f32_e32 v175, 1.0, v175
	v_rcp_f32_e32 v152, v152
	v_rcp_f32_e32 v153, v153
	v_rcp_f32_e32 v174, v174
	v_rcp_f32_e32 v175, v175
	global_store_dwordx4 v[172:173], v[196:199], off
	s_nop 1
	v_pk_mul_f32 v[196:197], v[152:153], v[162:163]
	v_pk_mul_f32 v[198:199], v[174:175], v[170:171]
	v_mul_f32_e32 v152, 0x3fb8aa3b, v72
	v_mul_f32_e32 v153, 0x3fb8aa3b, v73
	v_mul_f32_e32 v174, 0x3fb8aa3b, v74
	v_mul_f32_e32 v175, 0x3fb8aa3b, v75
	v_exp_f32_e32 v152, v152
	v_exp_f32_e32 v153, v153
	v_exp_f32_e32 v174, v174
	v_exp_f32_e32 v175, v175
	v_add_f32_e32 v152, 1.0, v152
	v_add_f32_e32 v153, 1.0, v153
	v_add_f32_e32 v174, 1.0, v174
	v_add_f32_e32 v175, 1.0, v175
	v_rcp_f32_e32 v152, v152
	v_rcp_f32_e32 v153, v153
	v_rcp_f32_e32 v174, v174
	v_rcp_f32_e32 v175, v175
	global_store_dwordx4 v[172:173], v[196:199], off offset:16
	s_nop 1
	v_pk_mul_f32 v[196:197], v[152:153], v[136:137]
	v_pk_mul_f32 v[198:199], v[174:175], v[138:139]
	v_mul_f32_e32 v152, 0x3fb8aa3b, v68
	v_mul_f32_e32 v153, 0x3fb8aa3b, v69
	v_mul_f32_e32 v174, 0x3fb8aa3b, v70
	v_mul_f32_e32 v175, 0x3fb8aa3b, v71
	v_exp_f32_e32 v152, v152
	v_exp_f32_e32 v153, v153
	v_exp_f32_e32 v174, v174
	v_exp_f32_e32 v175, v175
	v_add_f32_e32 v152, 1.0, v152
	v_add_f32_e32 v153, 1.0, v153
	v_add_f32_e32 v174, 1.0, v174
	v_add_f32_e32 v175, 1.0, v175
	v_rcp_f32_e32 v152, v152
	v_rcp_f32_e32 v153, v153
	v_rcp_f32_e32 v174, v174
	v_rcp_f32_e32 v175, v175
	global_store_dwordx4 v[172:173], v[196:199], off offset:512
	s_nop 1
	v_pk_mul_f32 v[196:197], v[152:153], v[132:133]
	v_pk_mul_f32 v[198:199], v[174:175], v[134:135]
	global_store_dwordx4 v[172:173], v[196:199], off offset:528
	v_mul_f32_e32 v172, 0x3fb8aa3b, v64
	v_mul_f32_e32 v173, 0x3fb8aa3b, v65
	v_mul_f32_e32 v174, 0x3fb8aa3b, v66
	v_mul_f32_e32 v175, 0x3fb8aa3b, v67
	v_exp_f32_e32 v172, v172
	v_exp_f32_e32 v173, v173
	v_exp_f32_e32 v174, v174
	v_exp_f32_e32 v175, v175
	v_add_f32_e32 v172, 1.0, v172
	v_add_f32_e32 v173, 1.0, v173
	v_add_f32_e32 v174, 1.0, v174
	v_add_f32_e32 v175, 1.0, v175
	v_rcp_f32_e32 v172, v172
	v_rcp_f32_e32 v173, v173
	v_rcp_f32_e32 v174, v174
	v_rcp_f32_e32 v175, v175
	v_add_u32_e32 v152, 0x80, v195
	v_mad_i64_i32 v[152:153], s[2:3], v152, s96, v[168:169]
	v_pk_mul_f32 v[196:197], v[172:173], v[160:161]
	v_pk_mul_f32 v[198:199], v[174:175], v[164:165]
	v_lshl_add_u64 v[172:173], v[152:153], 0, v[166:167]
	v_mul_f32_e32 v152, 0x3fb8aa3b, v60
	v_mul_f32_e32 v153, 0x3fb8aa3b, v61
	v_mul_f32_e32 v174, 0x3fb8aa3b, v62
	v_mul_f32_e32 v175, 0x3fb8aa3b, v63
	v_exp_f32_e32 v152, v152
	v_exp_f32_e32 v153, v153
	v_exp_f32_e32 v174, v174
	v_exp_f32_e32 v175, v175
	v_add_f32_e32 v152, 1.0, v152
	v_add_f32_e32 v153, 1.0, v153
	v_add_f32_e32 v174, 1.0, v174
	v_add_f32_e32 v175, 1.0, v175
	v_rcp_f32_e32 v152, v152
	v_rcp_f32_e32 v153, v153
	v_rcp_f32_e32 v174, v174
	v_rcp_f32_e32 v175, v175
	global_store_dwordx4 v[172:173], v[196:199], off
	s_nop 1
	v_pk_mul_f32 v[196:197], v[152:153], v[162:163]
	v_pk_mul_f32 v[198:199], v[174:175], v[170:171]
	v_mul_f32_e32 v152, 0x3fb8aa3b, v56
	v_mul_f32_e32 v153, 0x3fb8aa3b, v57
	v_mul_f32_e32 v174, 0x3fb8aa3b, v58
	v_mul_f32_e32 v175, 0x3fb8aa3b, v59
	v_exp_f32_e32 v152, v152
	v_exp_f32_e32 v153, v153
	v_exp_f32_e32 v174, v174
	v_exp_f32_e32 v175, v175
	v_add_f32_e32 v152, 1.0, v152
	v_add_f32_e32 v153, 1.0, v153
	v_add_f32_e32 v174, 1.0, v174
	v_add_f32_e32 v175, 1.0, v175
	v_rcp_f32_e32 v152, v152
	v_rcp_f32_e32 v153, v153
	v_rcp_f32_e32 v174, v174
	v_rcp_f32_e32 v175, v175
	global_store_dwordx4 v[172:173], v[196:199], off offset:16
	s_nop 1
	v_pk_mul_f32 v[196:197], v[152:153], v[136:137]
	v_pk_mul_f32 v[198:199], v[174:175], v[138:139]
	v_mul_f32_e32 v152, 0x3fb8aa3b, v52
	v_mul_f32_e32 v153, 0x3fb8aa3b, v53
	v_mul_f32_e32 v174, 0x3fb8aa3b, v54
	v_mul_f32_e32 v175, 0x3fb8aa3b, v55
	v_exp_f32_e32 v152, v152
	v_exp_f32_e32 v153, v153
	v_exp_f32_e32 v174, v174
	v_exp_f32_e32 v175, v175
	v_add_f32_e32 v152, 1.0, v152
	v_add_f32_e32 v153, 1.0, v153
	v_add_f32_e32 v174, 1.0, v174
	v_add_f32_e32 v175, 1.0, v175
	v_rcp_f32_e32 v152, v152
	v_rcp_f32_e32 v153, v153
	v_rcp_f32_e32 v174, v174
	v_rcp_f32_e32 v175, v175
	global_store_dwordx4 v[172:173], v[196:199], off offset:512
	s_nop 1
	v_pk_mul_f32 v[196:197], v[152:153], v[132:133]
	v_pk_mul_f32 v[198:199], v[174:175], v[134:135]
	global_store_dwordx4 v[172:173], v[196:199], off offset:528
	v_mul_f32_e32 v172, 0x3fb8aa3b, v48
	v_mul_f32_e32 v173, 0x3fb8aa3b, v49
	v_mul_f32_e32 v174, 0x3fb8aa3b, v50
	v_mul_f32_e32 v175, 0x3fb8aa3b, v51
	v_exp_f32_e32 v172, v172
	v_exp_f32_e32 v173, v173
	v_exp_f32_e32 v174, v174
	v_exp_f32_e32 v175, v175
	v_add_f32_e32 v172, 1.0, v172
	v_add_f32_e32 v173, 1.0, v173
	v_add_f32_e32 v174, 1.0, v174
	v_add_f32_e32 v175, 1.0, v175
	v_rcp_f32_e32 v172, v172
	v_rcp_f32_e32 v173, v173
	v_rcp_f32_e32 v174, v174
	v_rcp_f32_e32 v175, v175
	v_add_u32_e32 v152, 0x90, v195
	v_mad_i64_i32 v[152:153], s[2:3], v152, s96, v[168:169]
	v_pk_mul_f32 v[196:197], v[172:173], v[160:161]
	v_pk_mul_f32 v[198:199], v[174:175], v[164:165]
	v_lshl_add_u64 v[172:173], v[152:153], 0, v[166:167]
	v_mul_f32_e32 v152, 0x3fb8aa3b, v44
	v_mul_f32_e32 v153, 0x3fb8aa3b, v45
	v_mul_f32_e32 v174, 0x3fb8aa3b, v46
	v_mul_f32_e32 v175, 0x3fb8aa3b, v47
	v_exp_f32_e32 v152, v152
	v_exp_f32_e32 v153, v153
	v_exp_f32_e32 v174, v174
	v_exp_f32_e32 v175, v175
	v_add_f32_e32 v152, 1.0, v152
	v_add_f32_e32 v153, 1.0, v153
	v_add_f32_e32 v174, 1.0, v174
	v_add_f32_e32 v175, 1.0, v175
	v_rcp_f32_e32 v152, v152
	v_rcp_f32_e32 v153, v153
	v_rcp_f32_e32 v174, v174
	v_rcp_f32_e32 v175, v175
	global_store_dwordx4 v[172:173], v[196:199], off
	s_nop 1
	v_pk_mul_f32 v[196:197], v[152:153], v[162:163]
	v_pk_mul_f32 v[198:199], v[174:175], v[170:171]
	v_mul_f32_e32 v152, 0x3fb8aa3b, v40
	v_mul_f32_e32 v153, 0x3fb8aa3b, v41
	v_mul_f32_e32 v174, 0x3fb8aa3b, v42
	v_mul_f32_e32 v175, 0x3fb8aa3b, v43
	v_exp_f32_e32 v152, v152
	v_exp_f32_e32 v153, v153
	v_exp_f32_e32 v174, v174
	v_exp_f32_e32 v175, v175
	v_add_f32_e32 v152, 1.0, v152
	v_add_f32_e32 v153, 1.0, v153
	v_add_f32_e32 v174, 1.0, v174
	v_add_f32_e32 v175, 1.0, v175
	v_rcp_f32_e32 v152, v152
	v_rcp_f32_e32 v153, v153
	v_rcp_f32_e32 v174, v174
	v_rcp_f32_e32 v175, v175
	global_store_dwordx4 v[172:173], v[196:199], off offset:16
	s_nop 1
	v_pk_mul_f32 v[196:197], v[152:153], v[136:137]
	v_pk_mul_f32 v[198:199], v[174:175], v[138:139]
	v_mul_f32_e32 v152, 0x3fb8aa3b, v36
	v_mul_f32_e32 v153, 0x3fb8aa3b, v37
	v_mul_f32_e32 v174, 0x3fb8aa3b, v38
	v_mul_f32_e32 v175, 0x3fb8aa3b, v39
	v_exp_f32_e32 v152, v152
	v_exp_f32_e32 v153, v153
	v_exp_f32_e32 v174, v174
	v_exp_f32_e32 v175, v175
	v_add_f32_e32 v152, 1.0, v152
	v_add_f32_e32 v153, 1.0, v153
	v_add_f32_e32 v174, 1.0, v174
	v_add_f32_e32 v175, 1.0, v175
	v_rcp_f32_e32 v152, v152
	v_rcp_f32_e32 v153, v153
	v_rcp_f32_e32 v174, v174
	v_rcp_f32_e32 v175, v175
	global_store_dwordx4 v[172:173], v[196:199], off offset:512
	s_nop 1
	v_pk_mul_f32 v[196:197], v[152:153], v[132:133]
	v_pk_mul_f32 v[198:199], v[174:175], v[134:135]
	global_store_dwordx4 v[172:173], v[196:199], off offset:528
	v_mul_f32_e32 v172, 0x3fb8aa3b, v32
	v_mul_f32_e32 v173, 0x3fb8aa3b, v33
	v_mul_f32_e32 v174, 0x3fb8aa3b, v34
	v_mul_f32_e32 v175, 0x3fb8aa3b, v35
	v_exp_f32_e32 v172, v172
	v_exp_f32_e32 v173, v173
	v_exp_f32_e32 v174, v174
	v_exp_f32_e32 v175, v175
	v_add_f32_e32 v172, 1.0, v172
	v_add_f32_e32 v173, 1.0, v173
	v_add_f32_e32 v174, 1.0, v174
	v_add_f32_e32 v175, 1.0, v175
	v_rcp_f32_e32 v172, v172
	v_rcp_f32_e32 v173, v173
	v_rcp_f32_e32 v174, v174
	v_rcp_f32_e32 v175, v175
	v_add_u32_e32 v152, 0xa0, v195
	v_mad_i64_i32 v[152:153], s[2:3], v152, s96, v[168:169]
	v_pk_mul_f32 v[196:197], v[172:173], v[160:161]
	v_pk_mul_f32 v[198:199], v[174:175], v[164:165]
	v_lshl_add_u64 v[172:173], v[152:153], 0, v[166:167]
	v_mul_f32_e32 v152, 0x3fb8aa3b, v28
	v_mul_f32_e32 v153, 0x3fb8aa3b, v29
	v_mul_f32_e32 v174, 0x3fb8aa3b, v30
	v_mul_f32_e32 v175, 0x3fb8aa3b, v31
	v_exp_f32_e32 v152, v152
	v_exp_f32_e32 v153, v153
	v_exp_f32_e32 v174, v174
	v_exp_f32_e32 v175, v175
	v_add_f32_e32 v152, 1.0, v152
	v_add_f32_e32 v153, 1.0, v153
	v_add_f32_e32 v174, 1.0, v174
	v_add_f32_e32 v175, 1.0, v175
	v_rcp_f32_e32 v152, v152
	v_rcp_f32_e32 v153, v153
	v_rcp_f32_e32 v174, v174
	v_rcp_f32_e32 v175, v175
	global_store_dwordx4 v[172:173], v[196:199], off
	s_nop 1
	v_pk_mul_f32 v[196:197], v[152:153], v[162:163]
	v_pk_mul_f32 v[198:199], v[174:175], v[170:171]
	v_mul_f32_e32 v152, 0x3fb8aa3b, v24
	v_mul_f32_e32 v153, 0x3fb8aa3b, v25
	v_mul_f32_e32 v174, 0x3fb8aa3b, v26
	v_mul_f32_e32 v175, 0x3fb8aa3b, v27
	v_exp_f32_e32 v152, v152
	v_exp_f32_e32 v153, v153
	v_exp_f32_e32 v174, v174
	v_exp_f32_e32 v175, v175
	v_add_f32_e32 v152, 1.0, v152
	v_add_f32_e32 v153, 1.0, v153
	v_add_f32_e32 v174, 1.0, v174
	v_add_f32_e32 v175, 1.0, v175
	v_rcp_f32_e32 v152, v152
	v_rcp_f32_e32 v153, v153
	v_rcp_f32_e32 v174, v174
	v_rcp_f32_e32 v175, v175
	global_store_dwordx4 v[172:173], v[196:199], off offset:16
	s_nop 1
	v_pk_mul_f32 v[196:197], v[152:153], v[136:137]
	v_pk_mul_f32 v[198:199], v[174:175], v[138:139]
	v_mul_f32_e32 v152, 0x3fb8aa3b, v20
	v_mul_f32_e32 v153, 0x3fb8aa3b, v21
	v_mul_f32_e32 v174, 0x3fb8aa3b, v22
	v_mul_f32_e32 v175, 0x3fb8aa3b, v23
	v_exp_f32_e32 v152, v152
	v_exp_f32_e32 v153, v153
	v_exp_f32_e32 v174, v174
	v_exp_f32_e32 v175, v175
	v_add_f32_e32 v152, 1.0, v152
	v_add_f32_e32 v153, 1.0, v153
	v_add_f32_e32 v174, 1.0, v174
	v_add_f32_e32 v175, 1.0, v175
	v_rcp_f32_e32 v152, v152
	v_rcp_f32_e32 v153, v153
	v_rcp_f32_e32 v174, v174
	v_rcp_f32_e32 v175, v175
	global_store_dwordx4 v[172:173], v[196:199], off offset:512
	s_nop 1
	v_pk_mul_f32 v[196:197], v[152:153], v[132:133]
	v_pk_mul_f32 v[198:199], v[174:175], v[134:135]
	global_store_dwordx4 v[172:173], v[196:199], off offset:528
	v_mul_f32_e32 v172, 0x3fb8aa3b, v18
	v_exp_f32_e32 v172, v172
	v_add_u32_e32 v152, 0xb0, v195
	v_mad_i64_i32 v[152:153], s[2:3], v152, s96, v[168:169]
	v_add_f32_e32 v172, 1.0, v172
	v_mul_f32_e32 v168, 0x3fb8aa3b, v16
	v_mul_f32_e32 v169, 0x3fb8aa3b, v17
	v_rcp_f32_e32 v174, v172
	v_mul_f32_e32 v172, 0x3fb8aa3b, v19
	v_exp_f32_e32 v168, v168
	v_exp_f32_e32 v169, v169
	v_exp_f32_e32 v172, v172
	v_add_f32_e32 v168, 1.0, v168
	v_add_f32_e32 v169, 1.0, v169
	v_add_f32_e32 v172, 1.0, v172
	v_rcp_f32_e32 v168, v168
	v_rcp_f32_e32 v169, v169
	v_rcp_f32_e32 v175, v172
	v_pk_mul_f32 v[172:173], v[168:169], v[160:161]
	v_pk_mul_f32 v[174:175], v[174:175], v[164:165]
	v_lshl_add_u64 v[160:161], v[152:153], 0, v[166:167]
	v_mul_f32_e32 v152, 0x3fb8aa3b, v12
	v_mul_f32_e32 v153, 0x3fb8aa3b, v13
	v_mul_f32_e32 v164, 0x3fb8aa3b, v14
	v_mul_f32_e32 v165, 0x3fb8aa3b, v15
	v_exp_f32_e32 v152, v152
	v_exp_f32_e32 v153, v153
	v_exp_f32_e32 v164, v164
	v_exp_f32_e32 v165, v165
	v_add_f32_e32 v152, 1.0, v152
	v_add_f32_e32 v153, 1.0, v153
	v_add_f32_e32 v164, 1.0, v164
	v_add_f32_e32 v165, 1.0, v165
	v_rcp_f32_e32 v152, v152
	v_rcp_f32_e32 v153, v153
	v_rcp_f32_e32 v164, v164
	v_rcp_f32_e32 v165, v165
	global_store_dwordx4 v[160:161], v[172:175], off
	v_pk_mul_f32 v[162:163], v[152:153], v[162:163]
	v_mul_f32_e32 v152, 0x3fb8aa3b, v8
	v_pk_mul_f32 v[164:165], v[164:165], v[170:171]
	global_store_dwordx4 v[160:161], v[162:165], off offset:16
	v_mul_f32_e32 v153, 0x3fb8aa3b, v9
	v_exp_f32_e32 v152, v152
	v_mul_f32_e32 v162, 0x3fb8aa3b, v10
	v_mul_f32_e32 v163, 0x3fb8aa3b, v11
	v_exp_f32_e32 v153, v153
	v_exp_f32_e32 v162, v162
	v_exp_f32_e32 v163, v163
	v_add_f32_e32 v152, 1.0, v152
	v_add_f32_e32 v153, 1.0, v153
	v_add_f32_e32 v162, 1.0, v162
	v_add_f32_e32 v163, 1.0, v163
	v_rcp_f32_e32 v152, v152
	v_rcp_f32_e32 v153, v153
	v_rcp_f32_e32 v162, v162
	v_rcp_f32_e32 v163, v163
	v_pk_mul_f32 v[136:137], v[152:153], v[136:137]
	v_pk_mul_f32 v[138:139], v[162:163], v[138:139]
	global_store_dwordx4 v[160:161], v[136:139], off offset:512
	s_nop 1
	v_mul_f32_e32 v136, 0x3fb8aa3b, v4
	v_mul_f32_e32 v137, 0x3fb8aa3b, v5
	v_mul_f32_e32 v138, 0x3fb8aa3b, v6
	v_mul_f32_e32 v139, 0x3fb8aa3b, v7
	v_exp_f32_e32 v136, v136
	v_exp_f32_e32 v137, v137
	v_exp_f32_e32 v138, v138
	v_exp_f32_e32 v139, v139
	v_add_f32_e32 v136, 1.0, v136
	v_add_f32_e32 v137, 1.0, v137
	v_add_f32_e32 v138, 1.0, v138
	v_add_f32_e32 v139, 1.0, v139
	v_rcp_f32_e32 v136, v136
	v_rcp_f32_e32 v137, v137
	v_rcp_f32_e32 v138, v138
	v_rcp_f32_e32 v139, v139
	v_pk_mul_f32 v[132:133], v[136:137], v[132:133]
	v_pk_mul_f32 v[134:135], v[138:139], v[134:135]
	global_store_dwordx4 v[160:161], v[132:135], off offset:528

.LBB0_592:
	v_mul_f32_e32 v138, 0xbfb8aa3b, v128
	v_exp_f32_e32 v138, v138
	v_lshl_or_b32 v132, s50, 9, v193
	v_mov_b64_e32 v[134:135], s[42:43]
	v_ashrrev_i32_e32 v133, 31, v132
	v_add_f32_e32 v138, 1.0, v138
	v_rcp_f32_e32 v138, v138
	v_mad_i64_i32 v[136:137], s[2:3], v195, s96, v[134:135]
	v_lshl_add_u64 v[136:137], v[136:137], 0, v[132:133]
	v_mul_f32_e32 v128, v128, v138
	v_mul_f32_e32 v138, 0xbfb8aa3b, v129
	v_exp_f32_e32 v138, v138
	s_nop 0
	v_add_f32_e32 v138, 1.0, v138
	v_rcp_f32_e32 v138, v138
	s_nop 0
	v_mul_f32_e32 v129, v129, v138
	v_cvt_pk_bf16_f32 v128, v128, v129
	v_mul_f32_e32 v129, 0xbfb8aa3b, v130
	v_exp_f32_e32 v129, v129
	s_nop 0
	v_add_f32_e32 v129, 1.0, v129
	v_rcp_f32_e32 v129, v129
	s_nop 0
	v_mul_f32_e32 v129, v130, v129
	v_mul_f32_e32 v130, 0xbfb8aa3b, v131
	v_exp_f32_e32 v130, v130
	s_nop 0
	v_add_f32_e32 v130, 1.0, v130
	v_rcp_f32_e32 v130, v130
	s_nop 0
	v_mul_f32_e32 v130, v131, v130
	v_cvt_pk_bf16_f32 v129, v129, v130
	v_mul_f32_e32 v130, 0xbfb8aa3b, v124
	v_exp_f32_e32 v130, v130
	s_nop 0
	v_add_f32_e32 v130, 1.0, v130
	v_rcp_f32_e32 v130, v130
	s_nop 0
	v_mul_f32_e32 v124, v124, v130
	v_mul_f32_e32 v130, 0xbfb8aa3b, v125
	v_exp_f32_e32 v130, v130
	s_nop 0
	v_add_f32_e32 v130, 1.0, v130
	v_rcp_f32_e32 v130, v130
	s_nop 0
	v_mul_f32_e32 v125, v125, v130
	v_cvt_pk_bf16_f32 v130, v124, v125
	v_mul_f32_e32 v124, 0xbfb8aa3b, v126
	v_exp_f32_e32 v124, v124
	v_mul_f32_e32 v125, 0xbfb8aa3b, v127
	v_exp_f32_e32 v125, v125
	v_add_f32_e32 v124, 1.0, v124
	v_rcp_f32_e32 v124, v124
	v_add_f32_e32 v125, 1.0, v125
	v_rcp_f32_e32 v125, v125
	v_mul_f32_e32 v124, v126, v124
	v_mul_f32_e32 v125, v127, v125
	v_cvt_pk_bf16_f32 v131, v124, v125
	v_mul_f32_e32 v124, 0xbfb8aa3b, v120
	v_exp_f32_e32 v124, v124
	global_store_dwordx4 v[136:137], v[128:131], off offset:2048
	v_add_f32_e32 v124, 1.0, v124
	v_rcp_f32_e32 v124, v124
	s_nop 0
	v_mul_f32_e32 v120, v120, v124
	v_mul_f32_e32 v124, 0xbfb8aa3b, v121
	v_exp_f32_e32 v124, v124
	s_nop 0
	v_add_f32_e32 v124, 1.0, v124
	v_rcp_f32_e32 v124, v124
	s_nop 0
	v_mul_f32_e32 v121, v121, v124
	v_cvt_pk_bf16_f32 v120, v120, v121
	v_mul_f32_e32 v121, 0xbfb8aa3b, v122
	v_exp_f32_e32 v121, v121
	s_nop 0
	v_add_f32_e32 v121, 1.0, v121
	v_rcp_f32_e32 v121, v121
	s_nop 0
	v_mul_f32_e32 v121, v122, v121
	v_mul_f32_e32 v122, 0xbfb8aa3b, v123
	v_exp_f32_e32 v122, v122
	s_nop 0
	v_add_f32_e32 v122, 1.0, v122
	v_rcp_f32_e32 v122, v122
	s_nop 0
	v_mul_f32_e32 v122, v123, v122
	v_cvt_pk_bf16_f32 v121, v121, v122
	v_mul_f32_e32 v122, 0xbfb8aa3b, v116
	v_exp_f32_e32 v122, v122
	s_nop 0
	v_add_f32_e32 v122, 1.0, v122
	v_rcp_f32_e32 v122, v122
	s_nop 0
	v_mul_f32_e32 v116, v116, v122
	v_mul_f32_e32 v122, 0xbfb8aa3b, v117
	v_exp_f32_e32 v122, v122
	s_nop 0
	v_add_f32_e32 v122, 1.0, v122
	v_rcp_f32_e32 v122, v122
	s_nop 0
	v_mul_f32_e32 v117, v117, v122
	v_cvt_pk_bf16_f32 v122, v116, v117
	v_mul_f32_e32 v116, 0xbfb8aa3b, v118
	v_exp_f32_e32 v116, v116
	v_mul_f32_e32 v117, 0xbfb8aa3b, v119
	v_exp_f32_e32 v117, v117
	v_add_f32_e32 v116, 1.0, v116
	v_rcp_f32_e32 v116, v116
	v_add_f32_e32 v117, 1.0, v117
	v_rcp_f32_e32 v117, v117
	v_mul_f32_e32 v116, v118, v116
	v_mul_f32_e32 v118, 0xbfb8aa3b, v112
	v_exp_f32_e32 v118, v118
	v_mul_f32_e32 v117, v119, v117
	v_cvt_pk_bf16_f32 v123, v116, v117
	global_store_dwordx4 v[136:137], v[120:123], off offset:2304
	v_add_f32_e32 v118, 1.0, v118
	v_rcp_f32_e32 v118, v118
	v_or_b32_e32 v116, 16, v195
	v_mad_i64_i32 v[116:117], s[2:3], v116, s96, v[134:135]
	v_mul_f32_e32 v112, v112, v118
	v_mul_f32_e32 v118, 0xbfb8aa3b, v113
	v_exp_f32_e32 v118, v118
	v_lshl_add_u64 v[116:117], v[116:117], 0, v[132:133]
	v_add_f32_e32 v118, 1.0, v118
	v_rcp_f32_e32 v118, v118
	s_nop 0
	v_mul_f32_e32 v113, v113, v118
	v_cvt_pk_bf16_f32 v112, v112, v113
	v_mul_f32_e32 v113, 0xbfb8aa3b, v114
	v_exp_f32_e32 v113, v113
	s_nop 0
	v_add_f32_e32 v113, 1.0, v113
	v_rcp_f32_e32 v113, v113
	s_nop 0
	v_mul_f32_e32 v113, v114, v113
	v_mul_f32_e32 v114, 0xbfb8aa3b, v115
	v_exp_f32_e32 v114, v114
	s_nop 0
	v_add_f32_e32 v114, 1.0, v114
	v_rcp_f32_e32 v114, v114
	s_nop 0
	v_mul_f32_e32 v114, v115, v114
	v_cvt_pk_bf16_f32 v113, v113, v114
	v_mul_f32_e32 v114, 0xbfb8aa3b, v108
	v_exp_f32_e32 v114, v114
	s_nop 0
	v_add_f32_e32 v114, 1.0, v114
	v_rcp_f32_e32 v114, v114
	s_nop 0
	v_mul_f32_e32 v108, v108, v114
	v_mul_f32_e32 v114, 0xbfb8aa3b, v109
	v_exp_f32_e32 v114, v114
	s_nop 0
	v_add_f32_e32 v114, 1.0, v114
	v_rcp_f32_e32 v114, v114
	s_nop 0
	v_mul_f32_e32 v109, v109, v114
	v_cvt_pk_bf16_f32 v114, v108, v109
	v_mul_f32_e32 v108, 0xbfb8aa3b, v110
	v_exp_f32_e32 v108, v108
	v_mul_f32_e32 v109, 0xbfb8aa3b, v111
	v_exp_f32_e32 v109, v109
	v_add_f32_e32 v108, 1.0, v108
	v_rcp_f32_e32 v108, v108
	v_add_f32_e32 v109, 1.0, v109
	v_rcp_f32_e32 v109, v109
	v_mul_f32_e32 v108, v110, v108
	v_mul_f32_e32 v109, v111, v109
	v_cvt_pk_bf16_f32 v115, v108, v109
	v_mul_f32_e32 v108, 0xbfb8aa3b, v104
	v_exp_f32_e32 v108, v108
	global_store_dwordx4 v[116:117], v[112:115], off offset:2048
	v_add_f32_e32 v108, 1.0, v108
	v_rcp_f32_e32 v108, v108
	s_nop 0
	v_mul_f32_e32 v104, v104, v108
	v_mul_f32_e32 v108, 0xbfb8aa3b, v105
	v_exp_f32_e32 v108, v108
	s_nop 0
	v_add_f32_e32 v108, 1.0, v108
	v_rcp_f32_e32 v108, v108
	s_nop 0
	v_mul_f32_e32 v105, v105, v108
	v_cvt_pk_bf16_f32 v104, v104, v105
	v_mul_f32_e32 v105, 0xbfb8aa3b, v106
	v_exp_f32_e32 v105, v105
	s_nop 0
	v_add_f32_e32 v105, 1.0, v105
	v_rcp_f32_e32 v105, v105
	s_nop 0
	v_mul_f32_e32 v105, v106, v105
	v_mul_f32_e32 v106, 0xbfb8aa3b, v107
	v_exp_f32_e32 v106, v106
	s_nop 0
	v_add_f32_e32 v106, 1.0, v106
	v_rcp_f32_e32 v106, v106
	s_nop 0
	v_mul_f32_e32 v106, v107, v106
	v_cvt_pk_bf16_f32 v105, v105, v106
	v_mul_f32_e32 v106, 0xbfb8aa3b, v100
	v_exp_f32_e32 v106, v106
	s_nop 0
	v_add_f32_e32 v106, 1.0, v106
	v_rcp_f32_e32 v106, v106
	s_nop 0
	v_mul_f32_e32 v100, v100, v106
	v_mul_f32_e32 v106, 0xbfb8aa3b, v101
	v_exp_f32_e32 v106, v106
	s_nop 0
	v_add_f32_e32 v106, 1.0, v106
	v_rcp_f32_e32 v106, v106
	s_nop 0
	v_mul_f32_e32 v101, v101, v106
	v_cvt_pk_bf16_f32 v106, v100, v101
	v_mul_f32_e32 v100, 0xbfb8aa3b, v102
	v_exp_f32_e32 v100, v100
	v_mul_f32_e32 v101, 0xbfb8aa3b, v103
	v_exp_f32_e32 v101, v101
	v_add_f32_e32 v100, 1.0, v100
	v_rcp_f32_e32 v100, v100
	v_add_f32_e32 v101, 1.0, v101
	v_rcp_f32_e32 v101, v101
	v_mul_f32_e32 v100, v102, v100
	v_mul_f32_e32 v102, 0xbfb8aa3b, v96
	v_exp_f32_e32 v102, v102
	v_mul_f32_e32 v101, v103, v101
	v_cvt_pk_bf16_f32 v107, v100, v101
	global_store_dwordx4 v[116:117], v[104:107], off offset:2304
	v_add_f32_e32 v102, 1.0, v102
	v_rcp_f32_e32 v102, v102
	v_or_b32_e32 v100, 32, v195
	v_mad_i64_i32 v[100:101], s[2:3], v100, s96, v[134:135]
	v_mul_f32_e32 v96, v96, v102
	v_mul_f32_e32 v102, 0xbfb8aa3b, v97
	v_exp_f32_e32 v102, v102
	v_lshl_add_u64 v[100:101], v[100:101], 0, v[132:133]
	v_add_f32_e32 v102, 1.0, v102
	v_rcp_f32_e32 v102, v102
	s_nop 0
	v_mul_f32_e32 v97, v97, v102
	v_cvt_pk_bf16_f32 v96, v96, v97
	v_mul_f32_e32 v97, 0xbfb8aa3b, v98
	v_exp_f32_e32 v97, v97
	s_nop 0
	v_add_f32_e32 v97, 1.0, v97
	v_rcp_f32_e32 v97, v97
	s_nop 0
	v_mul_f32_e32 v97, v98, v97
	v_mul_f32_e32 v98, 0xbfb8aa3b, v99
	v_exp_f32_e32 v98, v98
	s_nop 0
	v_add_f32_e32 v98, 1.0, v98
	v_rcp_f32_e32 v98, v98
	s_nop 0
	v_mul_f32_e32 v98, v99, v98
	v_cvt_pk_bf16_f32 v97, v97, v98
	v_mul_f32_e32 v98, 0xbfb8aa3b, v92
	v_exp_f32_e32 v98, v98
	s_nop 0
	v_add_f32_e32 v98, 1.0, v98
	v_rcp_f32_e32 v98, v98
	s_nop 0
	v_mul_f32_e32 v92, v92, v98
	v_mul_f32_e32 v98, 0xbfb8aa3b, v93
	v_exp_f32_e32 v98, v98
	s_nop 0
	v_add_f32_e32 v98, 1.0, v98
	v_rcp_f32_e32 v98, v98
	s_nop 0
	v_mul_f32_e32 v93, v93, v98
	v_cvt_pk_bf16_f32 v98, v92, v93
	v_mul_f32_e32 v92, 0xbfb8aa3b, v94
	v_exp_f32_e32 v92, v92
	v_mul_f32_e32 v93, 0xbfb8aa3b, v95
	v_exp_f32_e32 v93, v93
	v_add_f32_e32 v92, 1.0, v92
	v_rcp_f32_e32 v92, v92
	v_add_f32_e32 v93, 1.0, v93
	v_rcp_f32_e32 v93, v93
	v_mul_f32_e32 v92, v94, v92
	v_mul_f32_e32 v93, v95, v93
	v_cvt_pk_bf16_f32 v99, v92, v93
	v_mul_f32_e32 v92, 0xbfb8aa3b, v88
	v_exp_f32_e32 v92, v92
	global_store_dwordx4 v[100:101], v[96:99], off offset:2048
	v_add_f32_e32 v92, 1.0, v92
	v_rcp_f32_e32 v92, v92
	s_nop 0
	v_mul_f32_e32 v88, v88, v92
	v_mul_f32_e32 v92, 0xbfb8aa3b, v89
	v_exp_f32_e32 v92, v92
	s_nop 0
	v_add_f32_e32 v92, 1.0, v92
	v_rcp_f32_e32 v92, v92
	s_nop 0
	v_mul_f32_e32 v89, v89, v92
	v_cvt_pk_bf16_f32 v88, v88, v89
	v_mul_f32_e32 v89, 0xbfb8aa3b, v90
	v_exp_f32_e32 v89, v89
	s_nop 0
	v_add_f32_e32 v89, 1.0, v89
	v_rcp_f32_e32 v89, v89
	s_nop 0
	v_mul_f32_e32 v89, v90, v89
	v_mul_f32_e32 v90, 0xbfb8aa3b, v91
	v_exp_f32_e32 v90, v90
	s_nop 0
	v_add_f32_e32 v90, 1.0, v90
	v_rcp_f32_e32 v90, v90
	s_nop 0
	v_mul_f32_e32 v90, v91, v90
	v_cvt_pk_bf16_f32 v89, v89, v90
	v_mul_f32_e32 v90, 0xbfb8aa3b, v84
	v_exp_f32_e32 v90, v90
	s_nop 0
	v_add_f32_e32 v90, 1.0, v90
	v_rcp_f32_e32 v90, v90
	s_nop 0
	v_mul_f32_e32 v84, v84, v90
	v_mul_f32_e32 v90, 0xbfb8aa3b, v85
	v_exp_f32_e32 v90, v90
	s_nop 0
	v_add_f32_e32 v90, 1.0, v90
	v_rcp_f32_e32 v90, v90
	s_nop 0
	v_mul_f32_e32 v85, v85, v90
	v_cvt_pk_bf16_f32 v90, v84, v85
	v_mul_f32_e32 v84, 0xbfb8aa3b, v86
	v_exp_f32_e32 v84, v84
	v_mul_f32_e32 v85, 0xbfb8aa3b, v87
	v_exp_f32_e32 v85, v85
	v_add_f32_e32 v84, 1.0, v84
	v_rcp_f32_e32 v84, v84
	v_add_f32_e32 v85, 1.0, v85
	v_rcp_f32_e32 v85, v85
	v_mul_f32_e32 v84, v86, v84
	v_mul_f32_e32 v86, 0xbfb8aa3b, v80
	v_exp_f32_e32 v86, v86
	v_mul_f32_e32 v85, v87, v85
	v_cvt_pk_bf16_f32 v91, v84, v85
	global_store_dwordx4 v[100:101], v[88:91], off offset:2304
	v_add_f32_e32 v86, 1.0, v86
	v_rcp_f32_e32 v86, v86
	v_or_b32_e32 v84, 48, v195
	v_mad_i64_i32 v[84:85], s[2:3], v84, s96, v[134:135]
	v_mul_f32_e32 v80, v80, v86
	v_mul_f32_e32 v86, 0xbfb8aa3b, v81
	v_exp_f32_e32 v86, v86
	v_lshl_add_u64 v[84:85], v[84:85], 0, v[132:133]
	v_add_f32_e32 v86, 1.0, v86
	v_rcp_f32_e32 v86, v86
	s_nop 0
	v_mul_f32_e32 v81, v81, v86
	v_cvt_pk_bf16_f32 v80, v80, v81
	v_mul_f32_e32 v81, 0xbfb8aa3b, v82
	v_exp_f32_e32 v81, v81
	s_nop 0
	v_add_f32_e32 v81, 1.0, v81
	v_rcp_f32_e32 v81, v81
	s_nop 0
	v_mul_f32_e32 v81, v82, v81
	v_mul_f32_e32 v82, 0xbfb8aa3b, v83
	v_exp_f32_e32 v82, v82
	s_nop 0
	v_add_f32_e32 v82, 1.0, v82
	v_rcp_f32_e32 v82, v82
	s_nop 0
	v_mul_f32_e32 v82, v83, v82
	v_cvt_pk_bf16_f32 v81, v81, v82
	v_mul_f32_e32 v82, 0xbfb8aa3b, v76
	v_exp_f32_e32 v82, v82
	s_nop 0
	v_add_f32_e32 v82, 1.0, v82
	v_rcp_f32_e32 v82, v82
	s_nop 0
	v_mul_f32_e32 v76, v76, v82
	v_mul_f32_e32 v82, 0xbfb8aa3b, v77
	v_exp_f32_e32 v82, v82
	s_nop 0
	v_add_f32_e32 v82, 1.0, v82
	v_rcp_f32_e32 v82, v82
	s_nop 0
	v_mul_f32_e32 v77, v77, v82
	v_cvt_pk_bf16_f32 v82, v76, v77
	v_mul_f32_e32 v76, 0xbfb8aa3b, v78
	v_exp_f32_e32 v76, v76
	v_mul_f32_e32 v77, 0xbfb8aa3b, v79
	v_exp_f32_e32 v77, v77
	v_add_f32_e32 v76, 1.0, v76
	v_rcp_f32_e32 v76, v76
	v_add_f32_e32 v77, 1.0, v77
	v_rcp_f32_e32 v77, v77
	v_mul_f32_e32 v76, v78, v76
	v_mul_f32_e32 v77, v79, v77
	v_cvt_pk_bf16_f32 v83, v76, v77
	v_mul_f32_e32 v76, 0xbfb8aa3b, v72
	v_exp_f32_e32 v76, v76
	global_store_dwordx4 v[84:85], v[80:83], off offset:2048
	v_add_f32_e32 v76, 1.0, v76
	v_rcp_f32_e32 v76, v76
	s_nop 0
	v_mul_f32_e32 v72, v72, v76
	v_mul_f32_e32 v76, 0xbfb8aa3b, v73
	v_exp_f32_e32 v76, v76
	s_nop 0
	v_add_f32_e32 v76, 1.0, v76
	v_rcp_f32_e32 v76, v76
	s_nop 0
	v_mul_f32_e32 v73, v73, v76
	v_cvt_pk_bf16_f32 v72, v72, v73
	v_mul_f32_e32 v73, 0xbfb8aa3b, v74
	v_exp_f32_e32 v73, v73
	s_nop 0
	v_add_f32_e32 v73, 1.0, v73
	v_rcp_f32_e32 v73, v73
	s_nop 0
	v_mul_f32_e32 v73, v74, v73
	v_mul_f32_e32 v74, 0xbfb8aa3b, v75
	v_exp_f32_e32 v74, v74
	s_nop 0
	v_add_f32_e32 v74, 1.0, v74
	v_rcp_f32_e32 v74, v74
	s_nop 0
	v_mul_f32_e32 v74, v75, v74
	v_cvt_pk_bf16_f32 v73, v73, v74
	v_mul_f32_e32 v74, 0xbfb8aa3b, v68
	v_exp_f32_e32 v74, v74
	s_nop 0
	v_add_f32_e32 v74, 1.0, v74
	v_rcp_f32_e32 v74, v74
	s_nop 0
	v_mul_f32_e32 v68, v68, v74
	v_mul_f32_e32 v74, 0xbfb8aa3b, v69
	v_exp_f32_e32 v74, v74
	s_nop 0
	v_add_f32_e32 v74, 1.0, v74
	v_rcp_f32_e32 v74, v74
	s_nop 0
	v_mul_f32_e32 v69, v69, v74
	v_cvt_pk_bf16_f32 v74, v68, v69
	v_mul_f32_e32 v68, 0xbfb8aa3b, v70
	v_exp_f32_e32 v68, v68
	v_mul_f32_e32 v69, 0xbfb8aa3b, v71
	v_exp_f32_e32 v69, v69
	v_add_f32_e32 v68, 1.0, v68
	v_rcp_f32_e32 v68, v68
	v_add_f32_e32 v69, 1.0, v69
	v_rcp_f32_e32 v69, v69
	v_mul_f32_e32 v68, v70, v68
	v_mul_f32_e32 v70, 0xbfb8aa3b, v64
	v_exp_f32_e32 v70, v70
	v_mul_f32_e32 v69, v71, v69
	v_cvt_pk_bf16_f32 v75, v68, v69
	global_store_dwordx4 v[84:85], v[72:75], off offset:2304
	v_add_f32_e32 v70, 1.0, v70
	v_rcp_f32_e32 v70, v70
	v_add_u32_e32 v68, 0x80, v195
	v_mad_i64_i32 v[68:69], s[2:3], v68, s96, v[134:135]
	v_mul_f32_e32 v64, v64, v70
	v_mul_f32_e32 v70, 0xbfb8aa3b, v65
	v_exp_f32_e32 v70, v70
	v_lshl_add_u64 v[68:69], v[68:69], 0, v[132:133]
	v_add_f32_e32 v70, 1.0, v70
	v_rcp_f32_e32 v70, v70
	s_nop 0
	v_mul_f32_e32 v65, v65, v70
	v_cvt_pk_bf16_f32 v64, v64, v65
	v_mul_f32_e32 v65, 0xbfb8aa3b, v66
	v_exp_f32_e32 v65, v65
	s_nop 0
	v_add_f32_e32 v65, 1.0, v65
	v_rcp_f32_e32 v65, v65
	s_nop 0
	v_mul_f32_e32 v65, v66, v65
	v_mul_f32_e32 v66, 0xbfb8aa3b, v67
	v_exp_f32_e32 v66, v66
	s_nop 0
	v_add_f32_e32 v66, 1.0, v66
	v_rcp_f32_e32 v66, v66
	s_nop 0
	v_mul_f32_e32 v66, v67, v66
	v_cvt_pk_bf16_f32 v65, v65, v66
	v_mul_f32_e32 v66, 0xbfb8aa3b, v60
	v_exp_f32_e32 v66, v66
	s_nop 0
	v_add_f32_e32 v66, 1.0, v66
	v_rcp_f32_e32 v66, v66
	s_nop 0
	v_mul_f32_e32 v60, v60, v66
	v_mul_f32_e32 v66, 0xbfb8aa3b, v61
	v_exp_f32_e32 v66, v66
	s_nop 0
	v_add_f32_e32 v66, 1.0, v66
	v_rcp_f32_e32 v66, v66
	s_nop 0
	v_mul_f32_e32 v61, v61, v66
	v_cvt_pk_bf16_f32 v66, v60, v61
	v_mul_f32_e32 v60, 0xbfb8aa3b, v62
	v_exp_f32_e32 v60, v60
	v_mul_f32_e32 v61, 0xbfb8aa3b, v63
	v_exp_f32_e32 v61, v61
	v_add_f32_e32 v60, 1.0, v60
	v_rcp_f32_e32 v60, v60
	v_add_f32_e32 v61, 1.0, v61
	v_rcp_f32_e32 v61, v61
	v_mul_f32_e32 v60, v62, v60
	v_mul_f32_e32 v61, v63, v61
	v_cvt_pk_bf16_f32 v67, v60, v61
	v_mul_f32_e32 v60, 0xbfb8aa3b, v56
	v_exp_f32_e32 v60, v60
	global_store_dwordx4 v[68:69], v[64:67], off offset:2048
	v_add_f32_e32 v60, 1.0, v60
	v_rcp_f32_e32 v60, v60
	s_nop 0
	v_mul_f32_e32 v56, v56, v60
	v_mul_f32_e32 v60, 0xbfb8aa3b, v57
	v_exp_f32_e32 v60, v60
	s_nop 0
	v_add_f32_e32 v60, 1.0, v60
	v_rcp_f32_e32 v60, v60
	s_nop 0
	v_mul_f32_e32 v57, v57, v60
	v_cvt_pk_bf16_f32 v56, v56, v57
	v_mul_f32_e32 v57, 0xbfb8aa3b, v58
	v_exp_f32_e32 v57, v57
	s_nop 0
	v_add_f32_e32 v57, 1.0, v57
	v_rcp_f32_e32 v57, v57
	s_nop 0
	v_mul_f32_e32 v57, v58, v57
	v_mul_f32_e32 v58, 0xbfb8aa3b, v59
	v_exp_f32_e32 v58, v58
	s_nop 0
	v_add_f32_e32 v58, 1.0, v58
	v_rcp_f32_e32 v58, v58
	s_nop 0
	v_mul_f32_e32 v58, v59, v58
	v_cvt_pk_bf16_f32 v57, v57, v58
	v_mul_f32_e32 v58, 0xbfb8aa3b, v52
	v_exp_f32_e32 v58, v58
	s_nop 0
	v_add_f32_e32 v58, 1.0, v58
	v_rcp_f32_e32 v58, v58
	s_nop 0
	v_mul_f32_e32 v52, v52, v58
	v_mul_f32_e32 v58, 0xbfb8aa3b, v53
	v_exp_f32_e32 v58, v58
	s_nop 0
	v_add_f32_e32 v58, 1.0, v58
	v_rcp_f32_e32 v58, v58
	s_nop 0
	v_mul_f32_e32 v53, v53, v58
	v_cvt_pk_bf16_f32 v58, v52, v53
	v_mul_f32_e32 v52, 0xbfb8aa3b, v54
	v_exp_f32_e32 v52, v52
	v_mul_f32_e32 v53, 0xbfb8aa3b, v55
	v_exp_f32_e32 v53, v53
	v_add_f32_e32 v52, 1.0, v52
	v_rcp_f32_e32 v52, v52
	v_add_f32_e32 v53, 1.0, v53
	v_rcp_f32_e32 v53, v53
	v_mul_f32_e32 v52, v54, v52
	v_mul_f32_e32 v54, 0xbfb8aa3b, v48
	v_exp_f32_e32 v54, v54
	v_mul_f32_e32 v53, v55, v53
	v_cvt_pk_bf16_f32 v59, v52, v53
	global_store_dwordx4 v[68:69], v[56:59], off offset:2304
	v_add_f32_e32 v54, 1.0, v54
	v_rcp_f32_e32 v54, v54
	v_add_u32_e32 v52, 0x90, v195
	v_mad_i64_i32 v[52:53], s[2:3], v52, s96, v[134:135]
	v_mul_f32_e32 v48, v48, v54
	v_mul_f32_e32 v54, 0xbfb8aa3b, v49
	v_exp_f32_e32 v54, v54
	v_lshl_add_u64 v[52:53], v[52:53], 0, v[132:133]
	v_add_f32_e32 v54, 1.0, v54
	v_rcp_f32_e32 v54, v54
	s_nop 0
	v_mul_f32_e32 v49, v49, v54
	v_cvt_pk_bf16_f32 v48, v48, v49
	v_mul_f32_e32 v49, 0xbfb8aa3b, v50
	v_exp_f32_e32 v49, v49
	s_nop 0
	v_add_f32_e32 v49, 1.0, v49
	v_rcp_f32_e32 v49, v49
	s_nop 0
	v_mul_f32_e32 v49, v50, v49
	v_mul_f32_e32 v50, 0xbfb8aa3b, v51
	v_exp_f32_e32 v50, v50
	s_nop 0
	v_add_f32_e32 v50, 1.0, v50
	v_rcp_f32_e32 v50, v50
	s_nop 0
	v_mul_f32_e32 v50, v51, v50
	v_cvt_pk_bf16_f32 v49, v49, v50
	v_mul_f32_e32 v50, 0xbfb8aa3b, v44
	v_exp_f32_e32 v50, v50
	s_nop 0
	v_add_f32_e32 v50, 1.0, v50
	v_rcp_f32_e32 v50, v50
	s_nop 0
	v_mul_f32_e32 v44, v44, v50
	v_mul_f32_e32 v50, 0xbfb8aa3b, v45
	v_exp_f32_e32 v50, v50
	s_nop 0
	v_add_f32_e32 v50, 1.0, v50
	v_rcp_f32_e32 v50, v50
	s_nop 0
	v_mul_f32_e32 v45, v45, v50
	v_cvt_pk_bf16_f32 v50, v44, v45
	v_mul_f32_e32 v44, 0xbfb8aa3b, v46
	v_exp_f32_e32 v44, v44
	v_mul_f32_e32 v45, 0xbfb8aa3b, v47
	v_exp_f32_e32 v45, v45
	v_add_f32_e32 v44, 1.0, v44
	v_rcp_f32_e32 v44, v44
	v_add_f32_e32 v45, 1.0, v45
	v_rcp_f32_e32 v45, v45
	v_mul_f32_e32 v44, v46, v44
	v_mul_f32_e32 v45, v47, v45
	v_cvt_pk_bf16_f32 v51, v44, v45
	v_mul_f32_e32 v44, 0xbfb8aa3b, v40
	v_exp_f32_e32 v44, v44
	global_store_dwordx4 v[52:53], v[48:51], off offset:2048
	v_add_f32_e32 v44, 1.0, v44
	v_rcp_f32_e32 v44, v44
	s_nop 0
	v_mul_f32_e32 v40, v40, v44
	v_mul_f32_e32 v44, 0xbfb8aa3b, v41
	v_exp_f32_e32 v44, v44
	s_nop 0
	v_add_f32_e32 v44, 1.0, v44
	v_rcp_f32_e32 v44, v44
	s_nop 0
	v_mul_f32_e32 v41, v41, v44
	v_cvt_pk_bf16_f32 v40, v40, v41
	v_mul_f32_e32 v41, 0xbfb8aa3b, v42
	v_exp_f32_e32 v41, v41
	s_nop 0
	v_add_f32_e32 v41, 1.0, v41
	v_rcp_f32_e32 v41, v41
	s_nop 0
	v_mul_f32_e32 v41, v42, v41
	v_mul_f32_e32 v42, 0xbfb8aa3b, v43
	v_exp_f32_e32 v42, v42
	s_nop 0
	v_add_f32_e32 v42, 1.0, v42
	v_rcp_f32_e32 v42, v42
	s_nop 0
	v_mul_f32_e32 v42, v43, v42
	v_cvt_pk_bf16_f32 v41, v41, v42
	v_mul_f32_e32 v42, 0xbfb8aa3b, v36
	v_exp_f32_e32 v42, v42
	s_nop 0
	v_add_f32_e32 v42, 1.0, v42
	v_rcp_f32_e32 v42, v42
	s_nop 0
	v_mul_f32_e32 v36, v36, v42
	v_mul_f32_e32 v42, 0xbfb8aa3b, v37
	v_exp_f32_e32 v42, v42
	s_nop 0
	v_add_f32_e32 v42, 1.0, v42
	v_rcp_f32_e32 v42, v42
	s_nop 0
	v_mul_f32_e32 v37, v37, v42
	v_cvt_pk_bf16_f32 v42, v36, v37
	v_mul_f32_e32 v36, 0xbfb8aa3b, v38
	v_exp_f32_e32 v36, v36
	v_mul_f32_e32 v37, 0xbfb8aa3b, v39
	v_exp_f32_e32 v37, v37
	v_add_f32_e32 v36, 1.0, v36
	v_rcp_f32_e32 v36, v36
	v_add_f32_e32 v37, 1.0, v37
	v_rcp_f32_e32 v37, v37
	v_mul_f32_e32 v36, v38, v36
	v_mul_f32_e32 v38, 0xbfb8aa3b, v32
	v_exp_f32_e32 v38, v38
	v_mul_f32_e32 v37, v39, v37
	v_cvt_pk_bf16_f32 v43, v36, v37
	global_store_dwordx4 v[52:53], v[40:43], off offset:2304
	v_add_f32_e32 v38, 1.0, v38
	v_rcp_f32_e32 v38, v38
	v_add_u32_e32 v36, 0xa0, v195
	v_mad_i64_i32 v[36:37], s[2:3], v36, s96, v[134:135]
	v_mul_f32_e32 v32, v32, v38
	v_mul_f32_e32 v38, 0xbfb8aa3b, v33
	v_exp_f32_e32 v38, v38
	v_lshl_add_u64 v[36:37], v[36:37], 0, v[132:133]
	v_add_f32_e32 v38, 1.0, v38
	v_rcp_f32_e32 v38, v38
	s_nop 0
	v_mul_f32_e32 v33, v33, v38
	v_cvt_pk_bf16_f32 v32, v32, v33
	v_mul_f32_e32 v33, 0xbfb8aa3b, v34
	v_exp_f32_e32 v33, v33
	s_nop 0
	v_add_f32_e32 v33, 1.0, v33
	v_rcp_f32_e32 v33, v33
	s_nop 0
	v_mul_f32_e32 v33, v34, v33
	v_mul_f32_e32 v34, 0xbfb8aa3b, v35
	v_exp_f32_e32 v34, v34
	s_nop 0
	v_add_f32_e32 v34, 1.0, v34
	v_rcp_f32_e32 v34, v34
	s_nop 0
	v_mul_f32_e32 v34, v35, v34
	v_cvt_pk_bf16_f32 v33, v33, v34
	v_mul_f32_e32 v34, 0xbfb8aa3b, v28
	v_exp_f32_e32 v34, v34
	s_nop 0
	v_add_f32_e32 v34, 1.0, v34
	v_rcp_f32_e32 v34, v34
	s_nop 0
	v_mul_f32_e32 v28, v28, v34
	v_mul_f32_e32 v34, 0xbfb8aa3b, v29
	v_exp_f32_e32 v34, v34
	s_nop 0
	v_add_f32_e32 v34, 1.0, v34
	v_rcp_f32_e32 v34, v34
	s_nop 0
	v_mul_f32_e32 v29, v29, v34
	v_cvt_pk_bf16_f32 v34, v28, v29
	v_mul_f32_e32 v28, 0xbfb8aa3b, v30
	v_exp_f32_e32 v28, v28
	v_mul_f32_e32 v29, 0xbfb8aa3b, v31
	v_exp_f32_e32 v29, v29
	v_add_f32_e32 v28, 1.0, v28
	v_rcp_f32_e32 v28, v28
	v_add_f32_e32 v29, 1.0, v29
	v_rcp_f32_e32 v29, v29
	v_mul_f32_e32 v28, v30, v28
	v_mul_f32_e32 v29, v31, v29
	v_cvt_pk_bf16_f32 v35, v28, v29
	v_mul_f32_e32 v28, 0xbfb8aa3b, v24
	v_exp_f32_e32 v28, v28
	global_store_dwordx4 v[36:37], v[32:35], off offset:2048
	v_add_f32_e32 v28, 1.0, v28
	v_rcp_f32_e32 v28, v28
	s_nop 0
	v_mul_f32_e32 v24, v24, v28
	v_mul_f32_e32 v28, 0xbfb8aa3b, v25
	v_exp_f32_e32 v28, v28
	s_nop 0
	v_add_f32_e32 v28, 1.0, v28
	v_rcp_f32_e32 v28, v28
	s_nop 0
	v_mul_f32_e32 v25, v25, v28
	v_cvt_pk_bf16_f32 v24, v24, v25
	v_mul_f32_e32 v25, 0xbfb8aa3b, v26
	v_exp_f32_e32 v25, v25
	s_nop 0
	v_add_f32_e32 v25, 1.0, v25
	v_rcp_f32_e32 v25, v25
	s_nop 0
	v_mul_f32_e32 v25, v26, v25
	v_mul_f32_e32 v26, 0xbfb8aa3b, v27
	v_exp_f32_e32 v26, v26
	s_nop 0
	v_add_f32_e32 v26, 1.0, v26
	v_rcp_f32_e32 v26, v26
	s_nop 0
	v_mul_f32_e32 v26, v27, v26
	v_cvt_pk_bf16_f32 v25, v25, v26
	v_mul_f32_e32 v26, 0xbfb8aa3b, v20
	v_exp_f32_e32 v26, v26
	s_nop 0
	v_add_f32_e32 v26, 1.0, v26
	v_rcp_f32_e32 v26, v26
	s_nop 0
	v_mul_f32_e32 v20, v20, v26
	v_mul_f32_e32 v26, 0xbfb8aa3b, v21
	v_exp_f32_e32 v26, v26
	s_nop 0
	v_add_f32_e32 v26, 1.0, v26
	v_rcp_f32_e32 v26, v26
	s_nop 0
	v_mul_f32_e32 v21, v21, v26
	v_cvt_pk_bf16_f32 v26, v20, v21
	v_mul_f32_e32 v20, 0xbfb8aa3b, v22
	v_exp_f32_e32 v20, v20
	v_mul_f32_e32 v21, 0xbfb8aa3b, v23
	v_exp_f32_e32 v21, v21
	v_add_f32_e32 v20, 1.0, v20
	v_rcp_f32_e32 v20, v20
	v_add_f32_e32 v21, 1.0, v21
	v_rcp_f32_e32 v21, v21
	v_mul_f32_e32 v20, v22, v20
	v_mul_f32_e32 v22, 0xbfb8aa3b, v16
	v_exp_f32_e32 v22, v22
	v_mul_f32_e32 v21, v23, v21
	v_cvt_pk_bf16_f32 v27, v20, v21
	global_store_dwordx4 v[36:37], v[24:27], off offset:2304
	v_add_f32_e32 v22, 1.0, v22
	v_rcp_f32_e32 v22, v22
	v_add_u32_e32 v20, 0xb0, v195
	v_mad_i64_i32 v[20:21], s[2:3], v20, s96, v[134:135]
	v_mul_f32_e32 v16, v16, v22
	v_mul_f32_e32 v22, 0xbfb8aa3b, v17
	v_exp_f32_e32 v22, v22
	v_lshl_add_u64 v[20:21], v[20:21], 0, v[132:133]
	v_add_f32_e32 v22, 1.0, v22
	v_rcp_f32_e32 v22, v22
	s_nop 0
	v_mul_f32_e32 v17, v17, v22
	v_cvt_pk_bf16_f32 v16, v16, v17
	v_mul_f32_e32 v17, 0xbfb8aa3b, v18
	v_exp_f32_e32 v17, v17
	s_nop 0
	v_add_f32_e32 v17, 1.0, v17
	v_rcp_f32_e32 v17, v17
	s_nop 0
	v_mul_f32_e32 v17, v18, v17
	v_mul_f32_e32 v18, 0xbfb8aa3b, v19
	v_exp_f32_e32 v18, v18
	s_nop 0
	v_add_f32_e32 v18, 1.0, v18
	v_rcp_f32_e32 v18, v18
	s_nop 0
	v_mul_f32_e32 v18, v19, v18
	v_cvt_pk_bf16_f32 v17, v17, v18
	v_mul_f32_e32 v18, 0xbfb8aa3b, v12
	v_exp_f32_e32 v18, v18
	s_nop 0
	v_add_f32_e32 v18, 1.0, v18
	v_rcp_f32_e32 v18, v18
	s_nop 0
	v_mul_f32_e32 v12, v12, v18
	v_mul_f32_e32 v18, 0xbfb8aa3b, v13
	v_exp_f32_e32 v18, v18
	s_nop 0
	v_add_f32_e32 v18, 1.0, v18
	v_rcp_f32_e32 v18, v18
	s_nop 0
	v_mul_f32_e32 v13, v13, v18
	v_cvt_pk_bf16_f32 v18, v12, v13
	v_mul_f32_e32 v12, 0xbfb8aa3b, v14
	v_exp_f32_e32 v12, v12
	v_mul_f32_e32 v13, 0xbfb8aa3b, v15
	v_exp_f32_e32 v13, v13
	v_add_f32_e32 v12, 1.0, v12
	v_rcp_f32_e32 v12, v12
	v_add_f32_e32 v13, 1.0, v13
	v_rcp_f32_e32 v13, v13
	v_mul_f32_e32 v12, v14, v12
	v_mul_f32_e32 v13, v15, v13
	v_cvt_pk_bf16_f32 v19, v12, v13
	v_mul_f32_e32 v12, 0xbfb8aa3b, v8
	v_exp_f32_e32 v12, v12
	global_store_dwordx4 v[20:21], v[16:19], off offset:2048
	v_add_f32_e32 v12, 1.0, v12
	v_rcp_f32_e32 v12, v12
	s_nop 0
	v_mul_f32_e32 v8, v8, v12
	v_mul_f32_e32 v12, 0xbfb8aa3b, v9
	v_exp_f32_e32 v12, v12
	s_nop 0
	v_add_f32_e32 v12, 1.0, v12
	v_rcp_f32_e32 v12, v12
	s_nop 0
	v_mul_f32_e32 v9, v9, v12
	v_cvt_pk_bf16_f32 v8, v8, v9
	v_mul_f32_e32 v9, 0xbfb8aa3b, v10
	v_exp_f32_e32 v9, v9
	s_nop 0
	v_add_f32_e32 v9, 1.0, v9
	v_rcp_f32_e32 v9, v9
	s_nop 0
	v_mul_f32_e32 v9, v10, v9
	v_mul_f32_e32 v10, 0xbfb8aa3b, v11
	v_exp_f32_e32 v10, v10
	s_nop 0
	v_add_f32_e32 v10, 1.0, v10
	v_rcp_f32_e32 v10, v10
	s_nop 0
	v_mul_f32_e32 v10, v11, v10
	v_cvt_pk_bf16_f32 v9, v9, v10
	v_mul_f32_e32 v10, 0xbfb8aa3b, v4
	v_exp_f32_e32 v10, v10
	s_nop 0
	v_add_f32_e32 v10, 1.0, v10
	v_rcp_f32_e32 v10, v10
	s_nop 0
	v_mul_f32_e32 v4, v4, v10
	v_mul_f32_e32 v10, 0xbfb8aa3b, v5
	v_exp_f32_e32 v10, v10
	s_nop 0
	v_add_f32_e32 v10, 1.0, v10
	v_rcp_f32_e32 v10, v10
	s_nop 0
	v_mul_f32_e32 v5, v5, v10
	v_cvt_pk_bf16_f32 v10, v4, v5
	v_mul_f32_e32 v4, 0xbfb8aa3b, v6
	v_mul_f32_e32 v5, 0xbfb8aa3b, v7
	v_exp_f32_e32 v4, v4
	v_exp_f32_e32 v5, v5
	v_add_f32_e32 v4, 1.0, v4
	v_add_f32_e32 v5, 1.0, v5
	v_rcp_f32_e32 v4, v4
	v_rcp_f32_e32 v5, v5
	v_mul_f32_e32 v4, v6, v4
	v_mul_f32_e32 v5, v7, v5
	v_cvt_pk_bf16_f32 v11, v4, v5
	global_store_dwordx4 v[20:21], v[8:11], off offset:2304
	s_andn2_b64 vcc, exec, s[38:39]
	s_mov_b64 s[2:3], -1
	s_cbranch_vccnz .LBB0_430

.LBB0_702:
	v_add_u32_e32 v0, s11, v71
	s_barrier
	ds_write_b128 v0, v[44:47]
	ds_write_b128 v0, v[40:43] offset:1024
	s_waitcnt lgkmcnt(0)
	s_barrier
	s_and_saveexec_b64 s[4:5], s[38:39]
	s_cbranch_execz .LBB0_687
	ds_read_b128 v[96:99], v72
	ds_read_b128 v[100:103], v72 offset:2048
	ds_read_b128 v[104:107], v72 offset:4096
	ds_read_b128 v[108:111], v72 offset:6144
	ds_read_b128 v[112:115], v72 offset:8192
	ds_read_b128 v[116:119], v72 offset:10240
	ds_read_b128 v[120:123], v72 offset:12288
	ds_read_b128 v[124:127], v72 offset:14336
	v_add_u32_e32 v46, s13, v73
	v_ashrrev_i32_e32 v47, 31, v46
	v_lshlrev_b64 v[50:51], 12, v[46:47]
	s_mov_b32 s8, 0x18000
	v_lshlrev_b32_e32 v40, 2, v74
	v_mov_b32_e32 v41, v2
	v_lshl_add_u64 v[48:49], s[0:1], 0, v[40:41]
	v_lshl_add_u64 v[42:43], s[2:3], 0, v[40:41]
	v_lshl_add_u64 v[48:49], v[48:49], 0, v[50:51]
	s_mov_b64 s[6:7], 0x1000
	v_lshl_add_u64 v[52:53], v[48:49], 0, s[6:7]
	s_mov_b64 s[6:7], 0x3000
	v_lshl_add_u64 v[54:55], v[48:49], 0, s[6:7]
	global_load_dword v128, v[52:53], off offset:-4096
	global_load_dword v129, v[52:53], off
	global_load_dword v130, v[54:55], off offset:-4096
	global_load_dword v131, v[54:55], off
	v_add_u32_e32 v47, 8, v46
	v_mad_i64_i32 v[56:57], s[6:7], v47, s8, v[42:43]
	global_load_dword v132, v[56:57], off
	v_add_u32_e32 v47, 9, v46
	v_mad_i64_i32 v[56:57], s[6:7], v47, s8, v[42:43]
	global_load_dword v133, v[56:57], off
	v_add_u32_e32 v47, 10, v46
	v_mad_i64_i32 v[56:57], s[6:7], v47, s8, v[42:43]
	global_load_dword v134, v[56:57], off
	v_add_u32_e32 v47, 11, v46
	v_mad_i64_i32 v[56:57], s[6:7], v47, s8, v[42:43]
	global_load_dword v135, v[56:57], off
	v_lshl_add_u64 v[40:41], s[60:61], 0, v[40:41]
	v_lshl_add_u64 v[40:41], v[40:41], 0, v[50:51]
	s_mov_b32 s6, 0x4001000
	v_add_co_u32_e32 v50, vcc, s6, v40
	s_nop 1
	v_addc_co_u32_e32 v51, vcc, 0, v41, vcc
	s_mov_b32 s6, 0x4003000
	v_add_co_u32_e32 v52, vcc, s6, v40
	s_nop 1
	v_addc_co_u32_e32 v53, vcc, 0, v41, vcc
	s_waitcnt lgkmcnt(0)
	v_pk_add_f32 v[0:1], v[98:99], 0 op_sel_hi:[1,0]
	v_pk_add_f32 v[44:45], v[96:97], 0 op_sel_hi:[1,0]
	v_pk_add_f32 v[0:1], v[0:1], v[102:103]
	v_pk_add_f32 v[44:45], v[44:45], v[100:101]
	v_pk_add_f32 v[0:1], v[0:1], v[106:107]
	v_pk_add_f32 v[44:45], v[44:45], v[104:105]
	v_pk_add_f32 v[0:1], v[0:1], v[110:111]
	v_pk_add_f32 v[44:45], v[44:45], v[108:109]
	v_pk_add_f32 v[0:1], v[0:1], v[114:115]
	v_pk_add_f32 v[44:45], v[44:45], v[112:113]
	v_pk_add_f32 v[0:1], v[0:1], v[118:119]
	v_pk_add_f32 v[44:45], v[44:45], v[116:117]
	v_pk_add_f32 v[0:1], v[0:1], v[122:123]
	v_pk_add_f32 v[44:45], v[44:45], v[120:121]
	v_pk_add_f32 v[0:1], v[0:1], v[126:127]
	v_pk_add_f32 v[44:45], v[44:45], v[124:125]
	s_waitcnt vmcnt(0)
	v_fmac_f32_e32 v128, v44, v132
	v_fmac_f32_e32 v129, v45, v133
	v_fmac_f32_e32 v130, v0, v134
	v_fmac_f32_e32 v131, v1, v135
	global_store_dword v[50:51], v128, off offset:-4096
	global_store_dword v[50:51], v129, off
	global_store_dword v[52:53], v130, off offset:-4096
	global_store_dword v[52:53], v131, off
	s_branch .LBB0_687
